# hyena: next-trip cache-line touches with counted waits in stage and pointwise loops; k=8192 special-case spectrum load hoisted to loop top
# speedup vs baseline: 1.0323x; 1.0011x over previous
; DI void hyena_item(const Params& p, int l, int dpr, LAS unsigned char* lds) {
;     ...
;     for (int r = 0; r < 16; ++r) { const int t = tid + NTHR * r;
;         float v[4];
; #pragma unroll
;         for (int c = 0; c < 4; ++c) v[c] = conv3(bint + (size_t)(a + c) * S, t, w[c][0], w[c][1], w[c][2]) * 0.25f;
.LBB0_601:
	v_add_u32_e32 v22, s7, v12
	v_mov_b32_e32 v149, 0
	v_mov_b32_e32 v151, 0
	v_mov_b32_e32 v153, 0
	v_mov_b32_e32 v148, v22
	v_max_i32_e32 v150, 1, v148
	v_min_i32_e32 v152, 0x1ffe, v148
	v_lshlrev_b32_e32 v148, 2, v148
	v_lshlrev_b32_e32 v150, 2, v150
	v_lshlrev_b32_e32 v152, 2, v152
	v_lshl_add_u64 v[154:155], s[58:59], 0, v[148:149]
	global_load_dword v100, v[154:155], off
	v_lshl_add_u64 v[154:155], s[58:59], 0, v[150:151]
	global_load_dword v101, v[154:155], off offset:-4
	v_lshl_add_u64 v[154:155], s[58:59], 0, v[152:153]
	global_load_dword v102, v[154:155], off offset:4
	v_lshl_add_u64 v[154:155], s[62:63], 0, v[148:149]
	global_load_dword v103, v[154:155], off
	v_lshl_add_u64 v[154:155], s[62:63], 0, v[150:151]
	global_load_dword v104, v[154:155], off offset:-4
	v_lshl_add_u64 v[154:155], s[62:63], 0, v[152:153]
	global_load_dword v105, v[154:155], off offset:4
	v_lshl_add_u64 v[154:155], s[18:19], 0, v[148:149]
	global_load_dword v106, v[154:155], off
	v_lshl_add_u64 v[154:155], s[18:19], 0, v[150:151]
	global_load_dword v107, v[154:155], off offset:-4
	v_lshl_add_u64 v[154:155], s[18:19], 0, v[152:153]
	global_load_dword v108, v[154:155], off offset:4
	v_lshl_add_u64 v[154:155], s[16:17], 0, v[148:149]
	global_load_dword v109, v[154:155], off
	v_lshl_add_u64 v[154:155], s[16:17], 0, v[150:151]
	global_load_dword v110, v[154:155], off offset:-4
	v_lshl_add_u64 v[154:155], s[16:17], 0, v[152:153]
	global_load_dword v111, v[154:155], off offset:4
	v_add_u32_e32 v148, 0x200, v22
	v_max_i32_e32 v150, 1, v148
	v_min_i32_e32 v152, 0x1ffe, v148
	v_lshlrev_b32_e32 v148, 2, v148
	v_lshlrev_b32_e32 v150, 2, v150
	v_lshlrev_b32_e32 v152, 2, v152
	v_lshl_add_u64 v[154:155], s[58:59], 0, v[148:149]
	global_load_dword v112, v[154:155], off
	v_lshl_add_u64 v[154:155], s[58:59], 0, v[150:151]
	global_load_dword v113, v[154:155], off offset:-4
	v_lshl_add_u64 v[154:155], s[58:59], 0, v[152:153]
	global_load_dword v114, v[154:155], off offset:4
	v_lshl_add_u64 v[154:155], s[62:63], 0, v[148:149]
	global_load_dword v115, v[154:155], off
	v_lshl_add_u64 v[154:155], s[62:63], 0, v[150:151]
	global_load_dword v116, v[154:155], off offset:-4
	v_lshl_add_u64 v[154:155], s[62:63], 0, v[152:153]
	global_load_dword v117, v[154:155], off offset:4
	v_lshl_add_u64 v[154:155], s[18:19], 0, v[148:149]
	global_load_dword v118, v[154:155], off
	v_lshl_add_u64 v[154:155], s[18:19], 0, v[150:151]
	global_load_dword v119, v[154:155], off offset:-4
	v_lshl_add_u64 v[154:155], s[18:19], 0, v[152:153]
	global_load_dword v120, v[154:155], off offset:4
	v_lshl_add_u64 v[154:155], s[16:17], 0, v[148:149]
	global_load_dword v121, v[154:155], off
	v_lshl_add_u64 v[154:155], s[16:17], 0, v[150:151]
	global_load_dword v122, v[154:155], off offset:-4
	v_lshl_add_u64 v[154:155], s[16:17], 0, v[152:153]
	global_load_dword v123, v[154:155], off offset:4
	v_add_u32_e32 v148, 0x400, v22
	v_max_i32_e32 v150, 1, v148
	v_min_i32_e32 v152, 0x1ffe, v148
	v_lshlrev_b32_e32 v148, 2, v148
	v_lshlrev_b32_e32 v150, 2, v150
	v_lshlrev_b32_e32 v152, 2, v152
	v_lshl_add_u64 v[154:155], s[58:59], 0, v[148:149]
	global_load_dword v124, v[154:155], off
	v_lshl_add_u64 v[154:155], s[58:59], 0, v[150:151]
	global_load_dword v125, v[154:155], off offset:-4
	v_lshl_add_u64 v[154:155], s[58:59], 0, v[152:153]
	global_load_dword v126, v[154:155], off offset:4
	v_lshl_add_u64 v[154:155], s[62:63], 0, v[148:149]
	global_load_dword v127, v[154:155], off
	v_lshl_add_u64 v[154:155], s[62:63], 0, v[150:151]
	global_load_dword v128, v[154:155], off offset:-4
	v_lshl_add_u64 v[154:155], s[62:63], 0, v[152:153]
	global_load_dword v129, v[154:155], off offset:4
	v_lshl_add_u64 v[154:155], s[18:19], 0, v[148:149]
	global_load_dword v130, v[154:155], off
	v_lshl_add_u64 v[154:155], s[18:19], 0, v[150:151]
	global_load_dword v131, v[154:155], off offset:-4
	v_lshl_add_u64 v[154:155], s[18:19], 0, v[152:153]
	global_load_dword v132, v[154:155], off offset:4
	v_lshl_add_u64 v[154:155], s[16:17], 0, v[148:149]
	global_load_dword v133, v[154:155], off
	v_lshl_add_u64 v[154:155], s[16:17], 0, v[150:151]
	global_load_dword v134, v[154:155], off offset:-4
	v_lshl_add_u64 v[154:155], s[16:17], 0, v[152:153]
	global_load_dword v135, v[154:155], off offset:4
	v_add_u32_e32 v148, 0x600, v22
	v_max_i32_e32 v150, 1, v148
	v_min_i32_e32 v152, 0x1ffe, v148
	v_lshlrev_b32_e32 v148, 2, v148
	v_lshlrev_b32_e32 v150, 2, v150
	v_lshlrev_b32_e32 v152, 2, v152
	v_lshl_add_u64 v[154:155], s[58:59], 0, v[148:149]
	global_load_dword v136, v[154:155], off
	v_lshl_add_u64 v[154:155], s[58:59], 0, v[150:151]
	global_load_dword v137, v[154:155], off offset:-4
	v_lshl_add_u64 v[154:155], s[58:59], 0, v[152:153]
	global_load_dword v138, v[154:155], off offset:4
	v_lshl_add_u64 v[154:155], s[62:63], 0, v[148:149]
	global_load_dword v139, v[154:155], off
	v_lshl_add_u64 v[154:155], s[62:63], 0, v[150:151]
	global_load_dword v140, v[154:155], off offset:-4
	v_lshl_add_u64 v[154:155], s[62:63], 0, v[152:153]
	global_load_dword v141, v[154:155], off offset:4
	v_lshl_add_u64 v[154:155], s[18:19], 0, v[148:149]
	global_load_dword v142, v[154:155], off
	v_lshl_add_u64 v[154:155], s[18:19], 0, v[150:151]
	global_load_dword v143, v[154:155], off offset:-4
	v_lshl_add_u64 v[154:155], s[18:19], 0, v[152:153]
	global_load_dword v144, v[154:155], off offset:4
	v_lshl_add_u64 v[154:155], s[16:17], 0, v[148:149]
	global_load_dword v145, v[154:155], off
	v_lshl_add_u64 v[154:155], s[16:17], 0, v[150:151]
	global_load_dword v146, v[154:155], off offset:-4
	v_lshl_add_u64 v[154:155], s[16:17], 0, v[152:153]
	global_load_dword v147, v[154:155], off offset:4
; DI void hyena_item(const Params& p, int l, int dpr, LAS unsigned char* lds) {
;     ...
;     for (int r = 0; r < 16; ++r) { const int t = tid + NTHR * r;
;         float v[4];
; #pragma unroll
;         for (int c = 0; c < 4; ++c) v[c] = conv3(bint + (size_t)(a + c) * S, t, w[c][0], w[c][1], w[c][2]) * 0.25f;
;         X0[XI(t)] = (hc){(_Float16)v[0], (_Float16)v[1]}; X1[XI(t)] = (hc){(_Float16)v[2], (_Float16)v[3]};
;         X0[XI(t + 8192)] = hzero; X1[XI(t + 8192)] = hzero; }
	v_add_u32_e32 v156, 0x800, v22
	v_mov_b32_e32 v157, 0
	v_lshlrev_b32_e32 v156, 2, v156
	v_lshl_add_u64 v[158:159], s[58:59], 0, v[156:157]
	global_load_dword v160, v[158:159], off
	v_lshl_add_u64 v[158:159], s[62:63], 0, v[156:157]
	global_load_dword v161, v[158:159], off
	v_lshl_add_u64 v[158:159], s[18:19], 0, v[156:157]
	global_load_dword v162, v[158:159], off
	v_lshl_add_u64 v[158:159], s[16:17], 0, v[156:157]
	global_load_dword v163, v[158:159], off
	v_add_u32_e32 v156, 0xa00, v22
	v_mov_b32_e32 v157, 0
	v_lshlrev_b32_e32 v156, 2, v156
	v_lshl_add_u64 v[158:159], s[58:59], 0, v[156:157]
	global_load_dword v164, v[158:159], off
	v_lshl_add_u64 v[158:159], s[62:63], 0, v[156:157]
	global_load_dword v165, v[158:159], off
	v_lshl_add_u64 v[158:159], s[18:19], 0, v[156:157]
	global_load_dword v166, v[158:159], off
	v_lshl_add_u64 v[158:159], s[16:17], 0, v[156:157]
	global_load_dword v167, v[158:159], off
	v_add_u32_e32 v156, 0xc00, v22
	v_mov_b32_e32 v157, 0
	v_lshlrev_b32_e32 v156, 2, v156
	v_lshl_add_u64 v[158:159], s[58:59], 0, v[156:157]
	global_load_dword v168, v[158:159], off
	v_lshl_add_u64 v[158:159], s[62:63], 0, v[156:157]
	global_load_dword v169, v[158:159], off
	v_lshl_add_u64 v[158:159], s[18:19], 0, v[156:157]
	global_load_dword v170, v[158:159], off
	v_lshl_add_u64 v[158:159], s[16:17], 0, v[156:157]
	global_load_dword v171, v[158:159], off
	v_add_u32_e32 v156, 0xe00, v22
	v_mov_b32_e32 v157, 0
	v_lshlrev_b32_e32 v156, 2, v156
	v_lshl_add_u64 v[158:159], s[58:59], 0, v[156:157]
	global_load_dword v172, v[158:159], off
	v_lshl_add_u64 v[158:159], s[62:63], 0, v[156:157]
	global_load_dword v173, v[158:159], off
	v_lshl_add_u64 v[158:159], s[18:19], 0, v[156:157]
	global_load_dword v174, v[158:159], off
	v_lshl_add_u64 v[158:159], s[16:17], 0, v[156:157]
	global_load_dword v175, v[158:159], off
	s_waitcnt vmcnt(16)
	v_ashrrev_i32_e32 v23, 31, v22
	v_max_i32_e32 v96, 1, v22
	v_min_i32_e32 v24, 0x1ffe, v22
	v_lshlrev_b64 v[26:27], 2, v[22:23]
	v_lshlrev_b64 v[30:31], 2, v[96:97]
	v_ashrrev_i32_e32 v25, 31, v24
	v_lshl_add_u64 v[28:29], s[58:59], 0, v[26:27]
	v_lshl_add_u64 v[32:33], s[58:59], 0, v[30:31]
	v_mov_b32_e32 v28, v100
	v_lshlrev_b64 v[24:25], 2, v[24:25]
	v_mov_b32_e32 v23, v101
	v_lshl_add_u64 v[32:33], s[58:59], 0, v[24:25]
	v_mov_b32_e32 v32, v102
	v_cmp_lt_i32_e32 vcc, 0, v22
	v_cmp_gt_i32_e64 s[40:41], s29, v22
	s_addk_i32 s7, 0x800
	s_cmpk_eq_i32 s7, 0x2000
	s_nop 0
	v_cndmask_b32_e32 v29, 0, v23, vcc
	v_pk_mul_f32 v[28:29], v[0:1], v[28:29]
	s_nop 0
	v_cndmask_b32_e64 v23, 0, v32, s[40:41]
	v_add_f32_e32 v28, v28, v29
	v_fmac_f32_e32 v28, v4, v23
	v_mul_f32_e32 v23, 0x3e800000, v28
	v_lshl_add_u64 v[28:29], s[62:63], 0, v[26:27]
	v_lshl_add_u64 v[32:33], s[62:63], 0, v[30:31]
	v_mov_b32_e32 v28, v103
	s_nop 0
	v_mov_b32_e32 v29, v104
	v_lshl_add_u64 v[32:33], s[62:63], 0, v[24:25]
	v_mov_b32_e32 v32, v105
	s_nop 0
	v_cndmask_b32_e32 v29, 0, v29, vcc
	v_pk_mul_f32 v[28:29], v[8:9], v[28:29]
	s_nop 0
	v_cndmask_b32_e64 v32, 0, v32, s[40:41]
	v_add_f32_e32 v28, v28, v29
	v_fmac_f32_e32 v28, v5, v32
	v_mul_f32_e32 v34, 0x3e800000, v28
	v_lshl_add_u64 v[28:29], s[18:19], 0, v[26:27]
	v_lshl_add_u64 v[32:33], s[18:19], 0, v[30:31]
	v_lshl_add_u64 v[26:27], s[16:17], 0, v[26:27]
	v_mov_b32_e32 v28, v106
	v_cvt_pk_f16_f32 v23, v23, v34
	v_mov_b32_e32 v26, v109
	s_nop 0
	v_mov_b32_e32 v29, v107
	v_lshl_add_u64 v[32:33], s[18:19], 0, v[24:25]
	v_mov_b32_e32 v32, v108
	v_lshl_add_u64 v[24:25], s[16:17], 0, v[24:25]
	v_mov_b32_e32 v24, v111
	s_nop 0
	v_cndmask_b32_e32 v29, 0, v29, vcc
	v_pk_mul_f32 v[28:29], v[2:3], v[28:29]
	s_nop 0
	v_cndmask_b32_e64 v32, 0, v32, s[40:41]
	v_add_f32_e32 v28, v28, v29
	v_fmac_f32_e32 v28, v6, v32
	v_mul_f32_e32 v32, 0x3e800000, v28
	v_lshl_add_u64 v[28:29], s[16:17], 0, v[30:31]
	v_mov_b32_e32 v27, v110
	s_nop 0
	v_cndmask_b32_e64 v28, 0, v24, s[40:41]
	s_nop 0
	v_cndmask_b32_e32 v27, 0, v27, vcc
	v_pk_mul_f32 v[24:25], v[10:11], v[26:27]
	v_ashrrev_i32_e32 v26, 8, v22
	v_add_f32_e32 v24, v24, v25
	v_ashrrev_i32_e32 v25, 4, v22
	v_add_u32_e32 v25, v25, v26
	v_fmac_f32_e32 v24, v7, v28
	v_add_lshl_u32 v25, v22, v25, 2
	v_mul_f32_e32 v24, 0x3e800000, v24
	v_add_u32_e32 v26, 0, v25
	ds_write_b32 v26, v23
	v_cvt_pk_f16_f32 v23, v32, v24
	v_add_u32_e32 v24, s66, v25
	ds_write_b32 v24, v23
	v_add_u32_e32 v23, 0x2000, v22
	v_ashrrev_i32_e32 v24, 4, v23
	v_ashrrev_i32_e32 v23, 8, v23
	v_add_u32_e32 v23, v24, v23
	v_add_lshl_u32 v23, v22, v23, 2
	v_add_u32_e32 v24, 0, v23
	v_add_u32_e32 v23, s66, v23
	ds_write_b32 v23, v97 offset:32768
	v_add_u32_e32 v23, 0x200, v22
	v_max_i32_e32 v96, 1, v23
	ds_write_b32 v24, v97 offset:32768
	v_min_i32_e32 v24, 0x1ffe, v23
	v_lshlrev_b64 v[28:29], 2, v[96:97]
	v_ashrrev_i32_e32 v25, 31, v24
	v_lshl_add_u64 v[30:31], s[58:59], 0, v[28:29]
	v_mov_b32_e32 v27, v113
	v_lshlrev_b64 v[24:25], 2, v[24:25]
	v_mov_b32_e32 v26, v112
	v_lshl_add_u64 v[30:31], s[58:59], 0, v[24:25]
	v_mov_b32_e32 v30, v114
	v_cmp_lt_i32_e32 vcc, 0, v23
	v_cmp_gt_i32_e64 s[40:41], s29, v23
	v_lshl_add_u64 v[20:21], v[20:21], 0, s[46:47]
	s_nop 0
	v_cndmask_b32_e32 v27, 0, v27, vcc
	s_nop 0
	v_pk_mul_f32 v[26:27], v[0:1], v[26:27]
	s_nop 0
	v_add_f32_e32 v26, v26, v27
	s_nop 0
	v_cndmask_b32_e64 v30, 0, v30, s[40:41]
	v_fmac_f32_e32 v26, v4, v30
	v_lshl_add_u64 v[30:31], s[62:63], 0, v[28:29]
	v_mov_b32_e32 v27, v116
	v_mul_f32_e32 v32, 0x3e800000, v26
	v_mov_b32_e32 v26, v115
	v_lshl_add_u64 v[30:31], s[62:63], 0, v[24:25]
	v_mov_b32_e32 v30, v117
	v_lshl_add_u64 v[18:19], v[18:19], 0, s[46:47]
	s_nop 0
	v_cndmask_b32_e32 v27, 0, v27, vcc
	s_nop 0
	v_pk_mul_f32 v[26:27], v[8:9], v[26:27]
; DI void hyena_item(const Params& p, int l, int dpr, LAS unsigned char* lds) {
;     ...
;     for (int r = 0; r < 16; ++r) { const int t = tid + NTHR * r;
;         float v[4];
; #pragma unroll
;         for (int c = 0; c < 4; ++c) v[c] = conv3(bint + (size_t)(a + c) * S, t, w[c][0], w[c][1], w[c][2]) * 0.25f;
;         X0[XI(t)] = (hc){(_Float16)v[0], (_Float16)v[1]}; X1[XI(t)] = (hc){(_Float16)v[2], (_Float16)v[3]};
;         X0[XI(t + 8192)] = hzero; X1[XI(t + 8192)] = hzero; }
	s_nop 0
	v_add_f32_e32 v26, v26, v27
	s_nop 0
	v_cndmask_b32_e64 v30, 0, v30, s[40:41]
	v_fmac_f32_e32 v26, v5, v30
	v_lshl_add_u64 v[30:31], s[18:19], 0, v[28:29]
	v_mov_b32_e32 v27, v119
	v_mul_f32_e32 v33, 0x3e800000, v26
	v_mov_b32_e32 v26, v118
	v_lshl_add_u64 v[30:31], s[18:19], 0, v[24:25]
	v_mov_b32_e32 v30, v120
	v_lshl_add_u64 v[28:29], s[16:17], 0, v[28:29]
	v_lshl_add_u64 v[24:25], s[16:17], 0, v[24:25]
	v_lshl_add_u64 v[16:17], v[16:17], 0, s[46:47]
	v_mov_b32_e32 v24, v123
	s_nop 0
	v_cndmask_b32_e32 v27, 0, v27, vcc
	s_nop 0
	v_pk_mul_f32 v[26:27], v[2:3], v[26:27]
	s_nop 0
	v_add_f32_e32 v26, v26, v27
	v_mov_b32_e32 v27, v122
	s_nop 0
	v_cndmask_b32_e64 v30, 0, v30, s[40:41]
	v_fmac_f32_e32 v26, v6, v30
	v_mul_f32_e32 v30, 0x3e800000, v26
	v_mov_b32_e32 v26, v121
	v_lshl_add_u64 v[14:15], v[14:15], 0, s[46:47]
	s_nop 0
	v_cndmask_b32_e64 v28, 0, v24, s[40:41]
	s_nop 0
	v_cndmask_b32_e32 v27, 0, v27, vcc
	s_nop 0
	v_pk_mul_f32 v[24:25], v[10:11], v[26:27]
	s_nop 0
	v_add_f32_e32 v24, v24, v25
	v_ashrrev_i32_e32 v26, 4, v23
	v_ashrrev_i32_e32 v23, 8, v23
	v_fmac_f32_e32 v24, v7, v28
	v_add_u32_e32 v23, v26, v23
	v_mul_f32_e32 v24, 0x3e800000, v24
	v_add_lshl_u32 v23, v22, v23, 2
	v_add_u32_e32 v26, 0, v23
	v_cvt_pk_f16_f32 v24, v30, v24
	v_add_u32_e32 v23, s66, v23
	ds_write_b32 v23, v24 offset:2048
	v_add_u32_e32 v23, 0x2200, v22
	v_ashrrev_i32_e32 v24, 4, v23
	v_ashrrev_i32_e32 v23, 8, v23
	v_add_u32_e32 v23, v24, v23
	v_add_lshl_u32 v23, v22, v23, 2
	v_cvt_pk_f16_f32 v25, v32, v33
	v_add_u32_e32 v24, 0, v23
	ds_write_b32 v26, v25 offset:2048
	ds_write_b32 v24, v97 offset:34816
	v_add_u32_e32 v24, 0x400, v22
	v_ashrrev_i32_e32 v25, 31, v24
	v_max_i32_e32 v96, 1, v24
	v_min_i32_e32 v26, 0x1ffe, v24
	v_lshlrev_b64 v[28:29], 2, v[24:25]
	v_lshlrev_b64 v[32:33], 2, v[96:97]
	v_add_u32_e32 v23, s66, v23
	v_ashrrev_i32_e32 v27, 31, v26
	v_lshl_add_u64 v[30:31], s[58:59], 0, v[28:29]
	v_lshl_add_u64 v[34:35], s[58:59], 0, v[32:33]
	ds_write_b32 v23, v97 offset:34816
	v_mov_b32_e32 v30, v124
	v_lshlrev_b64 v[26:27], 2, v[26:27]
	v_mov_b32_e32 v23, v125
	v_lshl_add_u64 v[34:35], s[58:59], 0, v[26:27]
	v_mov_b32_e32 v25, v126
	v_cmp_lt_i32_e32 vcc, 0, v24
	v_cmp_gt_i32_e64 s[40:41], s29, v24
	v_lshl_add_u64 v[34:35], s[62:63], 0, v[32:33]
	s_nop 0
	v_cndmask_b32_e32 v31, 0, v23, vcc
	v_pk_mul_f32 v[30:31], v[0:1], v[30:31]
	s_nop 0
	v_cndmask_b32_e64 v23, 0, v25, s[40:41]
	v_add_f32_e32 v25, v30, v31
	v_fmac_f32_e32 v25, v4, v23
	v_lshl_add_u64 v[30:31], s[62:63], 0, v[28:29]
	v_mul_f32_e32 v23, 0x3e800000, v25
	v_mov_b32_e32 v30, v127
	s_nop 0
	v_mov_b32_e32 v25, v128
	v_lshl_add_u64 v[34:35], s[62:63], 0, v[26:27]
	v_mov_b32_e32 v34, v129
	s_nop 0
	v_cndmask_b32_e32 v31, 0, v25, vcc
	v_pk_mul_f32 v[30:31], v[8:9], v[30:31]
	s_nop 0
	v_cndmask_b32_e64 v25, 0, v34, s[40:41]
	v_add_f32_e32 v30, v30, v31
	v_fmac_f32_e32 v30, v5, v25
	v_mul_f32_e32 v25, 0x3e800000, v30
	v_lshl_add_u64 v[30:31], s[18:19], 0, v[28:29]
	v_lshl_add_u64 v[34:35], s[18:19], 0, v[32:33]
	v_lshl_add_u64 v[28:29], s[16:17], 0, v[28:29]
	v_mov_b32_e32 v30, v130
	v_cvt_pk_f16_f32 v23, v23, v25
	v_mov_b32_e32 v28, v133
	v_ashrrev_i32_e32 v25, 4, v24
	v_mov_b32_e32 v31, v131
	v_lshl_add_u64 v[34:35], s[18:19], 0, v[26:27]
	v_mov_b32_e32 v34, v132
	v_lshl_add_u64 v[26:27], s[16:17], 0, v[26:27]
	v_mov_b32_e32 v26, v135
	v_ashrrev_i32_e32 v24, 8, v24
	v_add_u32_e32 v24, v25, v24
	v_add_lshl_u32 v24, v22, v24, 2
	v_add_u32_e32 v25, 0, v24
	ds_write_b32 v25, v23 offset:4096
	v_add_u32_e32 v24, s66, v24
	s_nop 0
	v_cndmask_b32_e32 v31, 0, v31, vcc
	v_pk_mul_f32 v[30:31], v[2:3], v[30:31]
	s_nop 0
	v_cndmask_b32_e64 v34, 0, v34, s[40:41]
	v_add_f32_e32 v30, v30, v31
	v_fmac_f32_e32 v30, v6, v34
; DI void hyena_item(const Params& p, int l, int dpr, LAS unsigned char* lds) {
;     ...
;     for (int r = 0; r < 16; ++r) { const int t = tid + NTHR * r;
;         float v[4];
; #pragma unroll
;         for (int c = 0; c < 4; ++c) v[c] = conv3(bint + (size_t)(a + c) * S, t, w[c][0], w[c][1], w[c][2]) * 0.25f;
;         X0[XI(t)] = (hc){(_Float16)v[0], (_Float16)v[1]}; X1[XI(t)] = (hc){(_Float16)v[2], (_Float16)v[3]};
;         X0[XI(t + 8192)] = hzero; X1[XI(t + 8192)] = hzero; }
;     __syncthreads();
	v_mul_f32_e32 v34, 0x3e800000, v30
	v_lshl_add_u64 v[30:31], s[16:17], 0, v[32:33]
	v_mov_b32_e32 v29, v134
	s_nop 0
	v_cndmask_b32_e64 v30, 0, v26, s[40:41]
	s_nop 0
	v_cndmask_b32_e32 v29, 0, v29, vcc
	v_pk_mul_f32 v[26:27], v[10:11], v[28:29]
	s_nop 0
	v_add_f32_e32 v26, v26, v27
	v_fmac_f32_e32 v26, v7, v30
	v_mul_f32_e32 v26, 0x3e800000, v26
	v_cvt_pk_f16_f32 v23, v34, v26
	ds_write_b32 v24, v23 offset:4096
	v_add_u32_e32 v23, 0x2400, v22
	v_ashrrev_i32_e32 v24, 4, v23
	v_ashrrev_i32_e32 v23, 8, v23
	v_add_u32_e32 v23, v24, v23
	v_add_lshl_u32 v23, v22, v23, 2
	v_add_u32_e32 v24, 0, v23
	ds_write_b32 v24, v97 offset:36864
	v_add_u32_e32 v24, 0x600, v22
	v_ashrrev_i32_e32 v25, 31, v24
	v_max_i32_e32 v96, 1, v24
	v_min_i32_e32 v26, 0x1ffe, v24
	v_lshlrev_b64 v[28:29], 2, v[24:25]
	v_lshlrev_b64 v[32:33], 2, v[96:97]
	v_add_u32_e32 v23, s66, v23
	v_ashrrev_i32_e32 v27, 31, v26
	v_lshl_add_u64 v[30:31], s[58:59], 0, v[28:29]
	v_lshl_add_u64 v[34:35], s[58:59], 0, v[32:33]
	ds_write_b32 v23, v97 offset:36864
	v_mov_b32_e32 v30, v136
	v_lshlrev_b64 v[26:27], 2, v[26:27]
	v_mov_b32_e32 v23, v137
	v_lshl_add_u64 v[34:35], s[58:59], 0, v[26:27]
	v_mov_b32_e32 v25, v138
	v_cmp_lt_i32_e32 vcc, 0, v24
	v_cmp_gt_i32_e64 s[40:41], s29, v24
	v_lshl_add_u64 v[34:35], s[62:63], 0, v[32:33]
	s_nop 0
	v_cndmask_b32_e32 v31, 0, v23, vcc
	v_pk_mul_f32 v[30:31], v[0:1], v[30:31]
	s_nop 0
	v_cndmask_b32_e64 v23, 0, v25, s[40:41]
	v_add_f32_e32 v25, v30, v31
	v_fmac_f32_e32 v25, v4, v23
	v_lshl_add_u64 v[30:31], s[62:63], 0, v[28:29]
	v_mul_f32_e32 v23, 0x3e800000, v25
	v_mov_b32_e32 v30, v139
	s_nop 0
	v_mov_b32_e32 v25, v140
	v_lshl_add_u64 v[34:35], s[62:63], 0, v[26:27]
	v_mov_b32_e32 v34, v141
	s_nop 0
	v_cndmask_b32_e32 v31, 0, v25, vcc
	v_pk_mul_f32 v[30:31], v[8:9], v[30:31]
	s_nop 0
	v_cndmask_b32_e64 v25, 0, v34, s[40:41]
	v_add_f32_e32 v30, v30, v31
	v_fmac_f32_e32 v30, v5, v25
	v_mul_f32_e32 v25, 0x3e800000, v30
	v_lshl_add_u64 v[30:31], s[18:19], 0, v[28:29]
	v_lshl_add_u64 v[34:35], s[18:19], 0, v[32:33]
	v_lshl_add_u64 v[28:29], s[16:17], 0, v[28:29]
	v_mov_b32_e32 v30, v142
	v_cvt_pk_f16_f32 v23, v23, v25
	v_mov_b32_e32 v28, v145
	v_ashrrev_i32_e32 v25, 4, v24
	v_mov_b32_e32 v31, v143
	v_lshl_add_u64 v[34:35], s[18:19], 0, v[26:27]
	v_mov_b32_e32 v34, v144
	v_lshl_add_u64 v[26:27], s[16:17], 0, v[26:27]
	v_mov_b32_e32 v26, v147
	v_ashrrev_i32_e32 v24, 8, v24
	v_add_u32_e32 v24, v25, v24
	v_add_lshl_u32 v24, v22, v24, 2
	v_add_u32_e32 v25, 0, v24
	ds_write_b32 v25, v23 offset:6144
	v_add_u32_e32 v24, s66, v24
	s_nop 0
	v_cndmask_b32_e32 v31, 0, v31, vcc
	v_pk_mul_f32 v[30:31], v[2:3], v[30:31]
	s_nop 0
	v_cndmask_b32_e64 v34, 0, v34, s[40:41]
	v_add_f32_e32 v30, v30, v31
	v_fmac_f32_e32 v30, v6, v34
	v_mul_f32_e32 v34, 0x3e800000, v30
	v_lshl_add_u64 v[30:31], s[16:17], 0, v[32:33]
	v_mov_b32_e32 v29, v146
	s_nop 0
	v_cndmask_b32_e64 v30, 0, v26, s[40:41]
	s_nop 0
	v_cndmask_b32_e32 v29, 0, v29, vcc
	v_pk_mul_f32 v[26:27], v[10:11], v[28:29]
	s_nop 0
	v_add_f32_e32 v26, v26, v27
	v_fmac_f32_e32 v26, v7, v30
	v_mul_f32_e32 v26, 0x3e800000, v26
	v_cvt_pk_f16_f32 v23, v34, v26
	ds_write_b32 v24, v23 offset:6144
	v_add_u32_e32 v23, 0x2600, v22
	v_ashrrev_i32_e32 v24, 4, v23
	v_ashrrev_i32_e32 v23, 8, v23
	v_add_u32_e32 v23, v24, v23
	v_add_lshl_u32 v22, v22, v23, 2
	v_add_u32_e32 v23, 0, v22
	v_add_u32_e32 v22, s66, v22
	ds_write_b32 v23, v97 offset:38912
	ds_write_b32 v22, v97 offset:38912
	s_cbranch_scc0 .LBB0_601
	v_mov_b32_e32 v0, v12
	s_waitcnt lgkmcnt(0)
	s_barrier
	s_nop 0
	v_cmp_gt_i32_e32 vcc, s45, v0
	s_and_saveexec_b64 s[20:21], vcc
	s_movk_i32 s6, 0xc000
	s_movk_i32 s8, 0xdff
	s_mov_b64 s[26:27], 0x10000
	s_cbranch_execz .LBB0_605
	v_lshlrev_b32_e32 v1, 2, v0
	s_mov_b64 s[22:23], 0

; #define LAS __attribute__((address_space(3)))
; DI int rev4(int pp) { const unsigned br = __brev((unsigned)pp) >> 18; return (int)(((br & 0x2AAAu) >> 1) | ((br & 0x1555u) << 1)); }
; DI void pw_h(LAS hc* X, const f32x4* spec, int tid) {
; #pragma unroll 8
;     for (int r = 0; r < 16; ++r) {
;         const int k = tid + NTHR * r; const int pp = rev4(k);
;         const f32x4 sp = spec[k]; const cf P = (cf){sp[0], sp[1]} * 256.0f, Mq = (cf){sp[2], sp[3]} * 256.0f;
;         const hc zh = X[XI(pp)]; const cf z = (cf){(float)zh.x, (float)zh.y};
;         if (k == 0) { const cf y = cmul(z, P) + cmul((cf){z.x, -z.y}, Mq); X[XI(pp)] = (hc){(_Float16)y.x, (_Float16)y.y}; }
;         else { const int pm = rev4(16384 - k); const hc zmh = X[XI(pm)]; const cf zm = (cf){(float)zmh.x, (float)zmh.y};
;             const cf y = cmul(z, P) + cmul((cf){zm.x, -zm.y}, Mq);
;             const cf t = cmul((cf){zm.x, -zm.y}, P) + cmul(z, Mq);
;             X[XI(pp)] = (hc){(_Float16)y.x, (_Float16)y.y}; X[XI(pm)] = (hc){(_Float16)t.x, (_Float16)(-t.y)}; }
;     }
;     if (tid == 0) { const int pp = rev4(8192); const f32x4 sp = spec[8192]; const hc zh = X[XI(pp)]; const cf z = (cf){(float)zh.x, (float)zh.y};
;         const cf y = (cmul(z, (cf){sp[0], sp[1]}) + cmul((cf){z.x, -z.y}, (cf){sp[2], sp[3]})) * 256.0f; X[XI(pp)] = (hc){(_Float16)y.x, (_Float16)y.y}; }
.LBB0_616:
	global_load_dwordx4 v[132:135], v224, s[20:21]
	global_load_dwordx4 v[4:7], v[0:1], off
	v_add_u32_e32 v9, s4, v12
	v_add_u32_e32 v2, 0x2000, v9
	v_bfrev_b32_e32 v2, v2
	v_lshrrev_b32_e32 v3, 19, v2
	v_lshrrev_b32_e32 v2, 17, v2
	v_and_b32_e32 v2, 0x2aaa, v2
	v_and_or_b32 v10, v3, s89, v2
	s_movk_i32 s5, 0xe000
	v_cmp_ne_u32_e32 vcc, s5, v9
	v_add_u32_e32 v100, 0x2200, v9
	v_ashrrev_i32_e32 v101, 31, v100
	v_lshl_add_u64 v[100:101], v[100:101], 4, s[20:21]
	global_load_dwordx4 v[104:107], v[100:101], off
	v_add_u32_e32 v100, 0x2400, v9
	v_ashrrev_i32_e32 v101, 31, v100
	v_lshl_add_u64 v[100:101], v[100:101], 4, s[20:21]
	global_load_dwordx4 v[108:111], v[100:101], off
	v_add_u32_e32 v100, 0x2600, v9
	v_ashrrev_i32_e32 v101, 31, v100
	v_lshl_add_u64 v[100:101], v[100:101], 4, s[20:21]
	global_load_dwordx4 v[112:115], v[100:101], off
	v_add_u32_e32 v100, 0x2800, v9
	v_ashrrev_i32_e32 v101, 31, v100
	v_lshl_add_u64 v[100:101], v[100:101], 4, s[20:21]
	global_load_dwordx4 v[116:119], v[100:101], off
	v_add_u32_e32 v100, 0x2a00, v9
	v_ashrrev_i32_e32 v101, 31, v100
	v_lshl_add_u64 v[100:101], v[100:101], 4, s[20:21]
	global_load_dwordx4 v[120:123], v[100:101], off
	v_add_u32_e32 v100, 0x2c00, v9
	v_ashrrev_i32_e32 v101, 31, v100
	v_lshl_add_u64 v[100:101], v[100:101], 4, s[20:21]
	global_load_dwordx4 v[124:127], v[100:101], off
	v_add_u32_e32 v100, 0x2e00, v9
	v_ashrrev_i32_e32 v101, 31, v100
	v_lshl_add_u64 v[100:101], v[100:101], 4, s[20:21]
	global_load_dwordx4 v[128:131], v[100:101], off
	v_add_u32_e32 v100, 0x3000, v9
	v_ashrrev_i32_e32 v101, 31, v100
	v_lshl_add_u64 v[100:101], v[100:101], 4, s[20:21]
	global_load_dword v136, v[100:101], off
	v_add_u32_e32 v100, 0x3200, v9
	v_ashrrev_i32_e32 v101, 31, v100
	v_lshl_add_u64 v[100:101], v[100:101], 4, s[20:21]
	global_load_dword v137, v[100:101], off
	v_add_u32_e32 v100, 0x3400, v9
	v_ashrrev_i32_e32 v101, 31, v100
	v_lshl_add_u64 v[100:101], v[100:101], 4, s[20:21]
	global_load_dword v138, v[100:101], off
	v_add_u32_e32 v100, 0x3600, v9
	v_ashrrev_i32_e32 v101, 31, v100
	v_lshl_add_u64 v[100:101], v[100:101], 4, s[20:21]
	global_load_dword v139, v[100:101], off
	v_add_u32_e32 v100, 0x3800, v9
	v_ashrrev_i32_e32 v101, 31, v100
	v_lshl_add_u64 v[100:101], v[100:101], 4, s[20:21]
	global_load_dword v140, v[100:101], off
	v_add_u32_e32 v100, 0x3a00, v9
	v_ashrrev_i32_e32 v101, 31, v100
	v_lshl_add_u64 v[100:101], v[100:101], 4, s[20:21]
	global_load_dword v141, v[100:101], off
	v_add_u32_e32 v100, 0x3c00, v9
	v_ashrrev_i32_e32 v101, 31, v100
	v_lshl_add_u64 v[100:101], v[100:101], 4, s[20:21]
	global_load_dword v142, v[100:101], off
	v_add_u32_e32 v100, 0x3e00, v9
	v_ashrrev_i32_e32 v101, 31, v100
	v_lshl_add_u64 v[100:101], v[100:101], 4, s[20:21]
	global_load_dword v143, v[100:101], off
	s_waitcnt vmcnt(15)
	v_pk_mul_f32 v[2:3], v[6:7], s[90:91] op_sel_hi:[1,0]
	v_lshl_add_u32 v6, v10, 2, 0
	v_lshrrev_b32_e32 v7, 2, v10
	v_lshrrev_b32_e32 v10, 6, v10
	v_and_b32_e32 v7, 0xffc, v7
	v_and_b32_e32 v10, 0xfc, v10
	v_add3_u32 v10, v6, v7, v10
	ds_read_b32 v7, v10
	v_pk_mul_f32 v[4:5], v[4:5], s[90:91] op_sel_hi:[1,0]
	s_waitcnt lgkmcnt(0)
	v_cvt_f32_f16_e32 v6, v7
	v_cvt_f32_f16_sdwa v7, v7 dst_sel:DWORD dst_unused:UNUSED_PAD src0_sel:WORD_1
	s_and_saveexec_b64 s[22:23], vcc
	s_xor_b64 s[22:23], exec, s[22:23]
	s_cbranch_execz .LBB0_618
	v_add_u32_e32 v11, 0xe00, v8
	v_bfrev_b32_e32 v11, v11
	v_lshrrev_b32_e32 v13, 19, v11
	v_lshrrev_b32_e32 v11, 17, v11
	v_and_b32_e32 v11, 0x2aaa, v11
	v_and_or_b32 v11, v13, s89, v11
	v_lshl_add_u32 v13, v11, 2, 0
	v_lshrrev_b32_e32 v16, 2, v11
	v_lshrrev_b32_e32 v11, 6, v11
	v_and_b32_e32 v16, 0xffc, v16
	v_and_b32_e32 v11, 0xfc, v11
	v_add3_u32 v11, v13, v16, v11
	ds_read_b32 v13, v11
	v_pk_mul_f32 v[18:19], v[6:7], v[4:5] op_sel:[0,0] op_sel_hi:[0,1]
	s_waitcnt lgkmcnt(0)
	v_cvt_f32_f16_e32 v16, v13
	v_cvt_f32_f16_sdwa v17, -v13 dst_sel:DWORD dst_unused:UNUSED_PAD src0_sel:WORD_1
	v_pk_mul_f32 v[22:23], v[16:17], v[2:3] op_sel:[0,0] op_sel_hi:[0,1]
	v_pk_fma_f32 v[18:19], v[6:7], v[4:5], v[18:19] op_sel:[1,1,0] op_sel_hi:[1,0,1] neg_lo:[0,1,0]
	v_pk_fma_f32 v[22:23], v[16:17], v[2:3], v[22:23] op_sel:[1,1,0] op_sel_hi:[1,0,1] neg_lo:[0,1,0]
	v_pk_add_f32 v[18:19], v[18:19], v[22:23]
	v_pk_mul_f32 v[22:23], v[16:17], v[4:5] op_sel:[0,0] op_sel_hi:[0,1]
	v_pk_fma_f32 v[4:5], v[16:17], v[4:5], v[22:23] op_sel:[1,1,0] op_sel_hi:[1,0,1] neg_lo:[0,1,0]
	v_pk_mul_f32 v[16:17], v[6:7], v[2:3] op_sel:[0,0] op_sel_hi:[0,1]
	v_pk_fma_f32 v[2:3], v[6:7], v[2:3], v[16:17] op_sel:[1,1,0] op_sel_hi:[1,0,1] neg_lo:[0,1,0]
	s_nop 0
	v_pk_add_f32 v[2:3], v[4:5], v[2:3]
	v_cvt_pk_f16_f32 v4, v18, v19
	v_cvt_pk_f16_f32 v2, v2, -v3
	ds_write_b32 v10, v4
	ds_write_b32 v11, v2

; DI int rev4(int pp) { const unsigned br = __brev((unsigned)pp) >> 18; return (int)(((br & 0x2AAAu) >> 1) | ((br & 0x1555u) << 1)); }
; DI void pw_h(LAS hc* X, const f32x4* spec, int tid) {
;     ...
;     for (int r = 0; r < 16; ++r) {
;         const int k = tid + NTHR * r; const int pp = rev4(k);
;         const f32x4 sp = spec[k]; const cf P = (cf){sp[0], sp[1]} * 256.0f, Mq = (cf){sp[2], sp[3]} * 256.0f;
;         const hc zh = X[XI(pp)]; const cf z = (cf){(float)zh.x, (float)zh.y};
;         if (k == 0) { const cf y = cmul(z, P) + cmul((cf){z.x, -z.y}, Mq); X[XI(pp)] = (hc){(_Float16)y.x, (_Float16)y.y}; }
;         else { const int pm = rev4(16384 - k); const hc zmh = X[XI(pm)]; const cf zm = (cf){(float)zmh.x, (float)zmh.y};
;             const cf y = cmul(z, P) + cmul((cf){zm.x, -zm.y}, Mq);
;             const cf t = cmul((cf){zm.x, -zm.y}, P) + cmul(z, Mq);
;             X[XI(pp)] = (hc){(_Float16)y.x, (_Float16)y.y}; X[XI(pm)] = (hc){(_Float16)t.x, (_Float16)(-t.y)}; }
.LBB0_620:
	s_or_b64 exec, exec, s[22:23]
	v_add_u32_e32 v2, 0x2200, v9
	v_bfrev_b32_e32 v3, v2
	v_lshrrev_b32_e32 v4, 19, v3
	v_lshrrev_b32_e32 v3, 17, v3
	v_and_b32_e32 v3, 0x2aaa, v3
	v_and_or_b32 v10, v4, s89, v3
	s_movk_i32 s5, 0xde00
	v_cmp_ne_u32_e32 vcc, s5, v9
	s_waitcnt vmcnt(14)
	v_mov_b32_e32 v4, v104
	v_mov_b32_e32 v5, v105
	v_mov_b32_e32 v6, v106
	v_mov_b32_e32 v7, v107
	v_pk_mul_f32 v[2:3], v[6:7], s[90:91] op_sel_hi:[1,0]
	v_lshl_add_u32 v6, v10, 2, 0
	v_lshrrev_b32_e32 v7, 2, v10
	v_lshrrev_b32_e32 v10, 6, v10
	v_and_b32_e32 v7, 0xffc, v7
	v_and_b32_e32 v10, 0xfc, v10
	v_add3_u32 v10, v6, v7, v10
	ds_read_b32 v7, v10
	v_pk_mul_f32 v[4:5], v[4:5], s[90:91] op_sel_hi:[1,0]
	s_waitcnt lgkmcnt(0)
	v_cvt_f32_f16_e32 v6, v7
	v_cvt_f32_f16_sdwa v7, v7 dst_sel:DWORD dst_unused:UNUSED_PAD src0_sel:WORD_1
	s_and_saveexec_b64 s[22:23], vcc
	s_xor_b64 s[22:23], exec, s[22:23]
	s_cbranch_execz .LBB0_622
	v_add_u32_e32 v11, 0xc00, v8
	v_bfrev_b32_e32 v11, v11
	v_lshrrev_b32_e32 v13, 19, v11
	v_lshrrev_b32_e32 v11, 17, v11
	v_and_b32_e32 v11, 0x2aaa, v11
	v_and_or_b32 v11, v13, s89, v11
	v_lshl_add_u32 v13, v11, 2, 0
	v_lshrrev_b32_e32 v16, 2, v11
	v_lshrrev_b32_e32 v11, 6, v11
	v_and_b32_e32 v16, 0xffc, v16
	v_and_b32_e32 v11, 0xfc, v11
	v_add3_u32 v11, v13, v16, v11
	ds_read_b32 v13, v11
	v_pk_mul_f32 v[18:19], v[6:7], v[4:5] op_sel:[0,0] op_sel_hi:[0,1]
	s_waitcnt lgkmcnt(0)
	v_cvt_f32_f16_e32 v16, v13
	v_cvt_f32_f16_sdwa v17, -v13 dst_sel:DWORD dst_unused:UNUSED_PAD src0_sel:WORD_1
	v_pk_mul_f32 v[22:23], v[16:17], v[2:3] op_sel:[0,0] op_sel_hi:[0,1]
	v_pk_fma_f32 v[18:19], v[6:7], v[4:5], v[18:19] op_sel:[1,1,0] op_sel_hi:[1,0,1] neg_lo:[0,1,0]
	v_pk_fma_f32 v[22:23], v[16:17], v[2:3], v[22:23] op_sel:[1,1,0] op_sel_hi:[1,0,1] neg_lo:[0,1,0]
	v_pk_add_f32 v[18:19], v[18:19], v[22:23]
	v_pk_mul_f32 v[22:23], v[16:17], v[4:5] op_sel:[0,0] op_sel_hi:[0,1]
	v_pk_fma_f32 v[4:5], v[16:17], v[4:5], v[22:23] op_sel:[1,1,0] op_sel_hi:[1,0,1] neg_lo:[0,1,0]
	v_pk_mul_f32 v[16:17], v[6:7], v[2:3] op_sel:[0,0] op_sel_hi:[0,1]
	v_pk_fma_f32 v[2:3], v[6:7], v[2:3], v[16:17] op_sel:[1,1,0] op_sel_hi:[1,0,1] neg_lo:[0,1,0]
	s_nop 0
	v_pk_add_f32 v[2:3], v[4:5], v[2:3]
	v_cvt_pk_f16_f32 v4, v18, v19
	v_cvt_pk_f16_f32 v2, v2, -v3
	ds_write_b32 v10, v4
	ds_write_b32 v11, v2

; DI int rev4(int pp) { const unsigned br = __brev((unsigned)pp) >> 18; return (int)(((br & 0x2AAAu) >> 1) | ((br & 0x1555u) << 1)); }
; DI void pw_h(LAS hc* X, const f32x4* spec, int tid) {
;     ...
;     for (int r = 0; r < 16; ++r) {
;         const int k = tid + NTHR * r; const int pp = rev4(k);
;         const f32x4 sp = spec[k]; const cf P = (cf){sp[0], sp[1]} * 256.0f, Mq = (cf){sp[2], sp[3]} * 256.0f;
;         const hc zh = X[XI(pp)]; const cf z = (cf){(float)zh.x, (float)zh.y};
;         if (k == 0) { const cf y = cmul(z, P) + cmul((cf){z.x, -z.y}, Mq); X[XI(pp)] = (hc){(_Float16)y.x, (_Float16)y.y}; }
;         else { const int pm = rev4(16384 - k); const hc zmh = X[XI(pm)]; const cf zm = (cf){(float)zmh.x, (float)zmh.y};
;             const cf y = cmul(z, P) + cmul((cf){zm.x, -zm.y}, Mq);
;             const cf t = cmul((cf){zm.x, -zm.y}, P) + cmul(z, Mq);
;             X[XI(pp)] = (hc){(_Float16)y.x, (_Float16)y.y}; X[XI(pm)] = (hc){(_Float16)t.x, (_Float16)(-t.y)}; }
.LBB0_624:
	s_or_b64 exec, exec, s[22:23]
	v_add_u32_e32 v2, 0x2400, v9
	v_bfrev_b32_e32 v3, v2
	v_lshrrev_b32_e32 v4, 19, v3
	v_lshrrev_b32_e32 v3, 17, v3
	v_and_b32_e32 v3, 0x2aaa, v3
	v_and_or_b32 v10, v4, s89, v3
	s_movk_i32 s5, 0xdc00
	v_cmp_ne_u32_e32 vcc, s5, v9
	s_waitcnt vmcnt(13)
	v_mov_b32_e32 v4, v108
	v_mov_b32_e32 v5, v109
	v_mov_b32_e32 v6, v110
	v_mov_b32_e32 v7, v111
	v_pk_mul_f32 v[2:3], v[6:7], s[90:91] op_sel_hi:[1,0]
	v_lshl_add_u32 v6, v10, 2, 0
	v_lshrrev_b32_e32 v7, 2, v10
	v_lshrrev_b32_e32 v10, 6, v10
	v_and_b32_e32 v7, 0xffc, v7
	v_and_b32_e32 v10, 0xfc, v10
	v_add3_u32 v10, v6, v7, v10
	ds_read_b32 v7, v10
	v_pk_mul_f32 v[4:5], v[4:5], s[90:91] op_sel_hi:[1,0]
	s_waitcnt lgkmcnt(0)
	v_cvt_f32_f16_e32 v6, v7
	v_cvt_f32_f16_sdwa v7, v7 dst_sel:DWORD dst_unused:UNUSED_PAD src0_sel:WORD_1
	s_and_saveexec_b64 s[22:23], vcc
	s_xor_b64 s[22:23], exec, s[22:23]
	s_cbranch_execz .LBB0_626
	v_add_u32_e32 v11, 0xa00, v8
	v_bfrev_b32_e32 v11, v11
	v_lshrrev_b32_e32 v13, 19, v11
	v_lshrrev_b32_e32 v11, 17, v11
	v_and_b32_e32 v11, 0x2aaa, v11
	v_and_or_b32 v11, v13, s89, v11
	v_lshl_add_u32 v13, v11, 2, 0
	v_lshrrev_b32_e32 v16, 2, v11
	v_lshrrev_b32_e32 v11, 6, v11
	v_and_b32_e32 v16, 0xffc, v16
	v_and_b32_e32 v11, 0xfc, v11
	v_add3_u32 v11, v13, v16, v11
	ds_read_b32 v13, v11
	v_pk_mul_f32 v[18:19], v[6:7], v[4:5] op_sel:[0,0] op_sel_hi:[0,1]
	s_waitcnt lgkmcnt(0)
	v_cvt_f32_f16_e32 v16, v13
	v_cvt_f32_f16_sdwa v17, -v13 dst_sel:DWORD dst_unused:UNUSED_PAD src0_sel:WORD_1
	v_pk_mul_f32 v[22:23], v[16:17], v[2:3] op_sel:[0,0] op_sel_hi:[0,1]
	v_pk_fma_f32 v[18:19], v[6:7], v[4:5], v[18:19] op_sel:[1,1,0] op_sel_hi:[1,0,1] neg_lo:[0,1,0]
	v_pk_fma_f32 v[22:23], v[16:17], v[2:3], v[22:23] op_sel:[1,1,0] op_sel_hi:[1,0,1] neg_lo:[0,1,0]
	v_pk_add_f32 v[18:19], v[18:19], v[22:23]
	v_pk_mul_f32 v[22:23], v[16:17], v[4:5] op_sel:[0,0] op_sel_hi:[0,1]
	v_pk_fma_f32 v[4:5], v[16:17], v[4:5], v[22:23] op_sel:[1,1,0] op_sel_hi:[1,0,1] neg_lo:[0,1,0]
	v_pk_mul_f32 v[16:17], v[6:7], v[2:3] op_sel:[0,0] op_sel_hi:[0,1]
	v_pk_fma_f32 v[2:3], v[6:7], v[2:3], v[16:17] op_sel:[1,1,0] op_sel_hi:[1,0,1] neg_lo:[0,1,0]
	s_nop 0
	v_pk_add_f32 v[2:3], v[4:5], v[2:3]
	v_cvt_pk_f16_f32 v4, v18, v19
	v_cvt_pk_f16_f32 v2, v2, -v3
	ds_write_b32 v10, v4
	ds_write_b32 v11, v2

; DI int rev4(int pp) { const unsigned br = __brev((unsigned)pp) >> 18; return (int)(((br & 0x2AAAu) >> 1) | ((br & 0x1555u) << 1)); }
; DI void pw_h(LAS hc* X, const f32x4* spec, int tid) {
;     ...
;     for (int r = 0; r < 16; ++r) {
;         const int k = tid + NTHR * r; const int pp = rev4(k);
;         const f32x4 sp = spec[k]; const cf P = (cf){sp[0], sp[1]} * 256.0f, Mq = (cf){sp[2], sp[3]} * 256.0f;
;         const hc zh = X[XI(pp)]; const cf z = (cf){(float)zh.x, (float)zh.y};
;         if (k == 0) { const cf y = cmul(z, P) + cmul((cf){z.x, -z.y}, Mq); X[XI(pp)] = (hc){(_Float16)y.x, (_Float16)y.y}; }
;         else { const int pm = rev4(16384 - k); const hc zmh = X[XI(pm)]; const cf zm = (cf){(float)zmh.x, (float)zmh.y};
;             const cf y = cmul(z, P) + cmul((cf){zm.x, -zm.y}, Mq);
;             const cf t = cmul((cf){zm.x, -zm.y}, P) + cmul(z, Mq);
;             X[XI(pp)] = (hc){(_Float16)y.x, (_Float16)y.y}; X[XI(pm)] = (hc){(_Float16)t.x, (_Float16)(-t.y)}; }
.LBB0_628:
	s_or_b64 exec, exec, s[22:23]
	v_add_u32_e32 v2, 0x2600, v9
	v_bfrev_b32_e32 v3, v2
	v_lshrrev_b32_e32 v4, 19, v3
	v_lshrrev_b32_e32 v3, 17, v3
	v_and_b32_e32 v3, 0x2aaa, v3
	v_and_or_b32 v10, v4, s89, v3
	s_movk_i32 s5, 0xda00
	v_cmp_ne_u32_e32 vcc, s5, v9
	s_waitcnt vmcnt(12)
	v_mov_b32_e32 v4, v112
	v_mov_b32_e32 v5, v113
	v_mov_b32_e32 v6, v114
	v_mov_b32_e32 v7, v115
	v_pk_mul_f32 v[2:3], v[6:7], s[90:91] op_sel_hi:[1,0]
	v_lshl_add_u32 v6, v10, 2, 0
	v_lshrrev_b32_e32 v7, 2, v10
	v_lshrrev_b32_e32 v10, 6, v10
	v_and_b32_e32 v7, 0xffc, v7
	v_and_b32_e32 v10, 0xfc, v10
	v_add3_u32 v10, v6, v7, v10
	ds_read_b32 v7, v10
	v_pk_mul_f32 v[4:5], v[4:5], s[90:91] op_sel_hi:[1,0]
	s_waitcnt lgkmcnt(0)
	v_cvt_f32_f16_e32 v6, v7
	v_cvt_f32_f16_sdwa v7, v7 dst_sel:DWORD dst_unused:UNUSED_PAD src0_sel:WORD_1
	s_and_saveexec_b64 s[22:23], vcc
	s_xor_b64 s[22:23], exec, s[22:23]
	s_cbranch_execz .LBB0_630
	v_add_u32_e32 v11, 0x800, v8
	v_bfrev_b32_e32 v11, v11
	v_lshrrev_b32_e32 v13, 19, v11
	v_lshrrev_b32_e32 v11, 17, v11
	v_and_b32_e32 v11, 0x2aaa, v11
	v_and_or_b32 v11, v13, s89, v11
	v_lshl_add_u32 v13, v11, 2, 0
	v_lshrrev_b32_e32 v16, 2, v11
	v_lshrrev_b32_e32 v11, 6, v11
	v_and_b32_e32 v16, 0xffc, v16
	v_and_b32_e32 v11, 0xfc, v11
	v_add3_u32 v11, v13, v16, v11
	ds_read_b32 v13, v11
	v_pk_mul_f32 v[18:19], v[6:7], v[4:5] op_sel:[0,0] op_sel_hi:[0,1]
	s_waitcnt lgkmcnt(0)
	v_cvt_f32_f16_e32 v16, v13
	v_cvt_f32_f16_sdwa v17, -v13 dst_sel:DWORD dst_unused:UNUSED_PAD src0_sel:WORD_1
	v_pk_mul_f32 v[22:23], v[16:17], v[2:3] op_sel:[0,0] op_sel_hi:[0,1]
	v_pk_fma_f32 v[18:19], v[6:7], v[4:5], v[18:19] op_sel:[1,1,0] op_sel_hi:[1,0,1] neg_lo:[0,1,0]
	v_pk_fma_f32 v[22:23], v[16:17], v[2:3], v[22:23] op_sel:[1,1,0] op_sel_hi:[1,0,1] neg_lo:[0,1,0]
	v_pk_add_f32 v[18:19], v[18:19], v[22:23]
	v_pk_mul_f32 v[22:23], v[16:17], v[4:5] op_sel:[0,0] op_sel_hi:[0,1]
	v_pk_fma_f32 v[4:5], v[16:17], v[4:5], v[22:23] op_sel:[1,1,0] op_sel_hi:[1,0,1] neg_lo:[0,1,0]
	v_pk_mul_f32 v[16:17], v[6:7], v[2:3] op_sel:[0,0] op_sel_hi:[0,1]
	v_pk_fma_f32 v[2:3], v[6:7], v[2:3], v[16:17] op_sel:[1,1,0] op_sel_hi:[1,0,1] neg_lo:[0,1,0]
	s_nop 0
	v_pk_add_f32 v[2:3], v[4:5], v[2:3]
	v_cvt_pk_f16_f32 v4, v18, v19
	v_cvt_pk_f16_f32 v2, v2, -v3
	ds_write_b32 v10, v4
	ds_write_b32 v11, v2

; DI int rev4(int pp) { const unsigned br = __brev((unsigned)pp) >> 18; return (int)(((br & 0x2AAAu) >> 1) | ((br & 0x1555u) << 1)); }
; DI void pw_h(LAS hc* X, const f32x4* spec, int tid) {
;     ...
;     for (int r = 0; r < 16; ++r) {
;         const int k = tid + NTHR * r; const int pp = rev4(k);
;         const f32x4 sp = spec[k]; const cf P = (cf){sp[0], sp[1]} * 256.0f, Mq = (cf){sp[2], sp[3]} * 256.0f;
;         const hc zh = X[XI(pp)]; const cf z = (cf){(float)zh.x, (float)zh.y};
;         if (k == 0) { const cf y = cmul(z, P) + cmul((cf){z.x, -z.y}, Mq); X[XI(pp)] = (hc){(_Float16)y.x, (_Float16)y.y}; }
;         else { const int pm = rev4(16384 - k); const hc zmh = X[XI(pm)]; const cf zm = (cf){(float)zmh.x, (float)zmh.y};
;             const cf y = cmul(z, P) + cmul((cf){zm.x, -zm.y}, Mq);
;             const cf t = cmul((cf){zm.x, -zm.y}, P) + cmul(z, Mq);
;             X[XI(pp)] = (hc){(_Float16)y.x, (_Float16)y.y}; X[XI(pm)] = (hc){(_Float16)t.x, (_Float16)(-t.y)}; }
.LBB0_632:
	s_or_b64 exec, exec, s[22:23]
	v_add_u32_e32 v2, 0x2800, v9
	v_bfrev_b32_e32 v3, v2
	v_lshrrev_b32_e32 v4, 19, v3
	v_lshrrev_b32_e32 v3, 17, v3
	v_and_b32_e32 v3, 0x2aaa, v3
	v_and_or_b32 v10, v4, s89, v3
	s_movk_i32 s5, 0xd800
	v_cmp_ne_u32_e32 vcc, s5, v9
	s_waitcnt vmcnt(11)
	v_mov_b32_e32 v4, v116
	v_mov_b32_e32 v5, v117
	v_mov_b32_e32 v6, v118
	v_mov_b32_e32 v7, v119
	v_pk_mul_f32 v[2:3], v[6:7], s[90:91] op_sel_hi:[1,0]
	v_lshl_add_u32 v6, v10, 2, 0
	v_lshrrev_b32_e32 v7, 2, v10
	v_lshrrev_b32_e32 v10, 6, v10
	v_and_b32_e32 v7, 0xffc, v7
	v_and_b32_e32 v10, 0xfc, v10
	v_add3_u32 v10, v6, v7, v10
	ds_read_b32 v7, v10
	v_pk_mul_f32 v[4:5], v[4:5], s[90:91] op_sel_hi:[1,0]
	s_waitcnt lgkmcnt(0)
	v_cvt_f32_f16_e32 v6, v7
	v_cvt_f32_f16_sdwa v7, v7 dst_sel:DWORD dst_unused:UNUSED_PAD src0_sel:WORD_1
	s_and_saveexec_b64 s[22:23], vcc
	s_xor_b64 s[22:23], exec, s[22:23]
	s_cbranch_execz .LBB0_634
	v_add_u32_e32 v11, 0x600, v8
	v_bfrev_b32_e32 v11, v11
	v_lshrrev_b32_e32 v13, 19, v11
	v_lshrrev_b32_e32 v11, 17, v11
	v_and_b32_e32 v11, 0x2aaa, v11
	v_and_or_b32 v11, v13, s89, v11
	v_lshl_add_u32 v13, v11, 2, 0
	v_lshrrev_b32_e32 v16, 2, v11
	v_lshrrev_b32_e32 v11, 6, v11
	v_and_b32_e32 v16, 0xffc, v16
	v_and_b32_e32 v11, 0xfc, v11
	v_add3_u32 v11, v13, v16, v11
	ds_read_b32 v13, v11
	v_pk_mul_f32 v[18:19], v[6:7], v[4:5] op_sel:[0,0] op_sel_hi:[0,1]
	s_waitcnt lgkmcnt(0)
	v_cvt_f32_f16_e32 v16, v13
	v_cvt_f32_f16_sdwa v17, -v13 dst_sel:DWORD dst_unused:UNUSED_PAD src0_sel:WORD_1
	v_pk_mul_f32 v[22:23], v[16:17], v[2:3] op_sel:[0,0] op_sel_hi:[0,1]
	v_pk_fma_f32 v[18:19], v[6:7], v[4:5], v[18:19] op_sel:[1,1,0] op_sel_hi:[1,0,1] neg_lo:[0,1,0]
	v_pk_fma_f32 v[22:23], v[16:17], v[2:3], v[22:23] op_sel:[1,1,0] op_sel_hi:[1,0,1] neg_lo:[0,1,0]
	v_pk_add_f32 v[18:19], v[18:19], v[22:23]
	v_pk_mul_f32 v[22:23], v[16:17], v[4:5] op_sel:[0,0] op_sel_hi:[0,1]
	v_pk_fma_f32 v[4:5], v[16:17], v[4:5], v[22:23] op_sel:[1,1,0] op_sel_hi:[1,0,1] neg_lo:[0,1,0]
	v_pk_mul_f32 v[16:17], v[6:7], v[2:3] op_sel:[0,0] op_sel_hi:[0,1]
	v_pk_fma_f32 v[2:3], v[6:7], v[2:3], v[16:17] op_sel:[1,1,0] op_sel_hi:[1,0,1] neg_lo:[0,1,0]
	s_nop 0
	v_pk_add_f32 v[2:3], v[4:5], v[2:3]
	v_cvt_pk_f16_f32 v4, v18, v19
	v_cvt_pk_f16_f32 v2, v2, -v3
	ds_write_b32 v10, v4
	ds_write_b32 v11, v2

; DI int rev4(int pp) { const unsigned br = __brev((unsigned)pp) >> 18; return (int)(((br & 0x2AAAu) >> 1) | ((br & 0x1555u) << 1)); }
; DI void pw_h(LAS hc* X, const f32x4* spec, int tid) {
;     ...
;     for (int r = 0; r < 16; ++r) {
;         const int k = tid + NTHR * r; const int pp = rev4(k);
;         const f32x4 sp = spec[k]; const cf P = (cf){sp[0], sp[1]} * 256.0f, Mq = (cf){sp[2], sp[3]} * 256.0f;
;         const hc zh = X[XI(pp)]; const cf z = (cf){(float)zh.x, (float)zh.y};
;         if (k == 0) { const cf y = cmul(z, P) + cmul((cf){z.x, -z.y}, Mq); X[XI(pp)] = (hc){(_Float16)y.x, (_Float16)y.y}; }
;         else { const int pm = rev4(16384 - k); const hc zmh = X[XI(pm)]; const cf zm = (cf){(float)zmh.x, (float)zmh.y};
;             const cf y = cmul(z, P) + cmul((cf){zm.x, -zm.y}, Mq);
;             const cf t = cmul((cf){zm.x, -zm.y}, P) + cmul(z, Mq);
;             X[XI(pp)] = (hc){(_Float16)y.x, (_Float16)y.y}; X[XI(pm)] = (hc){(_Float16)t.x, (_Float16)(-t.y)}; }
.LBB0_636:
	s_or_b64 exec, exec, s[22:23]
	v_add_u32_e32 v2, 0x2a00, v9
	v_bfrev_b32_e32 v3, v2
	v_lshrrev_b32_e32 v4, 19, v3
	v_lshrrev_b32_e32 v3, 17, v3
	v_and_b32_e32 v3, 0x2aaa, v3
	v_and_or_b32 v10, v4, s89, v3
	s_movk_i32 s5, 0xd600
	v_cmp_ne_u32_e32 vcc, s5, v9
	s_waitcnt vmcnt(10)
	v_mov_b32_e32 v4, v120
	v_mov_b32_e32 v5, v121
	v_mov_b32_e32 v6, v122
	v_mov_b32_e32 v7, v123
	v_pk_mul_f32 v[2:3], v[6:7], s[90:91] op_sel_hi:[1,0]
	v_lshl_add_u32 v6, v10, 2, 0
	v_lshrrev_b32_e32 v7, 2, v10
	v_lshrrev_b32_e32 v10, 6, v10
	v_and_b32_e32 v7, 0xffc, v7
	v_and_b32_e32 v10, 0xfc, v10
	v_add3_u32 v10, v6, v7, v10
	ds_read_b32 v7, v10
	v_pk_mul_f32 v[4:5], v[4:5], s[90:91] op_sel_hi:[1,0]
	s_waitcnt lgkmcnt(0)
	v_cvt_f32_f16_e32 v6, v7
	v_cvt_f32_f16_sdwa v7, v7 dst_sel:DWORD dst_unused:UNUSED_PAD src0_sel:WORD_1
	s_and_saveexec_b64 s[22:23], vcc
	s_xor_b64 s[22:23], exec, s[22:23]
	s_cbranch_execz .LBB0_638
	v_add_u32_e32 v11, 0x400, v8
	v_bfrev_b32_e32 v11, v11
	v_lshrrev_b32_e32 v13, 19, v11
	v_lshrrev_b32_e32 v11, 17, v11
	v_and_b32_e32 v11, 0x2aaa, v11
	v_and_or_b32 v11, v13, s89, v11
	v_lshl_add_u32 v13, v11, 2, 0
	v_lshrrev_b32_e32 v16, 2, v11
	v_lshrrev_b32_e32 v11, 6, v11
	v_and_b32_e32 v16, 0xffc, v16
	v_and_b32_e32 v11, 0xfc, v11
	v_add3_u32 v11, v13, v16, v11
	ds_read_b32 v13, v11
	v_pk_mul_f32 v[18:19], v[6:7], v[4:5] op_sel:[0,0] op_sel_hi:[0,1]
	s_waitcnt lgkmcnt(0)
	v_cvt_f32_f16_e32 v16, v13
	v_cvt_f32_f16_sdwa v17, -v13 dst_sel:DWORD dst_unused:UNUSED_PAD src0_sel:WORD_1
	v_pk_mul_f32 v[22:23], v[16:17], v[2:3] op_sel:[0,0] op_sel_hi:[0,1]
	v_pk_fma_f32 v[18:19], v[6:7], v[4:5], v[18:19] op_sel:[1,1,0] op_sel_hi:[1,0,1] neg_lo:[0,1,0]
	v_pk_fma_f32 v[22:23], v[16:17], v[2:3], v[22:23] op_sel:[1,1,0] op_sel_hi:[1,0,1] neg_lo:[0,1,0]
	v_pk_add_f32 v[18:19], v[18:19], v[22:23]
	v_pk_mul_f32 v[22:23], v[16:17], v[4:5] op_sel:[0,0] op_sel_hi:[0,1]
	v_pk_fma_f32 v[4:5], v[16:17], v[4:5], v[22:23] op_sel:[1,1,0] op_sel_hi:[1,0,1] neg_lo:[0,1,0]
	v_pk_mul_f32 v[16:17], v[6:7], v[2:3] op_sel:[0,0] op_sel_hi:[0,1]
	v_pk_fma_f32 v[2:3], v[6:7], v[2:3], v[16:17] op_sel:[1,1,0] op_sel_hi:[1,0,1] neg_lo:[0,1,0]
	s_nop 0
	v_pk_add_f32 v[2:3], v[4:5], v[2:3]
	v_cvt_pk_f16_f32 v4, v18, v19
	v_cvt_pk_f16_f32 v2, v2, -v3
	ds_write_b32 v10, v4
	ds_write_b32 v11, v2

; DI int rev4(int pp) { const unsigned br = __brev((unsigned)pp) >> 18; return (int)(((br & 0x2AAAu) >> 1) | ((br & 0x1555u) << 1)); }
; DI void pw_h(LAS hc* X, const f32x4* spec, int tid) {
;     ...
;     for (int r = 0; r < 16; ++r) {
;         const int k = tid + NTHR * r; const int pp = rev4(k);
;         const f32x4 sp = spec[k]; const cf P = (cf){sp[0], sp[1]} * 256.0f, Mq = (cf){sp[2], sp[3]} * 256.0f;
;         const hc zh = X[XI(pp)]; const cf z = (cf){(float)zh.x, (float)zh.y};
;         if (k == 0) { const cf y = cmul(z, P) + cmul((cf){z.x, -z.y}, Mq); X[XI(pp)] = (hc){(_Float16)y.x, (_Float16)y.y}; }
;         else { const int pm = rev4(16384 - k); const hc zmh = X[XI(pm)]; const cf zm = (cf){(float)zmh.x, (float)zmh.y};
;             const cf y = cmul(z, P) + cmul((cf){zm.x, -zm.y}, Mq);
;             const cf t = cmul((cf){zm.x, -zm.y}, P) + cmul(z, Mq);
;             X[XI(pp)] = (hc){(_Float16)y.x, (_Float16)y.y}; X[XI(pm)] = (hc){(_Float16)t.x, (_Float16)(-t.y)}; }
;     }
.LBB0_640:
	s_or_b64 exec, exec, s[22:23]
	v_add_u32_e32 v2, 0x2c00, v9
	v_bfrev_b32_e32 v3, v2
	v_lshrrev_b32_e32 v4, 19, v3
	v_lshrrev_b32_e32 v3, 17, v3
	v_and_b32_e32 v3, 0x2aaa, v3
	v_and_or_b32 v10, v4, s89, v3
	v_cmp_ne_u32_e32 vcc, s96, v9
	s_waitcnt vmcnt(9)
	v_mov_b32_e32 v4, v124
	v_mov_b32_e32 v5, v125
	v_mov_b32_e32 v6, v126
	v_mov_b32_e32 v7, v127
	v_pk_mul_f32 v[2:3], v[6:7], s[90:91] op_sel_hi:[1,0]
	v_lshl_add_u32 v6, v10, 2, 0
	v_lshrrev_b32_e32 v7, 2, v10
	v_lshrrev_b32_e32 v10, 6, v10
	v_and_b32_e32 v7, 0xffc, v7
	v_and_b32_e32 v10, 0xfc, v10
	v_add3_u32 v10, v6, v7, v10
	ds_read_b32 v7, v10
	v_pk_mul_f32 v[4:5], v[4:5], s[90:91] op_sel_hi:[1,0]
	s_waitcnt lgkmcnt(0)
	v_cvt_f32_f16_e32 v6, v7
	v_cvt_f32_f16_sdwa v7, v7 dst_sel:DWORD dst_unused:UNUSED_PAD src0_sel:WORD_1
	s_and_saveexec_b64 s[22:23], vcc
	s_xor_b64 s[22:23], exec, s[22:23]
	s_cbranch_execz .LBB0_642
	v_add_u32_e32 v11, 0x200, v8
	v_bfrev_b32_e32 v11, v11
	v_lshrrev_b32_e32 v13, 19, v11
	v_lshrrev_b32_e32 v11, 17, v11
	v_and_b32_e32 v11, 0x2aaa, v11
	v_and_or_b32 v11, v13, s89, v11
	v_lshl_add_u32 v13, v11, 2, 0
	v_lshrrev_b32_e32 v16, 2, v11
	v_lshrrev_b32_e32 v11, 6, v11
	v_and_b32_e32 v16, 0xffc, v16
	v_and_b32_e32 v11, 0xfc, v11
	v_add3_u32 v11, v13, v16, v11
	ds_read_b32 v13, v11
	v_pk_mul_f32 v[18:19], v[6:7], v[4:5] op_sel:[0,0] op_sel_hi:[0,1]
	s_waitcnt lgkmcnt(0)
	v_cvt_f32_f16_e32 v16, v13
	v_cvt_f32_f16_sdwa v17, -v13 dst_sel:DWORD dst_unused:UNUSED_PAD src0_sel:WORD_1
	v_pk_mul_f32 v[22:23], v[16:17], v[2:3] op_sel:[0,0] op_sel_hi:[0,1]
	v_pk_fma_f32 v[18:19], v[6:7], v[4:5], v[18:19] op_sel:[1,1,0] op_sel_hi:[1,0,1] neg_lo:[0,1,0]
	v_pk_fma_f32 v[22:23], v[16:17], v[2:3], v[22:23] op_sel:[1,1,0] op_sel_hi:[1,0,1] neg_lo:[0,1,0]
	v_pk_add_f32 v[18:19], v[18:19], v[22:23]
	v_pk_mul_f32 v[22:23], v[16:17], v[4:5] op_sel:[0,0] op_sel_hi:[0,1]
	v_pk_fma_f32 v[4:5], v[16:17], v[4:5], v[22:23] op_sel:[1,1,0] op_sel_hi:[1,0,1] neg_lo:[0,1,0]
	v_pk_mul_f32 v[16:17], v[6:7], v[2:3] op_sel:[0,0] op_sel_hi:[0,1]
	v_pk_fma_f32 v[2:3], v[6:7], v[2:3], v[16:17] op_sel:[1,1,0] op_sel_hi:[1,0,1] neg_lo:[0,1,0]
	s_nop 0
	v_pk_add_f32 v[2:3], v[4:5], v[2:3]
	v_cvt_pk_f16_f32 v4, v18, v19
	v_cvt_pk_f16_f32 v2, v2, -v3
	ds_write_b32 v10, v4
	ds_write_b32 v11, v2

; DI int rev4(int pp) { const unsigned br = __brev((unsigned)pp) >> 18; return (int)(((br & 0x2AAAu) >> 1) | ((br & 0x1555u) << 1)); }
; DI void pw_h(LAS hc* X, const f32x4* spec, int tid) {
;     ...
;     for (int r = 0; r < 16; ++r) {
;         const int k = tid + NTHR * r; const int pp = rev4(k);
;         const f32x4 sp = spec[k]; const cf P = (cf){sp[0], sp[1]} * 256.0f, Mq = (cf){sp[2], sp[3]} * 256.0f;
;         const hc zh = X[XI(pp)]; const cf z = (cf){(float)zh.x, (float)zh.y};
;         if (k == 0) { const cf y = cmul(z, P) + cmul((cf){z.x, -z.y}, Mq); X[XI(pp)] = (hc){(_Float16)y.x, (_Float16)y.y}; }
;         else { const int pm = rev4(16384 - k); const hc zmh = X[XI(pm)]; const cf zm = (cf){(float)zmh.x, (float)zmh.y};
;             const cf y = cmul(z, P) + cmul((cf){zm.x, -zm.y}, Mq);
;             const cf t = cmul((cf){zm.x, -zm.y}, P) + cmul(z, Mq);
;             X[XI(pp)] = (hc){(_Float16)y.x, (_Float16)y.y}; X[XI(pm)] = (hc){(_Float16)t.x, (_Float16)(-t.y)}; }
;     }
.LBB0_644:
	s_or_b64 exec, exec, s[22:23]
	v_add_u32_e32 v2, 0x2e00, v9
	v_bfrev_b32_e32 v3, v2
	v_lshrrev_b32_e32 v4, 19, v3
	v_lshrrev_b32_e32 v3, 17, v3
	v_and_b32_e32 v3, 0x2aaa, v3
	v_and_or_b32 v10, v4, s89, v3
	v_cmp_ne_u32_e32 vcc, s84, v9
	s_waitcnt vmcnt(8)
	v_mov_b32_e32 v4, v128
	v_mov_b32_e32 v5, v129
	v_mov_b32_e32 v6, v130
	v_mov_b32_e32 v7, v131
	v_pk_mul_f32 v[2:3], v[6:7], s[90:91] op_sel_hi:[1,0]
	v_lshl_add_u32 v6, v10, 2, 0
	v_lshrrev_b32_e32 v7, 2, v10
	v_lshrrev_b32_e32 v10, 6, v10
	v_and_b32_e32 v7, 0xffc, v7
	v_and_b32_e32 v10, 0xfc, v10
	v_add3_u32 v10, v6, v7, v10
	ds_read_b32 v7, v10
	v_pk_mul_f32 v[4:5], v[4:5], s[90:91] op_sel_hi:[1,0]
	s_waitcnt lgkmcnt(0)
	v_cvt_f32_f16_e32 v6, v7
	v_cvt_f32_f16_sdwa v7, v7 dst_sel:DWORD dst_unused:UNUSED_PAD src0_sel:WORD_1
	s_and_saveexec_b64 s[22:23], vcc
	s_xor_b64 s[22:23], exec, s[22:23]
	s_cbranch_execz .LBB0_646
	v_bfrev_b32_e32 v9, v8
	v_lshrrev_b32_e32 v11, 19, v9
	v_lshrrev_b32_e32 v9, 17, v9
	v_and_b32_e32 v9, 0x2aaa, v9
	v_and_or_b32 v9, v11, s89, v9
	v_lshl_add_u32 v11, v9, 2, 0
	v_lshrrev_b32_e32 v13, 2, v9
	v_lshrrev_b32_e32 v9, 6, v9
	v_and_b32_e32 v13, 0xffc, v13
	v_and_b32_e32 v9, 0xfc, v9
	v_add3_u32 v9, v11, v13, v9
	ds_read_b32 v11, v9
	v_pk_mul_f32 v[18:19], v[6:7], v[4:5] op_sel:[0,0] op_sel_hi:[0,1]
	s_waitcnt lgkmcnt(0)
	v_cvt_f32_f16_e32 v16, v11
	v_cvt_f32_f16_sdwa v17, -v11 dst_sel:DWORD dst_unused:UNUSED_PAD src0_sel:WORD_1
	v_pk_mul_f32 v[22:23], v[16:17], v[2:3] op_sel:[0,0] op_sel_hi:[0,1]
	v_pk_fma_f32 v[18:19], v[6:7], v[4:5], v[18:19] op_sel:[1,1,0] op_sel_hi:[1,0,1] neg_lo:[0,1,0]
	v_pk_fma_f32 v[22:23], v[16:17], v[2:3], v[22:23] op_sel:[1,1,0] op_sel_hi:[1,0,1] neg_lo:[0,1,0]
	v_pk_add_f32 v[18:19], v[18:19], v[22:23]
	v_pk_mul_f32 v[22:23], v[16:17], v[4:5] op_sel:[0,0] op_sel_hi:[0,1]
	v_pk_fma_f32 v[4:5], v[16:17], v[4:5], v[22:23] op_sel:[1,1,0] op_sel_hi:[1,0,1] neg_lo:[0,1,0]
	v_pk_mul_f32 v[16:17], v[6:7], v[2:3] op_sel:[0,0] op_sel_hi:[0,1]
	v_pk_fma_f32 v[2:3], v[6:7], v[2:3], v[16:17] op_sel:[1,1,0] op_sel_hi:[1,0,1] neg_lo:[0,1,0]
	s_nop 0
	v_pk_add_f32 v[2:3], v[4:5], v[2:3]
	v_cvt_pk_f16_f32 v4, v18, v19
	v_cvt_pk_f16_f32 v2, v2, -v3
	ds_write_b32 v10, v4
	ds_write_b32 v9, v2

; DI int rev4(int pp) { const unsigned br = __brev((unsigned)pp) >> 18; return (int)(((br & 0x2AAAu) >> 1) | ((br & 0x1555u) << 1)); }
; DI void pw_h(LAS hc* X, const f32x4* spec, int tid) {
;     ...
;     if (tid == 0) { const int pp = rev4(8192); const f32x4 sp = spec[8192]; const hc zh = X[XI(pp)]; const cf z = (cf){(float)zh.x, (float)zh.y};
;         const cf y = (cmul(z, (cf){sp[0], sp[1]}) + cmul((cf){z.x, -z.y}, (cf){sp[2], sp[3]})) * 256.0f; X[XI(pp)] = (hc){(_Float16)y.x, (_Float16)y.y}; }
.LBB0_648:
	v_cmp_eq_u32_e32 vcc, 0, v12
	s_and_saveexec_b64 s[22:23], vcc
	s_cbranch_execz .LBB0_650
	ds_read_b32 v5, v97 offset:8
	v_mov_b32_e32 v0, v132
	v_mov_b32_e32 v1, v133
	v_mov_b32_e32 v2, v134
	v_mov_b32_e32 v3, v135
	s_waitcnt lgkmcnt(0)
	v_cvt_f32_f16_e32 v4, v5
	v_cvt_f32_f16_sdwa v5, v5 dst_sel:DWORD dst_unused:UNUSED_PAD src0_sel:WORD_1
	s_waitcnt vmcnt(0)
	v_pk_mul_f32 v[6:7], v[4:5], v[0:1] op_sel:[0,0] op_sel_hi:[0,1]
	v_pk_fma_f32 v[0:1], v[4:5], v[0:1], v[6:7] op_sel:[1,1,0] op_sel_hi:[1,0,1] neg_lo:[0,1,0]
	v_xor_b32_e32 v5, 0x80000000, v5
	v_pk_mul_f32 v[6:7], v[4:5], v[2:3] op_sel:[0,0] op_sel_hi:[0,1]
	v_pk_fma_f32 v[2:3], v[4:5], v[2:3], v[6:7] op_sel:[1,1,0] op_sel_hi:[1,0,1] neg_lo:[0,1,0]
	v_pk_add_f32 v[0:1], v[0:1], v[2:3]
	s_nop 0
	v_pk_mul_f32 v[0:1], v[0:1], s[90:91] op_sel_hi:[1,0]
	s_nop 0
	v_cvt_pk_f16_f32 v0, v0, v1
	ds_write_b32 v97, v0 offset:8

; DI int rev4(int pp) { const unsigned br = __brev((unsigned)pp) >> 18; return (int)(((br & 0x2AAAu) >> 1) | ((br & 0x1555u) << 1)); }
; DI void pw_h(LAS hc* X, const f32x4* spec, int tid) {
;     ...
;     for (int r = 0; r < 16; ++r) {
;         const int k = tid + NTHR * r; const int pp = rev4(k);
;         const f32x4 sp = spec[k]; const cf P = (cf){sp[0], sp[1]} * 256.0f, Mq = (cf){sp[2], sp[3]} * 256.0f;
;         const hc zh = X[XI(pp)]; const cf z = (cf){(float)zh.x, (float)zh.y};
;         if (k == 0) { const cf y = cmul(z, P) + cmul((cf){z.x, -z.y}, Mq); X[XI(pp)] = (hc){(_Float16)y.x, (_Float16)y.y}; }
;         else { const int pm = rev4(16384 - k); const hc zmh = X[XI(pm)]; const cf zm = (cf){(float)zmh.x, (float)zmh.y};
;             const cf y = cmul(z, P) + cmul((cf){zm.x, -zm.y}, Mq);
;             const cf t = cmul((cf){zm.x, -zm.y}, P) + cmul(z, Mq);
;             X[XI(pp)] = (hc){(_Float16)y.x, (_Float16)y.y}; X[XI(pm)] = (hc){(_Float16)t.x, (_Float16)(-t.y)}; }
;     }
.LBB0_652:
	global_load_dwordx4 v[132:135], v224, s[20:21]
	global_load_dwordx4 v[4:7], v[0:1], off
	v_add_u32_e32 v9, s4, v12
	v_add_u32_e32 v2, 0x2000, v9
	v_bfrev_b32_e32 v2, v2
	v_lshrrev_b32_e32 v3, 19, v2
	v_lshrrev_b32_e32 v2, 17, v2
	v_and_b32_e32 v2, 0x2aaa, v2
	v_and_or_b32 v10, v3, s89, v2
	s_movk_i32 s5, 0xe000
	v_cmp_ne_u32_e64 s[40:41], s5, v9
	v_add_u32_e32 v100, 0x2200, v9
	v_ashrrev_i32_e32 v101, 31, v100
	v_lshl_add_u64 v[100:101], v[100:101], 4, s[20:21]
	global_load_dwordx4 v[104:107], v[100:101], off
	v_add_u32_e32 v100, 0x2400, v9
	v_ashrrev_i32_e32 v101, 31, v100
	v_lshl_add_u64 v[100:101], v[100:101], 4, s[20:21]
	global_load_dwordx4 v[108:111], v[100:101], off
	v_add_u32_e32 v100, 0x2600, v9
	v_ashrrev_i32_e32 v101, 31, v100
	v_lshl_add_u64 v[100:101], v[100:101], 4, s[20:21]
	global_load_dwordx4 v[112:115], v[100:101], off
	v_add_u32_e32 v100, 0x2800, v9
	v_ashrrev_i32_e32 v101, 31, v100
	v_lshl_add_u64 v[100:101], v[100:101], 4, s[20:21]
	global_load_dwordx4 v[116:119], v[100:101], off
	v_add_u32_e32 v100, 0x2a00, v9
	v_ashrrev_i32_e32 v101, 31, v100
	v_lshl_add_u64 v[100:101], v[100:101], 4, s[20:21]
	global_load_dwordx4 v[120:123], v[100:101], off
	v_add_u32_e32 v100, 0x2c00, v9
	v_ashrrev_i32_e32 v101, 31, v100
	v_lshl_add_u64 v[100:101], v[100:101], 4, s[20:21]
	global_load_dwordx4 v[124:127], v[100:101], off
	v_add_u32_e32 v100, 0x2e00, v9
	v_ashrrev_i32_e32 v101, 31, v100
	v_lshl_add_u64 v[100:101], v[100:101], 4, s[20:21]
	global_load_dwordx4 v[128:131], v[100:101], off
	v_add_u32_e32 v100, 0x3000, v9
	v_ashrrev_i32_e32 v101, 31, v100
	v_lshl_add_u64 v[100:101], v[100:101], 4, s[20:21]
	global_load_dword v136, v[100:101], off
	v_add_u32_e32 v100, 0x3200, v9
	v_ashrrev_i32_e32 v101, 31, v100
	v_lshl_add_u64 v[100:101], v[100:101], 4, s[20:21]
	global_load_dword v137, v[100:101], off
	v_add_u32_e32 v100, 0x3400, v9
	v_ashrrev_i32_e32 v101, 31, v100
	v_lshl_add_u64 v[100:101], v[100:101], 4, s[20:21]
	global_load_dword v138, v[100:101], off
	v_add_u32_e32 v100, 0x3600, v9
	v_ashrrev_i32_e32 v101, 31, v100
	v_lshl_add_u64 v[100:101], v[100:101], 4, s[20:21]
	global_load_dword v139, v[100:101], off
	v_add_u32_e32 v100, 0x3800, v9
	v_ashrrev_i32_e32 v101, 31, v100
	v_lshl_add_u64 v[100:101], v[100:101], 4, s[20:21]
	global_load_dword v140, v[100:101], off
	v_add_u32_e32 v100, 0x3a00, v9
	v_ashrrev_i32_e32 v101, 31, v100
	v_lshl_add_u64 v[100:101], v[100:101], 4, s[20:21]
	global_load_dword v141, v[100:101], off
	v_add_u32_e32 v100, 0x3c00, v9
	v_ashrrev_i32_e32 v101, 31, v100
	v_lshl_add_u64 v[100:101], v[100:101], 4, s[20:21]
	global_load_dword v142, v[100:101], off
	v_add_u32_e32 v100, 0x3e00, v9
	v_ashrrev_i32_e32 v101, 31, v100
	v_lshl_add_u64 v[100:101], v[100:101], 4, s[20:21]
	global_load_dword v143, v[100:101], off
	s_waitcnt vmcnt(15)
	v_pk_mul_f32 v[2:3], v[6:7], s[90:91] op_sel_hi:[1,0]
	v_lshl_add_u32 v6, v10, 2, s66
	v_lshrrev_b32_e32 v7, 2, v10
	v_lshrrev_b32_e32 v10, 6, v10
	v_and_b32_e32 v7, 0xffc, v7
	v_and_b32_e32 v10, 0xfc, v10
	v_add3_u32 v10, v6, v7, v10
	ds_read_b32 v7, v10
	v_pk_mul_f32 v[4:5], v[4:5], s[90:91] op_sel_hi:[1,0]
	s_waitcnt lgkmcnt(0)
	v_cvt_f32_f16_e32 v6, v7
	v_cvt_f32_f16_sdwa v7, v7 dst_sel:DWORD dst_unused:UNUSED_PAD src0_sel:WORD_1
	s_and_saveexec_b64 s[22:23], s[40:41]
	s_xor_b64 s[22:23], exec, s[22:23]
	s_cbranch_execz .LBB0_654
	v_add_u32_e32 v11, 0xe00, v8
	v_bfrev_b32_e32 v11, v11
	v_lshrrev_b32_e32 v13, 19, v11
	v_lshrrev_b32_e32 v11, 17, v11
	v_and_b32_e32 v11, 0x2aaa, v11
	v_and_or_b32 v11, v13, s89, v11
	v_lshl_add_u32 v13, v11, 2, s66
	v_lshrrev_b32_e32 v16, 2, v11
	v_lshrrev_b32_e32 v11, 6, v11
	v_and_b32_e32 v16, 0xffc, v16
	v_and_b32_e32 v11, 0xfc, v11
	v_add3_u32 v11, v13, v16, v11
	ds_read_b32 v13, v11
	v_pk_mul_f32 v[18:19], v[6:7], v[4:5] op_sel:[0,0] op_sel_hi:[0,1]
	s_waitcnt lgkmcnt(0)
	v_cvt_f32_f16_e32 v16, v13
	v_cvt_f32_f16_sdwa v17, -v13 dst_sel:DWORD dst_unused:UNUSED_PAD src0_sel:WORD_1
	v_pk_mul_f32 v[22:23], v[16:17], v[2:3] op_sel:[0,0] op_sel_hi:[0,1]
	v_pk_fma_f32 v[18:19], v[6:7], v[4:5], v[18:19] op_sel:[1,1,0] op_sel_hi:[1,0,1] neg_lo:[0,1,0]
	v_pk_fma_f32 v[22:23], v[16:17], v[2:3], v[22:23] op_sel:[1,1,0] op_sel_hi:[1,0,1] neg_lo:[0,1,0]
	v_pk_add_f32 v[18:19], v[18:19], v[22:23]
	v_pk_mul_f32 v[22:23], v[16:17], v[4:5] op_sel:[0,0] op_sel_hi:[0,1]
	v_pk_fma_f32 v[4:5], v[16:17], v[4:5], v[22:23] op_sel:[1,1,0] op_sel_hi:[1,0,1] neg_lo:[0,1,0]
	v_pk_mul_f32 v[16:17], v[6:7], v[2:3] op_sel:[0,0] op_sel_hi:[0,1]
	v_pk_fma_f32 v[2:3], v[6:7], v[2:3], v[16:17] op_sel:[1,1,0] op_sel_hi:[1,0,1] neg_lo:[0,1,0]
	s_nop 0
	v_pk_add_f32 v[2:3], v[4:5], v[2:3]
	v_cvt_pk_f16_f32 v4, v18, v19
	v_cvt_pk_f16_f32 v2, v2, -v3
	ds_write_b32 v10, v4
	ds_write_b32 v11, v2

; DI int rev4(int pp) { const unsigned br = __brev((unsigned)pp) >> 18; return (int)(((br & 0x2AAAu) >> 1) | ((br & 0x1555u) << 1)); }
; DI void pw_h(LAS hc* X, const f32x4* spec, int tid) {
;     ...
;     for (int r = 0; r < 16; ++r) {
;         const int k = tid + NTHR * r; const int pp = rev4(k);
;         const f32x4 sp = spec[k]; const cf P = (cf){sp[0], sp[1]} * 256.0f, Mq = (cf){sp[2], sp[3]} * 256.0f;
;         const hc zh = X[XI(pp)]; const cf z = (cf){(float)zh.x, (float)zh.y};
;         if (k == 0) { const cf y = cmul(z, P) + cmul((cf){z.x, -z.y}, Mq); X[XI(pp)] = (hc){(_Float16)y.x, (_Float16)y.y}; }
;         else { const int pm = rev4(16384 - k); const hc zmh = X[XI(pm)]; const cf zm = (cf){(float)zmh.x, (float)zmh.y};
;             const cf y = cmul(z, P) + cmul((cf){zm.x, -zm.y}, Mq);
;             const cf t = cmul((cf){zm.x, -zm.y}, P) + cmul(z, Mq);
;             X[XI(pp)] = (hc){(_Float16)y.x, (_Float16)y.y}; X[XI(pm)] = (hc){(_Float16)t.x, (_Float16)(-t.y)}; }
;     }
.LBB0_656:
	s_or_b64 exec, exec, s[22:23]
	v_add_u32_e32 v2, 0x2200, v9
	v_bfrev_b32_e32 v3, v2
	v_lshrrev_b32_e32 v4, 19, v3
	v_lshrrev_b32_e32 v3, 17, v3
	v_and_b32_e32 v3, 0x2aaa, v3
	v_and_or_b32 v10, v4, s89, v3
	s_movk_i32 s5, 0xde00
	v_cmp_ne_u32_e64 s[40:41], s5, v9
	s_waitcnt vmcnt(14)
	v_mov_b32_e32 v4, v104
	v_mov_b32_e32 v5, v105
	v_mov_b32_e32 v6, v106
	v_mov_b32_e32 v7, v107
	v_pk_mul_f32 v[2:3], v[6:7], s[90:91] op_sel_hi:[1,0]
	v_lshl_add_u32 v6, v10, 2, s66
	v_lshrrev_b32_e32 v7, 2, v10
	v_lshrrev_b32_e32 v10, 6, v10
	v_and_b32_e32 v7, 0xffc, v7
	v_and_b32_e32 v10, 0xfc, v10
	v_add3_u32 v10, v6, v7, v10
	ds_read_b32 v7, v10
	v_pk_mul_f32 v[4:5], v[4:5], s[90:91] op_sel_hi:[1,0]
	s_waitcnt lgkmcnt(0)
	v_cvt_f32_f16_e32 v6, v7
	v_cvt_f32_f16_sdwa v7, v7 dst_sel:DWORD dst_unused:UNUSED_PAD src0_sel:WORD_1
	s_and_saveexec_b64 s[22:23], s[40:41]
	s_xor_b64 s[22:23], exec, s[22:23]
	s_cbranch_execz .LBB0_658
	v_add_u32_e32 v11, 0xc00, v8
	v_bfrev_b32_e32 v11, v11
	v_lshrrev_b32_e32 v13, 19, v11
	v_lshrrev_b32_e32 v11, 17, v11
	v_and_b32_e32 v11, 0x2aaa, v11
	v_and_or_b32 v11, v13, s89, v11
	v_lshl_add_u32 v13, v11, 2, s66
	v_lshrrev_b32_e32 v16, 2, v11
	v_lshrrev_b32_e32 v11, 6, v11
	v_and_b32_e32 v16, 0xffc, v16
	v_and_b32_e32 v11, 0xfc, v11
	v_add3_u32 v11, v13, v16, v11
	ds_read_b32 v13, v11
	v_pk_mul_f32 v[18:19], v[6:7], v[4:5] op_sel:[0,0] op_sel_hi:[0,1]
	s_waitcnt lgkmcnt(0)
	v_cvt_f32_f16_e32 v16, v13
	v_cvt_f32_f16_sdwa v17, -v13 dst_sel:DWORD dst_unused:UNUSED_PAD src0_sel:WORD_1
	v_pk_mul_f32 v[22:23], v[16:17], v[2:3] op_sel:[0,0] op_sel_hi:[0,1]
	v_pk_fma_f32 v[18:19], v[6:7], v[4:5], v[18:19] op_sel:[1,1,0] op_sel_hi:[1,0,1] neg_lo:[0,1,0]
	v_pk_fma_f32 v[22:23], v[16:17], v[2:3], v[22:23] op_sel:[1,1,0] op_sel_hi:[1,0,1] neg_lo:[0,1,0]
	v_pk_add_f32 v[18:19], v[18:19], v[22:23]
	v_pk_mul_f32 v[22:23], v[16:17], v[4:5] op_sel:[0,0] op_sel_hi:[0,1]
	v_pk_fma_f32 v[4:5], v[16:17], v[4:5], v[22:23] op_sel:[1,1,0] op_sel_hi:[1,0,1] neg_lo:[0,1,0]
	v_pk_mul_f32 v[16:17], v[6:7], v[2:3] op_sel:[0,0] op_sel_hi:[0,1]
	v_pk_fma_f32 v[2:3], v[6:7], v[2:3], v[16:17] op_sel:[1,1,0] op_sel_hi:[1,0,1] neg_lo:[0,1,0]
	s_nop 0
	v_pk_add_f32 v[2:3], v[4:5], v[2:3]
	v_cvt_pk_f16_f32 v4, v18, v19
	v_cvt_pk_f16_f32 v2, v2, -v3
	ds_write_b32 v10, v4
	ds_write_b32 v11, v2

; DI int rev4(int pp) { const unsigned br = __brev((unsigned)pp) >> 18; return (int)(((br & 0x2AAAu) >> 1) | ((br & 0x1555u) << 1)); }
; DI void pw_h(LAS hc* X, const f32x4* spec, int tid) {
;     ...
;     if (tid == 0) { const int pp = rev4(8192); const f32x4 sp = spec[8192]; const hc zh = X[XI(pp)]; const cf z = (cf){(float)zh.x, (float)zh.y};
;         const cf y = (cmul(z, (cf){sp[0], sp[1]}) + cmul((cf){z.x, -z.y}, (cf){sp[2], sp[3]})) * 256.0f; X[XI(pp)] = (hc){(_Float16)y.x, (_Float16)y.y}; }
.LBB0_660:
	s_or_b64 exec, exec, s[22:23]
	v_add_u32_e32 v2, 0x2400, v9
	v_bfrev_b32_e32 v3, v2
	v_lshrrev_b32_e32 v4, 19, v3
	v_lshrrev_b32_e32 v3, 17, v3
	v_and_b32_e32 v3, 0x2aaa, v3
	v_and_or_b32 v10, v4, s89, v3
	s_movk_i32 s5, 0xdc00
	v_cmp_ne_u32_e64 s[40:41], s5, v9
	s_waitcnt vmcnt(13)
	v_mov_b32_e32 v4, v108
	v_mov_b32_e32 v5, v109
	v_mov_b32_e32 v6, v110
	v_mov_b32_e32 v7, v111
	v_pk_mul_f32 v[2:3], v[6:7], s[90:91] op_sel_hi:[1,0]
	v_lshl_add_u32 v6, v10, 2, s66
	v_lshrrev_b32_e32 v7, 2, v10
	v_lshrrev_b32_e32 v10, 6, v10
	v_and_b32_e32 v7, 0xffc, v7
	v_and_b32_e32 v10, 0xfc, v10
	v_add3_u32 v10, v6, v7, v10
	ds_read_b32 v7, v10
	v_pk_mul_f32 v[4:5], v[4:5], s[90:91] op_sel_hi:[1,0]
	s_waitcnt lgkmcnt(0)
	v_cvt_f32_f16_e32 v6, v7
	v_cvt_f32_f16_sdwa v7, v7 dst_sel:DWORD dst_unused:UNUSED_PAD src0_sel:WORD_1
	s_and_saveexec_b64 s[22:23], s[40:41]
	s_xor_b64 s[22:23], exec, s[22:23]
	s_cbranch_execz .LBB0_662
	v_add_u32_e32 v11, 0xa00, v8
	v_bfrev_b32_e32 v11, v11
	v_lshrrev_b32_e32 v13, 19, v11
	v_lshrrev_b32_e32 v11, 17, v11
	v_and_b32_e32 v11, 0x2aaa, v11
	v_and_or_b32 v11, v13, s89, v11
	v_lshl_add_u32 v13, v11, 2, s66
	v_lshrrev_b32_e32 v16, 2, v11
	v_lshrrev_b32_e32 v11, 6, v11
	v_and_b32_e32 v16, 0xffc, v16
	v_and_b32_e32 v11, 0xfc, v11
	v_add3_u32 v11, v13, v16, v11
	ds_read_b32 v13, v11
	v_pk_mul_f32 v[18:19], v[6:7], v[4:5] op_sel:[0,0] op_sel_hi:[0,1]
	s_waitcnt lgkmcnt(0)
	v_cvt_f32_f16_e32 v16, v13
	v_cvt_f32_f16_sdwa v17, -v13 dst_sel:DWORD dst_unused:UNUSED_PAD src0_sel:WORD_1
	v_pk_mul_f32 v[22:23], v[16:17], v[2:3] op_sel:[0,0] op_sel_hi:[0,1]
	v_pk_fma_f32 v[18:19], v[6:7], v[4:5], v[18:19] op_sel:[1,1,0] op_sel_hi:[1,0,1] neg_lo:[0,1,0]
	v_pk_fma_f32 v[22:23], v[16:17], v[2:3], v[22:23] op_sel:[1,1,0] op_sel_hi:[1,0,1] neg_lo:[0,1,0]
	v_pk_add_f32 v[18:19], v[18:19], v[22:23]
	v_pk_mul_f32 v[22:23], v[16:17], v[4:5] op_sel:[0,0] op_sel_hi:[0,1]
	v_pk_fma_f32 v[4:5], v[16:17], v[4:5], v[22:23] op_sel:[1,1,0] op_sel_hi:[1,0,1] neg_lo:[0,1,0]
	v_pk_mul_f32 v[16:17], v[6:7], v[2:3] op_sel:[0,0] op_sel_hi:[0,1]
	v_pk_fma_f32 v[2:3], v[6:7], v[2:3], v[16:17] op_sel:[1,1,0] op_sel_hi:[1,0,1] neg_lo:[0,1,0]
	s_nop 0
	v_pk_add_f32 v[2:3], v[4:5], v[2:3]
	v_cvt_pk_f16_f32 v4, v18, v19
	v_cvt_pk_f16_f32 v2, v2, -v3
	ds_write_b32 v10, v4
	ds_write_b32 v11, v2

; DI int rev4(int pp) { const unsigned br = __brev((unsigned)pp) >> 18; return (int)(((br & 0x2AAAu) >> 1) | ((br & 0x1555u) << 1)); }
; DI void pw_h(LAS hc* X, const f32x4* spec, int tid) {
;     ...
;     for (int r = 0; r < 16; ++r) {
;         const int k = tid + NTHR * r; const int pp = rev4(k);
;         const f32x4 sp = spec[k]; const cf P = (cf){sp[0], sp[1]} * 256.0f, Mq = (cf){sp[2], sp[3]} * 256.0f;
;         const hc zh = X[XI(pp)]; const cf z = (cf){(float)zh.x, (float)zh.y};
;         if (k == 0) { const cf y = cmul(z, P) + cmul((cf){z.x, -z.y}, Mq); X[XI(pp)] = (hc){(_Float16)y.x, (_Float16)y.y}; }
;         else { const int pm = rev4(16384 - k); const hc zmh = X[XI(pm)]; const cf zm = (cf){(float)zmh.x, (float)zmh.y};
;             const cf y = cmul(z, P) + cmul((cf){zm.x, -zm.y}, Mq);
;             const cf t = cmul((cf){zm.x, -zm.y}, P) + cmul(z, Mq);
;             X[XI(pp)] = (hc){(_Float16)y.x, (_Float16)y.y}; X[XI(pm)] = (hc){(_Float16)t.x, (_Float16)(-t.y)}; }
;     }
.LBB0_664:
	s_or_b64 exec, exec, s[22:23]
	v_add_u32_e32 v2, 0x2600, v9
	v_bfrev_b32_e32 v3, v2
	v_lshrrev_b32_e32 v4, 19, v3
	v_lshrrev_b32_e32 v3, 17, v3
	v_and_b32_e32 v3, 0x2aaa, v3
	v_and_or_b32 v10, v4, s89, v3
	s_movk_i32 s5, 0xda00
	v_cmp_ne_u32_e64 s[40:41], s5, v9
	s_waitcnt vmcnt(12)
	v_mov_b32_e32 v4, v112
	v_mov_b32_e32 v5, v113
	v_mov_b32_e32 v6, v114
	v_mov_b32_e32 v7, v115
	v_pk_mul_f32 v[2:3], v[6:7], s[90:91] op_sel_hi:[1,0]
	v_lshl_add_u32 v6, v10, 2, s66
	v_lshrrev_b32_e32 v7, 2, v10
	v_lshrrev_b32_e32 v10, 6, v10
	v_and_b32_e32 v7, 0xffc, v7
	v_and_b32_e32 v10, 0xfc, v10
	v_add3_u32 v10, v6, v7, v10
	ds_read_b32 v7, v10
	v_pk_mul_f32 v[4:5], v[4:5], s[90:91] op_sel_hi:[1,0]
	s_waitcnt lgkmcnt(0)
	v_cvt_f32_f16_e32 v6, v7
	v_cvt_f32_f16_sdwa v7, v7 dst_sel:DWORD dst_unused:UNUSED_PAD src0_sel:WORD_1
	s_and_saveexec_b64 s[22:23], s[40:41]
	s_xor_b64 s[22:23], exec, s[22:23]
	s_cbranch_execz .LBB0_666
	v_add_u32_e32 v11, 0x800, v8
	v_bfrev_b32_e32 v11, v11
	v_lshrrev_b32_e32 v13, 19, v11
	v_lshrrev_b32_e32 v11, 17, v11
	v_and_b32_e32 v11, 0x2aaa, v11
	v_and_or_b32 v11, v13, s89, v11
	v_lshl_add_u32 v13, v11, 2, s66
	v_lshrrev_b32_e32 v16, 2, v11
	v_lshrrev_b32_e32 v11, 6, v11
	v_and_b32_e32 v16, 0xffc, v16
	v_and_b32_e32 v11, 0xfc, v11
	v_add3_u32 v11, v13, v16, v11
	ds_read_b32 v13, v11
	v_pk_mul_f32 v[18:19], v[6:7], v[4:5] op_sel:[0,0] op_sel_hi:[0,1]
	s_waitcnt lgkmcnt(0)
	v_cvt_f32_f16_e32 v16, v13
	v_cvt_f32_f16_sdwa v17, -v13 dst_sel:DWORD dst_unused:UNUSED_PAD src0_sel:WORD_1
	v_pk_mul_f32 v[22:23], v[16:17], v[2:3] op_sel:[0,0] op_sel_hi:[0,1]
	v_pk_fma_f32 v[18:19], v[6:7], v[4:5], v[18:19] op_sel:[1,1,0] op_sel_hi:[1,0,1] neg_lo:[0,1,0]
	v_pk_fma_f32 v[22:23], v[16:17], v[2:3], v[22:23] op_sel:[1,1,0] op_sel_hi:[1,0,1] neg_lo:[0,1,0]
	v_pk_add_f32 v[18:19], v[18:19], v[22:23]
	v_pk_mul_f32 v[22:23], v[16:17], v[4:5] op_sel:[0,0] op_sel_hi:[0,1]
	v_pk_fma_f32 v[4:5], v[16:17], v[4:5], v[22:23] op_sel:[1,1,0] op_sel_hi:[1,0,1] neg_lo:[0,1,0]
	v_pk_mul_f32 v[16:17], v[6:7], v[2:3] op_sel:[0,0] op_sel_hi:[0,1]
	v_pk_fma_f32 v[2:3], v[6:7], v[2:3], v[16:17] op_sel:[1,1,0] op_sel_hi:[1,0,1] neg_lo:[0,1,0]
	s_nop 0
	v_pk_add_f32 v[2:3], v[4:5], v[2:3]
	v_cvt_pk_f16_f32 v4, v18, v19
	v_cvt_pk_f16_f32 v2, v2, -v3
	ds_write_b32 v10, v4
	ds_write_b32 v11, v2

; DI int rev4(int pp) { const unsigned br = __brev((unsigned)pp) >> 18; return (int)(((br & 0x2AAAu) >> 1) | ((br & 0x1555u) << 1)); }
; DI void pw_h(LAS hc* X, const f32x4* spec, int tid) {
;     ...
;     for (int r = 0; r < 16; ++r) {
;         const int k = tid + NTHR * r; const int pp = rev4(k);
;         const f32x4 sp = spec[k]; const cf P = (cf){sp[0], sp[1]} * 256.0f, Mq = (cf){sp[2], sp[3]} * 256.0f;
;         const hc zh = X[XI(pp)]; const cf z = (cf){(float)zh.x, (float)zh.y};
;         if (k == 0) { const cf y = cmul(z, P) + cmul((cf){z.x, -z.y}, Mq); X[XI(pp)] = (hc){(_Float16)y.x, (_Float16)y.y}; }
;         else { const int pm = rev4(16384 - k); const hc zmh = X[XI(pm)]; const cf zm = (cf){(float)zmh.x, (float)zmh.y};
;             const cf y = cmul(z, P) + cmul((cf){zm.x, -zm.y}, Mq);
;             const cf t = cmul((cf){zm.x, -zm.y}, P) + cmul(z, Mq);
;             X[XI(pp)] = (hc){(_Float16)y.x, (_Float16)y.y}; X[XI(pm)] = (hc){(_Float16)t.x, (_Float16)(-t.y)}; }
;     }
.LBB0_668:
	s_or_b64 exec, exec, s[22:23]
	v_add_u32_e32 v2, 0x2800, v9
	v_bfrev_b32_e32 v3, v2
	v_lshrrev_b32_e32 v4, 19, v3
	v_lshrrev_b32_e32 v3, 17, v3
	v_and_b32_e32 v3, 0x2aaa, v3
	v_and_or_b32 v10, v4, s89, v3
	s_movk_i32 s5, 0xd800
	v_cmp_ne_u32_e64 s[40:41], s5, v9
	s_waitcnt vmcnt(11)
	v_mov_b32_e32 v4, v116
	v_mov_b32_e32 v5, v117
	v_mov_b32_e32 v6, v118
	v_mov_b32_e32 v7, v119
	v_pk_mul_f32 v[2:3], v[6:7], s[90:91] op_sel_hi:[1,0]
	v_lshl_add_u32 v6, v10, 2, s66
	v_lshrrev_b32_e32 v7, 2, v10
	v_lshrrev_b32_e32 v10, 6, v10
	v_and_b32_e32 v7, 0xffc, v7
	v_and_b32_e32 v10, 0xfc, v10
	v_add3_u32 v10, v6, v7, v10
	ds_read_b32 v7, v10
	v_pk_mul_f32 v[4:5], v[4:5], s[90:91] op_sel_hi:[1,0]
	s_waitcnt lgkmcnt(0)
	v_cvt_f32_f16_e32 v6, v7
	v_cvt_f32_f16_sdwa v7, v7 dst_sel:DWORD dst_unused:UNUSED_PAD src0_sel:WORD_1
	s_and_saveexec_b64 s[22:23], s[40:41]
	s_xor_b64 s[22:23], exec, s[22:23]
	s_cbranch_execz .LBB0_670
	v_add_u32_e32 v11, 0x600, v8
	v_bfrev_b32_e32 v11, v11
	v_lshrrev_b32_e32 v13, 19, v11
	v_lshrrev_b32_e32 v11, 17, v11
	v_and_b32_e32 v11, 0x2aaa, v11
	v_and_or_b32 v11, v13, s89, v11
	v_lshl_add_u32 v13, v11, 2, s66
	v_lshrrev_b32_e32 v16, 2, v11
	v_lshrrev_b32_e32 v11, 6, v11
	v_and_b32_e32 v16, 0xffc, v16
	v_and_b32_e32 v11, 0xfc, v11
	v_add3_u32 v11, v13, v16, v11
	ds_read_b32 v13, v11
	v_pk_mul_f32 v[18:19], v[6:7], v[4:5] op_sel:[0,0] op_sel_hi:[0,1]
	s_waitcnt lgkmcnt(0)
	v_cvt_f32_f16_e32 v16, v13
	v_cvt_f32_f16_sdwa v17, -v13 dst_sel:DWORD dst_unused:UNUSED_PAD src0_sel:WORD_1
	v_pk_mul_f32 v[22:23], v[16:17], v[2:3] op_sel:[0,0] op_sel_hi:[0,1]
	v_pk_fma_f32 v[18:19], v[6:7], v[4:5], v[18:19] op_sel:[1,1,0] op_sel_hi:[1,0,1] neg_lo:[0,1,0]
	v_pk_fma_f32 v[22:23], v[16:17], v[2:3], v[22:23] op_sel:[1,1,0] op_sel_hi:[1,0,1] neg_lo:[0,1,0]
	v_pk_add_f32 v[18:19], v[18:19], v[22:23]
	v_pk_mul_f32 v[22:23], v[16:17], v[4:5] op_sel:[0,0] op_sel_hi:[0,1]
	v_pk_fma_f32 v[4:5], v[16:17], v[4:5], v[22:23] op_sel:[1,1,0] op_sel_hi:[1,0,1] neg_lo:[0,1,0]
	v_pk_mul_f32 v[16:17], v[6:7], v[2:3] op_sel:[0,0] op_sel_hi:[0,1]
	v_pk_fma_f32 v[2:3], v[6:7], v[2:3], v[16:17] op_sel:[1,1,0] op_sel_hi:[1,0,1] neg_lo:[0,1,0]
	s_nop 0
	v_pk_add_f32 v[2:3], v[4:5], v[2:3]
	v_cvt_pk_f16_f32 v4, v18, v19
	v_cvt_pk_f16_f32 v2, v2, -v3
	ds_write_b32 v10, v4
	ds_write_b32 v11, v2

; DI int rev4(int pp) { const unsigned br = __brev((unsigned)pp) >> 18; return (int)(((br & 0x2AAAu) >> 1) | ((br & 0x1555u) << 1)); }
; DI void pw_h(LAS hc* X, const f32x4* spec, int tid) {
;     ...
;     for (int r = 0; r < 16; ++r) {
;         const int k = tid + NTHR * r; const int pp = rev4(k);
;         const f32x4 sp = spec[k]; const cf P = (cf){sp[0], sp[1]} * 256.0f, Mq = (cf){sp[2], sp[3]} * 256.0f;
;         const hc zh = X[XI(pp)]; const cf z = (cf){(float)zh.x, (float)zh.y};
;         if (k == 0) { const cf y = cmul(z, P) + cmul((cf){z.x, -z.y}, Mq); X[XI(pp)] = (hc){(_Float16)y.x, (_Float16)y.y}; }
;         else { const int pm = rev4(16384 - k); const hc zmh = X[XI(pm)]; const cf zm = (cf){(float)zmh.x, (float)zmh.y};
;             const cf y = cmul(z, P) + cmul((cf){zm.x, -zm.y}, Mq);
;             const cf t = cmul((cf){zm.x, -zm.y}, P) + cmul(z, Mq);
;             X[XI(pp)] = (hc){(_Float16)y.x, (_Float16)y.y}; X[XI(pm)] = (hc){(_Float16)t.x, (_Float16)(-t.y)}; }
;     }
.LBB0_672:
	s_or_b64 exec, exec, s[22:23]
	v_add_u32_e32 v2, 0x2a00, v9
	v_bfrev_b32_e32 v3, v2
	v_lshrrev_b32_e32 v4, 19, v3
	v_lshrrev_b32_e32 v3, 17, v3
	v_and_b32_e32 v3, 0x2aaa, v3
	v_and_or_b32 v10, v4, s89, v3
	s_movk_i32 s5, 0xd600
	v_cmp_ne_u32_e64 s[40:41], s5, v9
	s_waitcnt vmcnt(10)
	v_mov_b32_e32 v4, v120
	v_mov_b32_e32 v5, v121
	v_mov_b32_e32 v6, v122
	v_mov_b32_e32 v7, v123
	v_pk_mul_f32 v[2:3], v[6:7], s[90:91] op_sel_hi:[1,0]
	v_lshl_add_u32 v6, v10, 2, s66
	v_lshrrev_b32_e32 v7, 2, v10
	v_lshrrev_b32_e32 v10, 6, v10
	v_and_b32_e32 v7, 0xffc, v7
	v_and_b32_e32 v10, 0xfc, v10
	v_add3_u32 v10, v6, v7, v10
	ds_read_b32 v7, v10
	v_pk_mul_f32 v[4:5], v[4:5], s[90:91] op_sel_hi:[1,0]
	s_waitcnt lgkmcnt(0)
	v_cvt_f32_f16_e32 v6, v7
	v_cvt_f32_f16_sdwa v7, v7 dst_sel:DWORD dst_unused:UNUSED_PAD src0_sel:WORD_1
	s_and_saveexec_b64 s[22:23], s[40:41]
	s_xor_b64 s[22:23], exec, s[22:23]
	s_cbranch_execz .LBB0_674
	v_add_u32_e32 v11, 0x400, v8
	v_bfrev_b32_e32 v11, v11
	v_lshrrev_b32_e32 v13, 19, v11
	v_lshrrev_b32_e32 v11, 17, v11
	v_and_b32_e32 v11, 0x2aaa, v11
	v_and_or_b32 v11, v13, s89, v11
	v_lshl_add_u32 v13, v11, 2, s66
	v_lshrrev_b32_e32 v16, 2, v11
	v_lshrrev_b32_e32 v11, 6, v11
	v_and_b32_e32 v16, 0xffc, v16
	v_and_b32_e32 v11, 0xfc, v11
	v_add3_u32 v11, v13, v16, v11
	ds_read_b32 v13, v11
	v_pk_mul_f32 v[18:19], v[6:7], v[4:5] op_sel:[0,0] op_sel_hi:[0,1]
	s_waitcnt lgkmcnt(0)
	v_cvt_f32_f16_e32 v16, v13
	v_cvt_f32_f16_sdwa v17, -v13 dst_sel:DWORD dst_unused:UNUSED_PAD src0_sel:WORD_1
	v_pk_mul_f32 v[22:23], v[16:17], v[2:3] op_sel:[0,0] op_sel_hi:[0,1]
	v_pk_fma_f32 v[18:19], v[6:7], v[4:5], v[18:19] op_sel:[1,1,0] op_sel_hi:[1,0,1] neg_lo:[0,1,0]
	v_pk_fma_f32 v[22:23], v[16:17], v[2:3], v[22:23] op_sel:[1,1,0] op_sel_hi:[1,0,1] neg_lo:[0,1,0]
	v_pk_add_f32 v[18:19], v[18:19], v[22:23]
	v_pk_mul_f32 v[22:23], v[16:17], v[4:5] op_sel:[0,0] op_sel_hi:[0,1]
	v_pk_fma_f32 v[4:5], v[16:17], v[4:5], v[22:23] op_sel:[1,1,0] op_sel_hi:[1,0,1] neg_lo:[0,1,0]
	v_pk_mul_f32 v[16:17], v[6:7], v[2:3] op_sel:[0,0] op_sel_hi:[0,1]
	v_pk_fma_f32 v[2:3], v[6:7], v[2:3], v[16:17] op_sel:[1,1,0] op_sel_hi:[1,0,1] neg_lo:[0,1,0]
	s_nop 0
	v_pk_add_f32 v[2:3], v[4:5], v[2:3]
	v_cvt_pk_f16_f32 v4, v18, v19
	v_cvt_pk_f16_f32 v2, v2, -v3
	ds_write_b32 v10, v4
	ds_write_b32 v11, v2

; DI int rev4(int pp) { const unsigned br = __brev((unsigned)pp) >> 18; return (int)(((br & 0x2AAAu) >> 1) | ((br & 0x1555u) << 1)); }
; DI void pw_h(LAS hc* X, const f32x4* spec, int tid) {
;     ...
;     for (int r = 0; r < 16; ++r) {
;         const int k = tid + NTHR * r; const int pp = rev4(k);
;         const f32x4 sp = spec[k]; const cf P = (cf){sp[0], sp[1]} * 256.0f, Mq = (cf){sp[2], sp[3]} * 256.0f;
;         const hc zh = X[XI(pp)]; const cf z = (cf){(float)zh.x, (float)zh.y};
;         if (k == 0) { const cf y = cmul(z, P) + cmul((cf){z.x, -z.y}, Mq); X[XI(pp)] = (hc){(_Float16)y.x, (_Float16)y.y}; }
;         else { const int pm = rev4(16384 - k); const hc zmh = X[XI(pm)]; const cf zm = (cf){(float)zmh.x, (float)zmh.y};
;             const cf y = cmul(z, P) + cmul((cf){zm.x, -zm.y}, Mq);
;             const cf t = cmul((cf){zm.x, -zm.y}, P) + cmul(z, Mq);
;             X[XI(pp)] = (hc){(_Float16)y.x, (_Float16)y.y}; X[XI(pm)] = (hc){(_Float16)t.x, (_Float16)(-t.y)}; }
;     }
.LBB0_676:
	s_or_b64 exec, exec, s[22:23]
	v_add_u32_e32 v2, 0x2c00, v9
	v_bfrev_b32_e32 v3, v2
	v_lshrrev_b32_e32 v4, 19, v3
	v_lshrrev_b32_e32 v3, 17, v3
	v_and_b32_e32 v3, 0x2aaa, v3
	v_and_or_b32 v10, v4, s89, v3
	v_cmp_ne_u32_e64 s[40:41], s96, v9
	s_waitcnt vmcnt(9)
	v_mov_b32_e32 v4, v124
	v_mov_b32_e32 v5, v125
	v_mov_b32_e32 v6, v126
	v_mov_b32_e32 v7, v127
	v_pk_mul_f32 v[2:3], v[6:7], s[90:91] op_sel_hi:[1,0]
	v_lshl_add_u32 v6, v10, 2, s66
	v_lshrrev_b32_e32 v7, 2, v10
	v_lshrrev_b32_e32 v10, 6, v10
	v_and_b32_e32 v7, 0xffc, v7
	v_and_b32_e32 v10, 0xfc, v10
	v_add3_u32 v10, v6, v7, v10
	ds_read_b32 v7, v10
	v_pk_mul_f32 v[4:5], v[4:5], s[90:91] op_sel_hi:[1,0]
	s_waitcnt lgkmcnt(0)
	v_cvt_f32_f16_e32 v6, v7
	v_cvt_f32_f16_sdwa v7, v7 dst_sel:DWORD dst_unused:UNUSED_PAD src0_sel:WORD_1
	s_and_saveexec_b64 s[22:23], s[40:41]
	s_xor_b64 s[22:23], exec, s[22:23]
	s_cbranch_execz .LBB0_678
	v_add_u32_e32 v11, 0x200, v8
	v_bfrev_b32_e32 v11, v11
	v_lshrrev_b32_e32 v13, 19, v11
	v_lshrrev_b32_e32 v11, 17, v11
	v_and_b32_e32 v11, 0x2aaa, v11
	v_and_or_b32 v11, v13, s89, v11
	v_lshl_add_u32 v13, v11, 2, s66
	v_lshrrev_b32_e32 v16, 2, v11
	v_lshrrev_b32_e32 v11, 6, v11
	v_and_b32_e32 v16, 0xffc, v16
	v_and_b32_e32 v11, 0xfc, v11
	v_add3_u32 v11, v13, v16, v11
	ds_read_b32 v13, v11
	v_pk_mul_f32 v[18:19], v[6:7], v[4:5] op_sel:[0,0] op_sel_hi:[0,1]
	s_waitcnt lgkmcnt(0)
	v_cvt_f32_f16_e32 v16, v13
	v_cvt_f32_f16_sdwa v17, -v13 dst_sel:DWORD dst_unused:UNUSED_PAD src0_sel:WORD_1
	v_pk_mul_f32 v[22:23], v[16:17], v[2:3] op_sel:[0,0] op_sel_hi:[0,1]
	v_pk_fma_f32 v[18:19], v[6:7], v[4:5], v[18:19] op_sel:[1,1,0] op_sel_hi:[1,0,1] neg_lo:[0,1,0]
	v_pk_fma_f32 v[22:23], v[16:17], v[2:3], v[22:23] op_sel:[1,1,0] op_sel_hi:[1,0,1] neg_lo:[0,1,0]
	v_pk_add_f32 v[18:19], v[18:19], v[22:23]
	v_pk_mul_f32 v[22:23], v[16:17], v[4:5] op_sel:[0,0] op_sel_hi:[0,1]
	v_pk_fma_f32 v[4:5], v[16:17], v[4:5], v[22:23] op_sel:[1,1,0] op_sel_hi:[1,0,1] neg_lo:[0,1,0]
	v_pk_mul_f32 v[16:17], v[6:7], v[2:3] op_sel:[0,0] op_sel_hi:[0,1]
	v_pk_fma_f32 v[2:3], v[6:7], v[2:3], v[16:17] op_sel:[1,1,0] op_sel_hi:[1,0,1] neg_lo:[0,1,0]
	s_nop 0
	v_pk_add_f32 v[2:3], v[4:5], v[2:3]
	v_cvt_pk_f16_f32 v4, v18, v19
	v_cvt_pk_f16_f32 v2, v2, -v3
	ds_write_b32 v10, v4
	ds_write_b32 v11, v2

; DI int rev4(int pp) { const unsigned br = __brev((unsigned)pp) >> 18; return (int)(((br & 0x2AAAu) >> 1) | ((br & 0x1555u) << 1)); }
; DI void pw_h(LAS hc* X, const f32x4* spec, int tid) {
;     ...
;     for (int r = 0; r < 16; ++r) {
;         const int k = tid + NTHR * r; const int pp = rev4(k);
;         const f32x4 sp = spec[k]; const cf P = (cf){sp[0], sp[1]} * 256.0f, Mq = (cf){sp[2], sp[3]} * 256.0f;
;         const hc zh = X[XI(pp)]; const cf z = (cf){(float)zh.x, (float)zh.y};
;         if (k == 0) { const cf y = cmul(z, P) + cmul((cf){z.x, -z.y}, Mq); X[XI(pp)] = (hc){(_Float16)y.x, (_Float16)y.y}; }
;         else { const int pm = rev4(16384 - k); const hc zmh = X[XI(pm)]; const cf zm = (cf){(float)zmh.x, (float)zmh.y};
;             const cf y = cmul(z, P) + cmul((cf){zm.x, -zm.y}, Mq);
;             const cf t = cmul((cf){zm.x, -zm.y}, P) + cmul(z, Mq);
;             X[XI(pp)] = (hc){(_Float16)y.x, (_Float16)y.y}; X[XI(pm)] = (hc){(_Float16)t.x, (_Float16)(-t.y)}; }
;     }
.LBB0_680:
	s_or_b64 exec, exec, s[22:23]
	v_add_u32_e32 v2, 0x2e00, v9
	v_bfrev_b32_e32 v3, v2
	v_lshrrev_b32_e32 v4, 19, v3
	v_lshrrev_b32_e32 v3, 17, v3
	v_and_b32_e32 v3, 0x2aaa, v3
	v_and_or_b32 v10, v4, s89, v3
	v_cmp_ne_u32_e64 s[40:41], s84, v9
	s_waitcnt vmcnt(8)
	v_mov_b32_e32 v4, v128
	v_mov_b32_e32 v5, v129
	v_mov_b32_e32 v6, v130
	v_mov_b32_e32 v7, v131
	v_pk_mul_f32 v[2:3], v[6:7], s[90:91] op_sel_hi:[1,0]
	v_lshl_add_u32 v6, v10, 2, s66
	v_lshrrev_b32_e32 v7, 2, v10
	v_lshrrev_b32_e32 v10, 6, v10
	v_and_b32_e32 v7, 0xffc, v7
	v_and_b32_e32 v10, 0xfc, v10
	v_add3_u32 v10, v6, v7, v10
	ds_read_b32 v7, v10
	v_pk_mul_f32 v[4:5], v[4:5], s[90:91] op_sel_hi:[1,0]
	s_waitcnt lgkmcnt(0)
	v_cvt_f32_f16_e32 v6, v7
	v_cvt_f32_f16_sdwa v7, v7 dst_sel:DWORD dst_unused:UNUSED_PAD src0_sel:WORD_1
	s_and_saveexec_b64 s[22:23], s[40:41]
	s_xor_b64 s[22:23], exec, s[22:23]
	s_cbranch_execz .LBB0_682
	v_bfrev_b32_e32 v9, v8
	v_lshrrev_b32_e32 v11, 19, v9
	v_lshrrev_b32_e32 v9, 17, v9
	v_and_b32_e32 v9, 0x2aaa, v9
	v_and_or_b32 v9, v11, s89, v9
	v_lshl_add_u32 v11, v9, 2, s66
	v_lshrrev_b32_e32 v13, 2, v9
	v_lshrrev_b32_e32 v9, 6, v9
	v_and_b32_e32 v13, 0xffc, v13
	v_and_b32_e32 v9, 0xfc, v9
	v_add3_u32 v9, v11, v13, v9
	ds_read_b32 v11, v9
	v_pk_mul_f32 v[18:19], v[6:7], v[4:5] op_sel:[0,0] op_sel_hi:[0,1]
	s_waitcnt lgkmcnt(0)
	v_cvt_f32_f16_e32 v16, v11
	v_cvt_f32_f16_sdwa v17, -v11 dst_sel:DWORD dst_unused:UNUSED_PAD src0_sel:WORD_1
	v_pk_mul_f32 v[22:23], v[16:17], v[2:3] op_sel:[0,0] op_sel_hi:[0,1]
	v_pk_fma_f32 v[18:19], v[6:7], v[4:5], v[18:19] op_sel:[1,1,0] op_sel_hi:[1,0,1] neg_lo:[0,1,0]
	v_pk_fma_f32 v[22:23], v[16:17], v[2:3], v[22:23] op_sel:[1,1,0] op_sel_hi:[1,0,1] neg_lo:[0,1,0]
	v_pk_add_f32 v[18:19], v[18:19], v[22:23]
	v_pk_mul_f32 v[22:23], v[16:17], v[4:5] op_sel:[0,0] op_sel_hi:[0,1]
	v_pk_fma_f32 v[4:5], v[16:17], v[4:5], v[22:23] op_sel:[1,1,0] op_sel_hi:[1,0,1] neg_lo:[0,1,0]
	v_pk_mul_f32 v[16:17], v[6:7], v[2:3] op_sel:[0,0] op_sel_hi:[0,1]
	v_pk_fma_f32 v[2:3], v[6:7], v[2:3], v[16:17] op_sel:[1,1,0] op_sel_hi:[1,0,1] neg_lo:[0,1,0]
	s_nop 0
	v_pk_add_f32 v[2:3], v[4:5], v[2:3]
	v_cvt_pk_f16_f32 v4, v18, v19
	v_cvt_pk_f16_f32 v2, v2, -v3
	ds_write_b32 v10, v4
	ds_write_b32 v9, v2

; DI int rev4(int pp) { const unsigned br = __brev((unsigned)pp) >> 18; return (int)(((br & 0x2AAAu) >> 1) | ((br & 0x1555u) << 1)); }
; DI void pw_h(LAS hc* X, const f32x4* spec, int tid) {
;     ...
;     if (tid == 0) { const int pp = rev4(8192); const f32x4 sp = spec[8192]; const hc zh = X[XI(pp)]; const cf z = (cf){(float)zh.x, (float)zh.y};
;         const cf y = (cmul(z, (cf){sp[0], sp[1]}) + cmul((cf){z.x, -z.y}, (cf){sp[2], sp[3]})) * 256.0f; X[XI(pp)] = (hc){(_Float16)y.x, (_Float16)y.y}; }
.LBB0_684:
	s_and_saveexec_b64 s[22:23], vcc
	s_cbranch_execz .LBB0_686
	v_readlane_b32 s4, v255, 18
	v_mov_b32_e32 v0, v132
	v_mov_b32_e32 v1, v133
	v_mov_b32_e32 v2, v134
	v_mov_b32_e32 v3, v135
	s_nop 0
	v_mov_b32_e32 v8, s4
	ds_read_b32 v5, v8
	s_waitcnt lgkmcnt(0)
	v_cvt_f32_f16_e32 v4, v5
	v_cvt_f32_f16_sdwa v5, v5 dst_sel:DWORD dst_unused:UNUSED_PAD src0_sel:WORD_1
	s_waitcnt vmcnt(0)
	v_pk_mul_f32 v[6:7], v[4:5], v[0:1] op_sel:[0,0] op_sel_hi:[0,1]
	v_pk_fma_f32 v[0:1], v[4:5], v[0:1], v[6:7] op_sel:[1,1,0] op_sel_hi:[1,0,1] neg_lo:[0,1,0]
	v_xor_b32_e32 v5, 0x80000000, v5
	v_pk_mul_f32 v[6:7], v[4:5], v[2:3] op_sel:[0,0] op_sel_hi:[0,1]
	v_pk_fma_f32 v[2:3], v[4:5], v[2:3], v[6:7] op_sel:[1,1,0] op_sel_hi:[1,0,1] neg_lo:[0,1,0]
	v_pk_add_f32 v[0:1], v[0:1], v[2:3]
	s_nop 0
	v_pk_mul_f32 v[0:1], v[0:1], s[90:91] op_sel_hi:[1,0]
	s_nop 0
	v_cvt_pk_f16_f32 v0, v0, v1
	ds_write_b32 v8, v0

; DI int rev4(int pp) { const unsigned br = __brev((unsigned)pp) >> 18; return (int)(((br & 0x2AAAu) >> 1) | ((br & 0x1555u) << 1)); }
; DI void pw_h(LAS hc* X, const f32x4* spec, int tid) {
;     ...
;     for (int r = 0; r < 16; ++r) {
;         const int k = tid + NTHR * r; const int pp = rev4(k);
;         const f32x4 sp = spec[k]; const cf P = (cf){sp[0], sp[1]} * 256.0f, Mq = (cf){sp[2], sp[3]} * 256.0f;
;         const hc zh = X[XI(pp)]; const cf z = (cf){(float)zh.x, (float)zh.y};
;         if (k == 0) { const cf y = cmul(z, P) + cmul((cf){z.x, -z.y}, Mq); X[XI(pp)] = (hc){(_Float16)y.x, (_Float16)y.y}; }
;         else { const int pm = rev4(16384 - k); const hc zmh = X[XI(pm)]; const cf zm = (cf){(float)zmh.x, (float)zmh.y};
;             const cf y = cmul(z, P) + cmul((cf){zm.x, -zm.y}, Mq);
;             const cf t = cmul((cf){zm.x, -zm.y}, P) + cmul(z, Mq);
;             X[XI(pp)] = (hc){(_Float16)y.x, (_Float16)y.y}; X[XI(pm)] = (hc){(_Float16)t.x, (_Float16)(-t.y)}; }
;     }
.LBB0_714:
	global_load_dwordx4 v[132:135], v224, s[20:21]
	global_load_dwordx4 v[4:7], v[0:1], off
	v_add_u32_e32 v9, s4, v12
	v_add_u32_e32 v2, 0x2000, v9
	v_bfrev_b32_e32 v2, v2
	v_lshrrev_b32_e32 v3, 19, v2
	v_lshrrev_b32_e32 v2, 17, v2
	v_and_b32_e32 v2, 0x2aaa, v2
	v_and_or_b32 v10, v3, s89, v2
	s_movk_i32 s5, 0xe000
	v_cmp_ne_u32_e64 s[40:41], s5, v9
	v_add_u32_e32 v100, 0x2200, v9
	v_ashrrev_i32_e32 v101, 31, v100
	v_lshl_add_u64 v[100:101], v[100:101], 4, s[20:21]
	global_load_dwordx4 v[104:107], v[100:101], off
	v_add_u32_e32 v100, 0x2400, v9
	v_ashrrev_i32_e32 v101, 31, v100
	v_lshl_add_u64 v[100:101], v[100:101], 4, s[20:21]
	global_load_dwordx4 v[108:111], v[100:101], off
	v_add_u32_e32 v100, 0x2600, v9
	v_ashrrev_i32_e32 v101, 31, v100
	v_lshl_add_u64 v[100:101], v[100:101], 4, s[20:21]
	global_load_dwordx4 v[112:115], v[100:101], off
	v_add_u32_e32 v100, 0x2800, v9
	v_ashrrev_i32_e32 v101, 31, v100
	v_lshl_add_u64 v[100:101], v[100:101], 4, s[20:21]
	global_load_dwordx4 v[116:119], v[100:101], off
	v_add_u32_e32 v100, 0x2a00, v9
	v_ashrrev_i32_e32 v101, 31, v100
	v_lshl_add_u64 v[100:101], v[100:101], 4, s[20:21]
	global_load_dwordx4 v[120:123], v[100:101], off
	v_add_u32_e32 v100, 0x2c00, v9
	v_ashrrev_i32_e32 v101, 31, v100
	v_lshl_add_u64 v[100:101], v[100:101], 4, s[20:21]
	global_load_dwordx4 v[124:127], v[100:101], off
	v_add_u32_e32 v100, 0x2e00, v9
	v_ashrrev_i32_e32 v101, 31, v100
	v_lshl_add_u64 v[100:101], v[100:101], 4, s[20:21]
	global_load_dwordx4 v[128:131], v[100:101], off
	v_add_u32_e32 v100, 0x3000, v9
	v_ashrrev_i32_e32 v101, 31, v100
	v_lshl_add_u64 v[100:101], v[100:101], 4, s[20:21]
	global_load_dword v136, v[100:101], off
	v_add_u32_e32 v100, 0x3200, v9
	v_ashrrev_i32_e32 v101, 31, v100
	v_lshl_add_u64 v[100:101], v[100:101], 4, s[20:21]
	global_load_dword v137, v[100:101], off
	v_add_u32_e32 v100, 0x3400, v9
	v_ashrrev_i32_e32 v101, 31, v100
	v_lshl_add_u64 v[100:101], v[100:101], 4, s[20:21]
	global_load_dword v138, v[100:101], off
	v_add_u32_e32 v100, 0x3600, v9
	v_ashrrev_i32_e32 v101, 31, v100
	v_lshl_add_u64 v[100:101], v[100:101], 4, s[20:21]
	global_load_dword v139, v[100:101], off
	v_add_u32_e32 v100, 0x3800, v9
	v_ashrrev_i32_e32 v101, 31, v100
	v_lshl_add_u64 v[100:101], v[100:101], 4, s[20:21]
	global_load_dword v140, v[100:101], off
	v_add_u32_e32 v100, 0x3a00, v9
	v_ashrrev_i32_e32 v101, 31, v100
	v_lshl_add_u64 v[100:101], v[100:101], 4, s[20:21]
	global_load_dword v141, v[100:101], off
	v_add_u32_e32 v100, 0x3c00, v9
	v_ashrrev_i32_e32 v101, 31, v100
	v_lshl_add_u64 v[100:101], v[100:101], 4, s[20:21]
	global_load_dword v142, v[100:101], off
	v_add_u32_e32 v100, 0x3e00, v9
	v_ashrrev_i32_e32 v101, 31, v100
	v_lshl_add_u64 v[100:101], v[100:101], 4, s[20:21]
	global_load_dword v143, v[100:101], off
	s_waitcnt vmcnt(15)
	v_pk_mul_f32 v[2:3], v[6:7], s[90:91] op_sel_hi:[1,0]
	v_lshl_add_u32 v6, v10, 2, 0
	v_lshrrev_b32_e32 v7, 2, v10
	v_lshrrev_b32_e32 v10, 6, v10
	v_and_b32_e32 v7, 0xffc, v7
	v_and_b32_e32 v10, 0xfc, v10
	v_add3_u32 v10, v6, v7, v10
	ds_read_b32 v7, v10
	v_pk_mul_f32 v[4:5], v[4:5], s[90:91] op_sel_hi:[1,0]
	s_waitcnt lgkmcnt(0)
	v_cvt_f32_f16_e32 v6, v7
	v_cvt_f32_f16_sdwa v7, v7 dst_sel:DWORD dst_unused:UNUSED_PAD src0_sel:WORD_1
	s_and_saveexec_b64 s[22:23], s[40:41]
	s_xor_b64 s[22:23], exec, s[22:23]
	s_cbranch_execz .LBB0_716
	v_add_u32_e32 v11, 0xe00, v8
	v_bfrev_b32_e32 v11, v11
	v_lshrrev_b32_e32 v13, 19, v11
	v_lshrrev_b32_e32 v11, 17, v11
	v_and_b32_e32 v11, 0x2aaa, v11
	v_and_or_b32 v11, v13, s89, v11
	v_lshl_add_u32 v13, v11, 2, 0
	v_lshrrev_b32_e32 v16, 2, v11
	v_lshrrev_b32_e32 v11, 6, v11
	v_and_b32_e32 v16, 0xffc, v16
	v_and_b32_e32 v11, 0xfc, v11
	v_add3_u32 v11, v13, v16, v11
	ds_read_b32 v13, v11
	v_pk_mul_f32 v[18:19], v[6:7], v[4:5] op_sel:[0,0] op_sel_hi:[0,1]
	s_waitcnt lgkmcnt(0)
	v_cvt_f32_f16_e32 v16, v13
	v_cvt_f32_f16_sdwa v17, -v13 dst_sel:DWORD dst_unused:UNUSED_PAD src0_sel:WORD_1
	v_pk_mul_f32 v[22:23], v[16:17], v[2:3] op_sel:[0,0] op_sel_hi:[0,1]
	v_pk_fma_f32 v[18:19], v[6:7], v[4:5], v[18:19] op_sel:[1,1,0] op_sel_hi:[1,0,1] neg_lo:[0,1,0]
	v_pk_fma_f32 v[22:23], v[16:17], v[2:3], v[22:23] op_sel:[1,1,0] op_sel_hi:[1,0,1] neg_lo:[0,1,0]
	v_pk_add_f32 v[18:19], v[18:19], v[22:23]
	v_pk_mul_f32 v[22:23], v[16:17], v[4:5] op_sel:[0,0] op_sel_hi:[0,1]
	v_pk_fma_f32 v[4:5], v[16:17], v[4:5], v[22:23] op_sel:[1,1,0] op_sel_hi:[1,0,1] neg_lo:[0,1,0]
	v_pk_mul_f32 v[16:17], v[6:7], v[2:3] op_sel:[0,0] op_sel_hi:[0,1]
	v_pk_fma_f32 v[2:3], v[6:7], v[2:3], v[16:17] op_sel:[1,1,0] op_sel_hi:[1,0,1] neg_lo:[0,1,0]
	s_nop 0
	v_pk_add_f32 v[2:3], v[4:5], v[2:3]
	v_cvt_pk_f16_f32 v4, v18, v19
	v_cvt_pk_f16_f32 v2, v2, -v3
	ds_write_b32 v10, v4
	ds_write_b32 v11, v2

; DI int rev4(int pp) { const unsigned br = __brev((unsigned)pp) >> 18; return (int)(((br & 0x2AAAu) >> 1) | ((br & 0x1555u) << 1)); }
; DI void pw_h(LAS hc* X, const f32x4* spec, int tid) {
;     ...
;     for (int r = 0; r < 16; ++r) {
;         const int k = tid + NTHR * r; const int pp = rev4(k);
;         const f32x4 sp = spec[k]; const cf P = (cf){sp[0], sp[1]} * 256.0f, Mq = (cf){sp[2], sp[3]} * 256.0f;
;         const hc zh = X[XI(pp)]; const cf z = (cf){(float)zh.x, (float)zh.y};
;         if (k == 0) { const cf y = cmul(z, P) + cmul((cf){z.x, -z.y}, Mq); X[XI(pp)] = (hc){(_Float16)y.x, (_Float16)y.y}; }
;         else { const int pm = rev4(16384 - k); const hc zmh = X[XI(pm)]; const cf zm = (cf){(float)zmh.x, (float)zmh.y};
;             const cf y = cmul(z, P) + cmul((cf){zm.x, -zm.y}, Mq);
;             const cf t = cmul((cf){zm.x, -zm.y}, P) + cmul(z, Mq);
;             X[XI(pp)] = (hc){(_Float16)y.x, (_Float16)y.y}; X[XI(pm)] = (hc){(_Float16)t.x, (_Float16)(-t.y)}; }
;     }
.LBB0_718:
	s_or_b64 exec, exec, s[22:23]
	v_add_u32_e32 v2, 0x2200, v9
	v_bfrev_b32_e32 v3, v2
	v_lshrrev_b32_e32 v4, 19, v3
	v_lshrrev_b32_e32 v3, 17, v3
	v_and_b32_e32 v3, 0x2aaa, v3
	v_and_or_b32 v10, v4, s89, v3
	s_movk_i32 s5, 0xde00
	v_cmp_ne_u32_e64 s[40:41], s5, v9
	s_waitcnt vmcnt(14)
	v_mov_b32_e32 v4, v104
	v_mov_b32_e32 v5, v105
	v_mov_b32_e32 v6, v106
	v_mov_b32_e32 v7, v107
	v_pk_mul_f32 v[2:3], v[6:7], s[90:91] op_sel_hi:[1,0]
	v_lshl_add_u32 v6, v10, 2, 0
	v_lshrrev_b32_e32 v7, 2, v10
	v_lshrrev_b32_e32 v10, 6, v10
	v_and_b32_e32 v7, 0xffc, v7
	v_and_b32_e32 v10, 0xfc, v10
	v_add3_u32 v10, v6, v7, v10
	ds_read_b32 v7, v10
	v_pk_mul_f32 v[4:5], v[4:5], s[90:91] op_sel_hi:[1,0]
	s_waitcnt lgkmcnt(0)
	v_cvt_f32_f16_e32 v6, v7
	v_cvt_f32_f16_sdwa v7, v7 dst_sel:DWORD dst_unused:UNUSED_PAD src0_sel:WORD_1
	s_and_saveexec_b64 s[22:23], s[40:41]
	s_xor_b64 s[22:23], exec, s[22:23]
	s_cbranch_execz .LBB0_720
	v_add_u32_e32 v11, 0xc00, v8
	v_bfrev_b32_e32 v11, v11
	v_lshrrev_b32_e32 v13, 19, v11
	v_lshrrev_b32_e32 v11, 17, v11
	v_and_b32_e32 v11, 0x2aaa, v11
	v_and_or_b32 v11, v13, s89, v11
	v_lshl_add_u32 v13, v11, 2, 0
	v_lshrrev_b32_e32 v16, 2, v11
	v_lshrrev_b32_e32 v11, 6, v11
	v_and_b32_e32 v16, 0xffc, v16
	v_and_b32_e32 v11, 0xfc, v11
	v_add3_u32 v11, v13, v16, v11
	ds_read_b32 v13, v11
	v_pk_mul_f32 v[18:19], v[6:7], v[4:5] op_sel:[0,0] op_sel_hi:[0,1]
	s_waitcnt lgkmcnt(0)
	v_cvt_f32_f16_e32 v16, v13
	v_cvt_f32_f16_sdwa v17, -v13 dst_sel:DWORD dst_unused:UNUSED_PAD src0_sel:WORD_1
	v_pk_mul_f32 v[22:23], v[16:17], v[2:3] op_sel:[0,0] op_sel_hi:[0,1]
	v_pk_fma_f32 v[18:19], v[6:7], v[4:5], v[18:19] op_sel:[1,1,0] op_sel_hi:[1,0,1] neg_lo:[0,1,0]
	v_pk_fma_f32 v[22:23], v[16:17], v[2:3], v[22:23] op_sel:[1,1,0] op_sel_hi:[1,0,1] neg_lo:[0,1,0]
	v_pk_add_f32 v[18:19], v[18:19], v[22:23]
	v_pk_mul_f32 v[22:23], v[16:17], v[4:5] op_sel:[0,0] op_sel_hi:[0,1]
	v_pk_fma_f32 v[4:5], v[16:17], v[4:5], v[22:23] op_sel:[1,1,0] op_sel_hi:[1,0,1] neg_lo:[0,1,0]
	v_pk_mul_f32 v[16:17], v[6:7], v[2:3] op_sel:[0,0] op_sel_hi:[0,1]
	v_pk_fma_f32 v[2:3], v[6:7], v[2:3], v[16:17] op_sel:[1,1,0] op_sel_hi:[1,0,1] neg_lo:[0,1,0]
	s_nop 0
	v_pk_add_f32 v[2:3], v[4:5], v[2:3]
	v_cvt_pk_f16_f32 v4, v18, v19
	v_cvt_pk_f16_f32 v2, v2, -v3
	ds_write_b32 v10, v4
	ds_write_b32 v11, v2

; DI int rev4(int pp) { const unsigned br = __brev((unsigned)pp) >> 18; return (int)(((br & 0x2AAAu) >> 1) | ((br & 0x1555u) << 1)); }
; DI void pw_h(LAS hc* X, const f32x4* spec, int tid) {
;     ...
;     for (int r = 0; r < 16; ++r) {
;         const int k = tid + NTHR * r; const int pp = rev4(k);
;         const f32x4 sp = spec[k]; const cf P = (cf){sp[0], sp[1]} * 256.0f, Mq = (cf){sp[2], sp[3]} * 256.0f;
;         const hc zh = X[XI(pp)]; const cf z = (cf){(float)zh.x, (float)zh.y};
;         if (k == 0) { const cf y = cmul(z, P) + cmul((cf){z.x, -z.y}, Mq); X[XI(pp)] = (hc){(_Float16)y.x, (_Float16)y.y}; }
;         else { const int pm = rev4(16384 - k); const hc zmh = X[XI(pm)]; const cf zm = (cf){(float)zmh.x, (float)zmh.y};
;             const cf y = cmul(z, P) + cmul((cf){zm.x, -zm.y}, Mq);
;             const cf t = cmul((cf){zm.x, -zm.y}, P) + cmul(z, Mq);
;             X[XI(pp)] = (hc){(_Float16)y.x, (_Float16)y.y}; X[XI(pm)] = (hc){(_Float16)t.x, (_Float16)(-t.y)}; }
;     }
.LBB0_722:
	s_or_b64 exec, exec, s[22:23]
	v_add_u32_e32 v2, 0x2400, v9
	v_bfrev_b32_e32 v3, v2
	v_lshrrev_b32_e32 v4, 19, v3
	v_lshrrev_b32_e32 v3, 17, v3
	v_and_b32_e32 v3, 0x2aaa, v3
	v_and_or_b32 v10, v4, s89, v3
	s_movk_i32 s5, 0xdc00
	v_cmp_ne_u32_e64 s[40:41], s5, v9
	s_waitcnt vmcnt(13)
	v_mov_b32_e32 v4, v108
	v_mov_b32_e32 v5, v109
	v_mov_b32_e32 v6, v110
	v_mov_b32_e32 v7, v111
	v_pk_mul_f32 v[2:3], v[6:7], s[90:91] op_sel_hi:[1,0]
	v_lshl_add_u32 v6, v10, 2, 0
	v_lshrrev_b32_e32 v7, 2, v10
	v_lshrrev_b32_e32 v10, 6, v10
	v_and_b32_e32 v7, 0xffc, v7
	v_and_b32_e32 v10, 0xfc, v10
	v_add3_u32 v10, v6, v7, v10
	ds_read_b32 v7, v10
	v_pk_mul_f32 v[4:5], v[4:5], s[90:91] op_sel_hi:[1,0]
	s_waitcnt lgkmcnt(0)
	v_cvt_f32_f16_e32 v6, v7
	v_cvt_f32_f16_sdwa v7, v7 dst_sel:DWORD dst_unused:UNUSED_PAD src0_sel:WORD_1
	s_and_saveexec_b64 s[22:23], s[40:41]
	s_xor_b64 s[22:23], exec, s[22:23]
	s_cbranch_execz .LBB0_724
	v_add_u32_e32 v11, 0xa00, v8
	v_bfrev_b32_e32 v11, v11
	v_lshrrev_b32_e32 v13, 19, v11
	v_lshrrev_b32_e32 v11, 17, v11
	v_and_b32_e32 v11, 0x2aaa, v11
	v_and_or_b32 v11, v13, s89, v11
	v_lshl_add_u32 v13, v11, 2, 0
	v_lshrrev_b32_e32 v16, 2, v11
	v_lshrrev_b32_e32 v11, 6, v11
	v_and_b32_e32 v16, 0xffc, v16
	v_and_b32_e32 v11, 0xfc, v11
	v_add3_u32 v11, v13, v16, v11
	ds_read_b32 v13, v11
	v_pk_mul_f32 v[18:19], v[6:7], v[4:5] op_sel:[0,0] op_sel_hi:[0,1]
	s_waitcnt lgkmcnt(0)
	v_cvt_f32_f16_e32 v16, v13
	v_cvt_f32_f16_sdwa v17, -v13 dst_sel:DWORD dst_unused:UNUSED_PAD src0_sel:WORD_1
	v_pk_mul_f32 v[22:23], v[16:17], v[2:3] op_sel:[0,0] op_sel_hi:[0,1]
	v_pk_fma_f32 v[18:19], v[6:7], v[4:5], v[18:19] op_sel:[1,1,0] op_sel_hi:[1,0,1] neg_lo:[0,1,0]
	v_pk_fma_f32 v[22:23], v[16:17], v[2:3], v[22:23] op_sel:[1,1,0] op_sel_hi:[1,0,1] neg_lo:[0,1,0]
	v_pk_add_f32 v[18:19], v[18:19], v[22:23]
	v_pk_mul_f32 v[22:23], v[16:17], v[4:5] op_sel:[0,0] op_sel_hi:[0,1]
	v_pk_fma_f32 v[4:5], v[16:17], v[4:5], v[22:23] op_sel:[1,1,0] op_sel_hi:[1,0,1] neg_lo:[0,1,0]
	v_pk_mul_f32 v[16:17], v[6:7], v[2:3] op_sel:[0,0] op_sel_hi:[0,1]
	v_pk_fma_f32 v[2:3], v[6:7], v[2:3], v[16:17] op_sel:[1,1,0] op_sel_hi:[1,0,1] neg_lo:[0,1,0]
	s_nop 0
	v_pk_add_f32 v[2:3], v[4:5], v[2:3]
	v_cvt_pk_f16_f32 v4, v18, v19
	v_cvt_pk_f16_f32 v2, v2, -v3
	ds_write_b32 v10, v4
	ds_write_b32 v11, v2

; DI int rev4(int pp) { const unsigned br = __brev((unsigned)pp) >> 18; return (int)(((br & 0x2AAAu) >> 1) | ((br & 0x1555u) << 1)); }
; DI void pw_h(LAS hc* X, const f32x4* spec, int tid) {
;     ...
;     for (int r = 0; r < 16; ++r) {
;         const int k = tid + NTHR * r; const int pp = rev4(k);
;         const f32x4 sp = spec[k]; const cf P = (cf){sp[0], sp[1]} * 256.0f, Mq = (cf){sp[2], sp[3]} * 256.0f;
;         const hc zh = X[XI(pp)]; const cf z = (cf){(float)zh.x, (float)zh.y};
;         if (k == 0) { const cf y = cmul(z, P) + cmul((cf){z.x, -z.y}, Mq); X[XI(pp)] = (hc){(_Float16)y.x, (_Float16)y.y}; }
;         else { const int pm = rev4(16384 - k); const hc zmh = X[XI(pm)]; const cf zm = (cf){(float)zmh.x, (float)zmh.y};
;             const cf y = cmul(z, P) + cmul((cf){zm.x, -zm.y}, Mq);
;             const cf t = cmul((cf){zm.x, -zm.y}, P) + cmul(z, Mq);
;             X[XI(pp)] = (hc){(_Float16)y.x, (_Float16)y.y}; X[XI(pm)] = (hc){(_Float16)t.x, (_Float16)(-t.y)}; }
;     }
.LBB0_726:
	s_or_b64 exec, exec, s[22:23]
	v_add_u32_e32 v2, 0x2600, v9
	v_bfrev_b32_e32 v3, v2
	v_lshrrev_b32_e32 v4, 19, v3
	v_lshrrev_b32_e32 v3, 17, v3
	v_and_b32_e32 v3, 0x2aaa, v3
	v_and_or_b32 v10, v4, s89, v3
	s_movk_i32 s5, 0xda00
	v_cmp_ne_u32_e64 s[40:41], s5, v9
	s_waitcnt vmcnt(12)
	v_mov_b32_e32 v4, v112
	v_mov_b32_e32 v5, v113
	v_mov_b32_e32 v6, v114
	v_mov_b32_e32 v7, v115
	v_pk_mul_f32 v[2:3], v[6:7], s[90:91] op_sel_hi:[1,0]
	v_lshl_add_u32 v6, v10, 2, 0
	v_lshrrev_b32_e32 v7, 2, v10
	v_lshrrev_b32_e32 v10, 6, v10
	v_and_b32_e32 v7, 0xffc, v7
	v_and_b32_e32 v10, 0xfc, v10
	v_add3_u32 v10, v6, v7, v10
	ds_read_b32 v7, v10
	v_pk_mul_f32 v[4:5], v[4:5], s[90:91] op_sel_hi:[1,0]
	s_waitcnt lgkmcnt(0)
	v_cvt_f32_f16_e32 v6, v7
	v_cvt_f32_f16_sdwa v7, v7 dst_sel:DWORD dst_unused:UNUSED_PAD src0_sel:WORD_1
	s_and_saveexec_b64 s[22:23], s[40:41]
	s_xor_b64 s[22:23], exec, s[22:23]
	s_cbranch_execz .LBB0_728
	v_add_u32_e32 v11, 0x800, v8
	v_bfrev_b32_e32 v11, v11
	v_lshrrev_b32_e32 v13, 19, v11
	v_lshrrev_b32_e32 v11, 17, v11
	v_and_b32_e32 v11, 0x2aaa, v11
	v_and_or_b32 v11, v13, s89, v11
	v_lshl_add_u32 v13, v11, 2, 0
	v_lshrrev_b32_e32 v16, 2, v11
	v_lshrrev_b32_e32 v11, 6, v11
	v_and_b32_e32 v16, 0xffc, v16
	v_and_b32_e32 v11, 0xfc, v11
	v_add3_u32 v11, v13, v16, v11
	ds_read_b32 v13, v11
	v_pk_mul_f32 v[18:19], v[6:7], v[4:5] op_sel:[0,0] op_sel_hi:[0,1]
	s_waitcnt lgkmcnt(0)
	v_cvt_f32_f16_e32 v16, v13
	v_cvt_f32_f16_sdwa v17, -v13 dst_sel:DWORD dst_unused:UNUSED_PAD src0_sel:WORD_1
	v_pk_mul_f32 v[22:23], v[16:17], v[2:3] op_sel:[0,0] op_sel_hi:[0,1]
	v_pk_fma_f32 v[18:19], v[6:7], v[4:5], v[18:19] op_sel:[1,1,0] op_sel_hi:[1,0,1] neg_lo:[0,1,0]
	v_pk_fma_f32 v[22:23], v[16:17], v[2:3], v[22:23] op_sel:[1,1,0] op_sel_hi:[1,0,1] neg_lo:[0,1,0]
	v_pk_add_f32 v[18:19], v[18:19], v[22:23]
	v_pk_mul_f32 v[22:23], v[16:17], v[4:5] op_sel:[0,0] op_sel_hi:[0,1]
	v_pk_fma_f32 v[4:5], v[16:17], v[4:5], v[22:23] op_sel:[1,1,0] op_sel_hi:[1,0,1] neg_lo:[0,1,0]
	v_pk_mul_f32 v[16:17], v[6:7], v[2:3] op_sel:[0,0] op_sel_hi:[0,1]
	v_pk_fma_f32 v[2:3], v[6:7], v[2:3], v[16:17] op_sel:[1,1,0] op_sel_hi:[1,0,1] neg_lo:[0,1,0]
	s_nop 0
	v_pk_add_f32 v[2:3], v[4:5], v[2:3]
	v_cvt_pk_f16_f32 v4, v18, v19
	v_cvt_pk_f16_f32 v2, v2, -v3
	ds_write_b32 v10, v4
	ds_write_b32 v11, v2

; DI int rev4(int pp) { const unsigned br = __brev((unsigned)pp) >> 18; return (int)(((br & 0x2AAAu) >> 1) | ((br & 0x1555u) << 1)); }
; DI void pw_h(LAS hc* X, const f32x4* spec, int tid) {
;     ...
;     for (int r = 0; r < 16; ++r) {
;         const int k = tid + NTHR * r; const int pp = rev4(k);
;         const f32x4 sp = spec[k]; const cf P = (cf){sp[0], sp[1]} * 256.0f, Mq = (cf){sp[2], sp[3]} * 256.0f;
;         const hc zh = X[XI(pp)]; const cf z = (cf){(float)zh.x, (float)zh.y};
;         if (k == 0) { const cf y = cmul(z, P) + cmul((cf){z.x, -z.y}, Mq); X[XI(pp)] = (hc){(_Float16)y.x, (_Float16)y.y}; }
;         else { const int pm = rev4(16384 - k); const hc zmh = X[XI(pm)]; const cf zm = (cf){(float)zmh.x, (float)zmh.y};
;             const cf y = cmul(z, P) + cmul((cf){zm.x, -zm.y}, Mq);
;             const cf t = cmul((cf){zm.x, -zm.y}, P) + cmul(z, Mq);
;             X[XI(pp)] = (hc){(_Float16)y.x, (_Float16)y.y}; X[XI(pm)] = (hc){(_Float16)t.x, (_Float16)(-t.y)}; }
;     }
.LBB0_730:
	s_or_b64 exec, exec, s[22:23]
	v_add_u32_e32 v2, 0x2800, v9
	v_bfrev_b32_e32 v3, v2
	v_lshrrev_b32_e32 v4, 19, v3
	v_lshrrev_b32_e32 v3, 17, v3
	v_and_b32_e32 v3, 0x2aaa, v3
	v_and_or_b32 v10, v4, s89, v3
	s_movk_i32 s5, 0xd800
	v_cmp_ne_u32_e64 s[40:41], s5, v9
	s_waitcnt vmcnt(11)
	v_mov_b32_e32 v4, v116
	v_mov_b32_e32 v5, v117
	v_mov_b32_e32 v6, v118
	v_mov_b32_e32 v7, v119
	v_pk_mul_f32 v[2:3], v[6:7], s[90:91] op_sel_hi:[1,0]
	v_lshl_add_u32 v6, v10, 2, 0
	v_lshrrev_b32_e32 v7, 2, v10
	v_lshrrev_b32_e32 v10, 6, v10
	v_and_b32_e32 v7, 0xffc, v7
	v_and_b32_e32 v10, 0xfc, v10
	v_add3_u32 v10, v6, v7, v10
	ds_read_b32 v7, v10
	v_pk_mul_f32 v[4:5], v[4:5], s[90:91] op_sel_hi:[1,0]
	s_waitcnt lgkmcnt(0)
	v_cvt_f32_f16_e32 v6, v7
	v_cvt_f32_f16_sdwa v7, v7 dst_sel:DWORD dst_unused:UNUSED_PAD src0_sel:WORD_1
	s_and_saveexec_b64 s[22:23], s[40:41]
	s_xor_b64 s[22:23], exec, s[22:23]
	s_cbranch_execz .LBB0_732
	v_add_u32_e32 v11, 0x600, v8
	v_bfrev_b32_e32 v11, v11
	v_lshrrev_b32_e32 v13, 19, v11
	v_lshrrev_b32_e32 v11, 17, v11
	v_and_b32_e32 v11, 0x2aaa, v11
	v_and_or_b32 v11, v13, s89, v11
	v_lshl_add_u32 v13, v11, 2, 0
	v_lshrrev_b32_e32 v16, 2, v11
	v_lshrrev_b32_e32 v11, 6, v11
	v_and_b32_e32 v16, 0xffc, v16
	v_and_b32_e32 v11, 0xfc, v11
	v_add3_u32 v11, v13, v16, v11
	ds_read_b32 v13, v11
	v_pk_mul_f32 v[18:19], v[6:7], v[4:5] op_sel:[0,0] op_sel_hi:[0,1]
	s_waitcnt lgkmcnt(0)
	v_cvt_f32_f16_e32 v16, v13
	v_cvt_f32_f16_sdwa v17, -v13 dst_sel:DWORD dst_unused:UNUSED_PAD src0_sel:WORD_1
	v_pk_mul_f32 v[22:23], v[16:17], v[2:3] op_sel:[0,0] op_sel_hi:[0,1]
	v_pk_fma_f32 v[18:19], v[6:7], v[4:5], v[18:19] op_sel:[1,1,0] op_sel_hi:[1,0,1] neg_lo:[0,1,0]
	v_pk_fma_f32 v[22:23], v[16:17], v[2:3], v[22:23] op_sel:[1,1,0] op_sel_hi:[1,0,1] neg_lo:[0,1,0]
	v_pk_add_f32 v[18:19], v[18:19], v[22:23]
	v_pk_mul_f32 v[22:23], v[16:17], v[4:5] op_sel:[0,0] op_sel_hi:[0,1]
	v_pk_fma_f32 v[4:5], v[16:17], v[4:5], v[22:23] op_sel:[1,1,0] op_sel_hi:[1,0,1] neg_lo:[0,1,0]
	v_pk_mul_f32 v[16:17], v[6:7], v[2:3] op_sel:[0,0] op_sel_hi:[0,1]
	v_pk_fma_f32 v[2:3], v[6:7], v[2:3], v[16:17] op_sel:[1,1,0] op_sel_hi:[1,0,1] neg_lo:[0,1,0]
	s_nop 0
	v_pk_add_f32 v[2:3], v[4:5], v[2:3]
	v_cvt_pk_f16_f32 v4, v18, v19
	v_cvt_pk_f16_f32 v2, v2, -v3
	ds_write_b32 v10, v4
	ds_write_b32 v11, v2

; DI int rev4(int pp) { const unsigned br = __brev((unsigned)pp) >> 18; return (int)(((br & 0x2AAAu) >> 1) | ((br & 0x1555u) << 1)); }
; DI void pw_h(LAS hc* X, const f32x4* spec, int tid) {
;     ...
;     for (int r = 0; r < 16; ++r) {
;         const int k = tid + NTHR * r; const int pp = rev4(k);
;         const f32x4 sp = spec[k]; const cf P = (cf){sp[0], sp[1]} * 256.0f, Mq = (cf){sp[2], sp[3]} * 256.0f;
;         const hc zh = X[XI(pp)]; const cf z = (cf){(float)zh.x, (float)zh.y};
;         if (k == 0) { const cf y = cmul(z, P) + cmul((cf){z.x, -z.y}, Mq); X[XI(pp)] = (hc){(_Float16)y.x, (_Float16)y.y}; }
;         else { const int pm = rev4(16384 - k); const hc zmh = X[XI(pm)]; const cf zm = (cf){(float)zmh.x, (float)zmh.y};
;             const cf y = cmul(z, P) + cmul((cf){zm.x, -zm.y}, Mq);
;             const cf t = cmul((cf){zm.x, -zm.y}, P) + cmul(z, Mq);
;             X[XI(pp)] = (hc){(_Float16)y.x, (_Float16)y.y}; X[XI(pm)] = (hc){(_Float16)t.x, (_Float16)(-t.y)}; }
;     }
.LBB0_734:
	s_or_b64 exec, exec, s[22:23]
	v_add_u32_e32 v2, 0x2a00, v9
	v_bfrev_b32_e32 v3, v2
	v_lshrrev_b32_e32 v4, 19, v3
	v_lshrrev_b32_e32 v3, 17, v3
	v_and_b32_e32 v3, 0x2aaa, v3
	v_and_or_b32 v10, v4, s89, v3
	s_movk_i32 s5, 0xd600
	v_cmp_ne_u32_e64 s[40:41], s5, v9
	s_waitcnt vmcnt(10)
	v_mov_b32_e32 v4, v120
	v_mov_b32_e32 v5, v121
	v_mov_b32_e32 v6, v122
	v_mov_b32_e32 v7, v123
	v_pk_mul_f32 v[2:3], v[6:7], s[90:91] op_sel_hi:[1,0]
	v_lshl_add_u32 v6, v10, 2, 0
	v_lshrrev_b32_e32 v7, 2, v10
	v_lshrrev_b32_e32 v10, 6, v10
	v_and_b32_e32 v7, 0xffc, v7
	v_and_b32_e32 v10, 0xfc, v10
	v_add3_u32 v10, v6, v7, v10
	ds_read_b32 v7, v10
	v_pk_mul_f32 v[4:5], v[4:5], s[90:91] op_sel_hi:[1,0]
	s_waitcnt lgkmcnt(0)
	v_cvt_f32_f16_e32 v6, v7
	v_cvt_f32_f16_sdwa v7, v7 dst_sel:DWORD dst_unused:UNUSED_PAD src0_sel:WORD_1
	s_and_saveexec_b64 s[22:23], s[40:41]
	s_xor_b64 s[22:23], exec, s[22:23]
	s_cbranch_execz .LBB0_736
	v_add_u32_e32 v11, 0x400, v8
	v_bfrev_b32_e32 v11, v11
	v_lshrrev_b32_e32 v13, 19, v11
	v_lshrrev_b32_e32 v11, 17, v11
	v_and_b32_e32 v11, 0x2aaa, v11
	v_and_or_b32 v11, v13, s89, v11
	v_lshl_add_u32 v13, v11, 2, 0
	v_lshrrev_b32_e32 v16, 2, v11
	v_lshrrev_b32_e32 v11, 6, v11
	v_and_b32_e32 v16, 0xffc, v16
	v_and_b32_e32 v11, 0xfc, v11
	v_add3_u32 v11, v13, v16, v11
	ds_read_b32 v13, v11
	v_pk_mul_f32 v[18:19], v[6:7], v[4:5] op_sel:[0,0] op_sel_hi:[0,1]
	s_waitcnt lgkmcnt(0)
	v_cvt_f32_f16_e32 v16, v13
	v_cvt_f32_f16_sdwa v17, -v13 dst_sel:DWORD dst_unused:UNUSED_PAD src0_sel:WORD_1
	v_pk_mul_f32 v[22:23], v[16:17], v[2:3] op_sel:[0,0] op_sel_hi:[0,1]
	v_pk_fma_f32 v[18:19], v[6:7], v[4:5], v[18:19] op_sel:[1,1,0] op_sel_hi:[1,0,1] neg_lo:[0,1,0]
	v_pk_fma_f32 v[22:23], v[16:17], v[2:3], v[22:23] op_sel:[1,1,0] op_sel_hi:[1,0,1] neg_lo:[0,1,0]
	v_pk_add_f32 v[18:19], v[18:19], v[22:23]
	v_pk_mul_f32 v[22:23], v[16:17], v[4:5] op_sel:[0,0] op_sel_hi:[0,1]
	v_pk_fma_f32 v[4:5], v[16:17], v[4:5], v[22:23] op_sel:[1,1,0] op_sel_hi:[1,0,1] neg_lo:[0,1,0]
	v_pk_mul_f32 v[16:17], v[6:7], v[2:3] op_sel:[0,0] op_sel_hi:[0,1]
	v_pk_fma_f32 v[2:3], v[6:7], v[2:3], v[16:17] op_sel:[1,1,0] op_sel_hi:[1,0,1] neg_lo:[0,1,0]
	s_nop 0
	v_pk_add_f32 v[2:3], v[4:5], v[2:3]
	v_cvt_pk_f16_f32 v4, v18, v19
	v_cvt_pk_f16_f32 v2, v2, -v3
	ds_write_b32 v10, v4
	ds_write_b32 v11, v2

; DI int rev4(int pp) { const unsigned br = __brev((unsigned)pp) >> 18; return (int)(((br & 0x2AAAu) >> 1) | ((br & 0x1555u) << 1)); }
; DI void pw_h(LAS hc* X, const f32x4* spec, int tid) {
;     ...
;     for (int r = 0; r < 16; ++r) {
;         const int k = tid + NTHR * r; const int pp = rev4(k);
;         const f32x4 sp = spec[k]; const cf P = (cf){sp[0], sp[1]} * 256.0f, Mq = (cf){sp[2], sp[3]} * 256.0f;
;         const hc zh = X[XI(pp)]; const cf z = (cf){(float)zh.x, (float)zh.y};
;         if (k == 0) { const cf y = cmul(z, P) + cmul((cf){z.x, -z.y}, Mq); X[XI(pp)] = (hc){(_Float16)y.x, (_Float16)y.y}; }
;         else { const int pm = rev4(16384 - k); const hc zmh = X[XI(pm)]; const cf zm = (cf){(float)zmh.x, (float)zmh.y};
;             const cf y = cmul(z, P) + cmul((cf){zm.x, -zm.y}, Mq);
;             const cf t = cmul((cf){zm.x, -zm.y}, P) + cmul(z, Mq);
;             X[XI(pp)] = (hc){(_Float16)y.x, (_Float16)y.y}; X[XI(pm)] = (hc){(_Float16)t.x, (_Float16)(-t.y)}; }
;     }
.LBB0_738:
	s_or_b64 exec, exec, s[22:23]
	v_add_u32_e32 v2, 0x2c00, v9
	v_bfrev_b32_e32 v3, v2
	v_lshrrev_b32_e32 v4, 19, v3
	v_lshrrev_b32_e32 v3, 17, v3
	v_and_b32_e32 v3, 0x2aaa, v3
	v_and_or_b32 v10, v4, s89, v3
	v_cmp_ne_u32_e64 s[40:41], s96, v9
	s_waitcnt vmcnt(9)
	v_mov_b32_e32 v4, v124
	v_mov_b32_e32 v5, v125
	v_mov_b32_e32 v6, v126
	v_mov_b32_e32 v7, v127
	v_pk_mul_f32 v[2:3], v[6:7], s[90:91] op_sel_hi:[1,0]
	v_lshl_add_u32 v6, v10, 2, 0
	v_lshrrev_b32_e32 v7, 2, v10
	v_lshrrev_b32_e32 v10, 6, v10
	v_and_b32_e32 v7, 0xffc, v7
	v_and_b32_e32 v10, 0xfc, v10
	v_add3_u32 v10, v6, v7, v10
	ds_read_b32 v7, v10
	v_pk_mul_f32 v[4:5], v[4:5], s[90:91] op_sel_hi:[1,0]
	s_waitcnt lgkmcnt(0)
	v_cvt_f32_f16_e32 v6, v7
	v_cvt_f32_f16_sdwa v7, v7 dst_sel:DWORD dst_unused:UNUSED_PAD src0_sel:WORD_1
	s_and_saveexec_b64 s[22:23], s[40:41]
	s_xor_b64 s[22:23], exec, s[22:23]
	s_cbranch_execz .LBB0_740
	v_add_u32_e32 v11, 0x200, v8
	v_bfrev_b32_e32 v11, v11
	v_lshrrev_b32_e32 v13, 19, v11
	v_lshrrev_b32_e32 v11, 17, v11
	v_and_b32_e32 v11, 0x2aaa, v11
	v_and_or_b32 v11, v13, s89, v11
	v_lshl_add_u32 v13, v11, 2, 0
	v_lshrrev_b32_e32 v16, 2, v11
	v_lshrrev_b32_e32 v11, 6, v11
	v_and_b32_e32 v16, 0xffc, v16
	v_and_b32_e32 v11, 0xfc, v11
	v_add3_u32 v11, v13, v16, v11
	ds_read_b32 v13, v11
	v_pk_mul_f32 v[18:19], v[6:7], v[4:5] op_sel:[0,0] op_sel_hi:[0,1]
	s_waitcnt lgkmcnt(0)
	v_cvt_f32_f16_e32 v16, v13
	v_cvt_f32_f16_sdwa v17, -v13 dst_sel:DWORD dst_unused:UNUSED_PAD src0_sel:WORD_1
	v_pk_mul_f32 v[22:23], v[16:17], v[2:3] op_sel:[0,0] op_sel_hi:[0,1]
	v_pk_fma_f32 v[18:19], v[6:7], v[4:5], v[18:19] op_sel:[1,1,0] op_sel_hi:[1,0,1] neg_lo:[0,1,0]
	v_pk_fma_f32 v[22:23], v[16:17], v[2:3], v[22:23] op_sel:[1,1,0] op_sel_hi:[1,0,1] neg_lo:[0,1,0]
	v_pk_add_f32 v[18:19], v[18:19], v[22:23]
	v_pk_mul_f32 v[22:23], v[16:17], v[4:5] op_sel:[0,0] op_sel_hi:[0,1]
	v_pk_fma_f32 v[4:5], v[16:17], v[4:5], v[22:23] op_sel:[1,1,0] op_sel_hi:[1,0,1] neg_lo:[0,1,0]
	v_pk_mul_f32 v[16:17], v[6:7], v[2:3] op_sel:[0,0] op_sel_hi:[0,1]
	v_pk_fma_f32 v[2:3], v[6:7], v[2:3], v[16:17] op_sel:[1,1,0] op_sel_hi:[1,0,1] neg_lo:[0,1,0]
	s_nop 0
	v_pk_add_f32 v[2:3], v[4:5], v[2:3]
	v_cvt_pk_f16_f32 v4, v18, v19
	v_cvt_pk_f16_f32 v2, v2, -v3
	ds_write_b32 v10, v4
	ds_write_b32 v11, v2

; DI int rev4(int pp) { const unsigned br = __brev((unsigned)pp) >> 18; return (int)(((br & 0x2AAAu) >> 1) | ((br & 0x1555u) << 1)); }
; DI void pw_h(LAS hc* X, const f32x4* spec, int tid) {
;     ...
;     for (int r = 0; r < 16; ++r) {
;         const int k = tid + NTHR * r; const int pp = rev4(k);
;         const f32x4 sp = spec[k]; const cf P = (cf){sp[0], sp[1]} * 256.0f, Mq = (cf){sp[2], sp[3]} * 256.0f;
;         const hc zh = X[XI(pp)]; const cf z = (cf){(float)zh.x, (float)zh.y};
;         if (k == 0) { const cf y = cmul(z, P) + cmul((cf){z.x, -z.y}, Mq); X[XI(pp)] = (hc){(_Float16)y.x, (_Float16)y.y}; }
;         else { const int pm = rev4(16384 - k); const hc zmh = X[XI(pm)]; const cf zm = (cf){(float)zmh.x, (float)zmh.y};
;             const cf y = cmul(z, P) + cmul((cf){zm.x, -zm.y}, Mq);
;             const cf t = cmul((cf){zm.x, -zm.y}, P) + cmul(z, Mq);
;             X[XI(pp)] = (hc){(_Float16)y.x, (_Float16)y.y}; X[XI(pm)] = (hc){(_Float16)t.x, (_Float16)(-t.y)}; }
;     }
.LBB0_742:
	s_or_b64 exec, exec, s[22:23]
	v_add_u32_e32 v2, 0x2e00, v9
	v_bfrev_b32_e32 v3, v2
	v_lshrrev_b32_e32 v4, 19, v3
	v_lshrrev_b32_e32 v3, 17, v3
	v_and_b32_e32 v3, 0x2aaa, v3
	v_and_or_b32 v10, v4, s89, v3
	v_cmp_ne_u32_e64 s[40:41], s84, v9
	s_waitcnt vmcnt(8)
	v_mov_b32_e32 v4, v128
	v_mov_b32_e32 v5, v129
	v_mov_b32_e32 v6, v130
	v_mov_b32_e32 v7, v131
	v_pk_mul_f32 v[2:3], v[6:7], s[90:91] op_sel_hi:[1,0]
	v_lshl_add_u32 v6, v10, 2, 0
	v_lshrrev_b32_e32 v7, 2, v10
	v_lshrrev_b32_e32 v10, 6, v10
	v_and_b32_e32 v7, 0xffc, v7
	v_and_b32_e32 v10, 0xfc, v10
	v_add3_u32 v10, v6, v7, v10
	ds_read_b32 v7, v10
	v_pk_mul_f32 v[4:5], v[4:5], s[90:91] op_sel_hi:[1,0]
	s_waitcnt lgkmcnt(0)
	v_cvt_f32_f16_e32 v6, v7
	v_cvt_f32_f16_sdwa v7, v7 dst_sel:DWORD dst_unused:UNUSED_PAD src0_sel:WORD_1
	s_and_saveexec_b64 s[22:23], s[40:41]
	s_xor_b64 s[22:23], exec, s[22:23]
	s_cbranch_execz .LBB0_744
	v_bfrev_b32_e32 v9, v8
	v_lshrrev_b32_e32 v11, 19, v9
	v_lshrrev_b32_e32 v9, 17, v9
	v_and_b32_e32 v9, 0x2aaa, v9
	v_and_or_b32 v9, v11, s89, v9
	v_lshl_add_u32 v11, v9, 2, 0
	v_lshrrev_b32_e32 v13, 2, v9
	v_lshrrev_b32_e32 v9, 6, v9
	v_and_b32_e32 v13, 0xffc, v13
	v_and_b32_e32 v9, 0xfc, v9
	v_add3_u32 v9, v11, v13, v9
	ds_read_b32 v11, v9
	v_pk_mul_f32 v[18:19], v[6:7], v[4:5] op_sel:[0,0] op_sel_hi:[0,1]
	s_waitcnt lgkmcnt(0)
	v_cvt_f32_f16_e32 v16, v11
	v_cvt_f32_f16_sdwa v17, -v11 dst_sel:DWORD dst_unused:UNUSED_PAD src0_sel:WORD_1
	v_pk_mul_f32 v[22:23], v[16:17], v[2:3] op_sel:[0,0] op_sel_hi:[0,1]
	v_pk_fma_f32 v[18:19], v[6:7], v[4:5], v[18:19] op_sel:[1,1,0] op_sel_hi:[1,0,1] neg_lo:[0,1,0]
	v_pk_fma_f32 v[22:23], v[16:17], v[2:3], v[22:23] op_sel:[1,1,0] op_sel_hi:[1,0,1] neg_lo:[0,1,0]
	v_pk_add_f32 v[18:19], v[18:19], v[22:23]
	v_pk_mul_f32 v[22:23], v[16:17], v[4:5] op_sel:[0,0] op_sel_hi:[0,1]
	v_pk_fma_f32 v[4:5], v[16:17], v[4:5], v[22:23] op_sel:[1,1,0] op_sel_hi:[1,0,1] neg_lo:[0,1,0]
	v_pk_mul_f32 v[16:17], v[6:7], v[2:3] op_sel:[0,0] op_sel_hi:[0,1]
	v_pk_fma_f32 v[2:3], v[6:7], v[2:3], v[16:17] op_sel:[1,1,0] op_sel_hi:[1,0,1] neg_lo:[0,1,0]
	s_nop 0
	v_pk_add_f32 v[2:3], v[4:5], v[2:3]
	v_cvt_pk_f16_f32 v4, v18, v19
	v_cvt_pk_f16_f32 v2, v2, -v3
	ds_write_b32 v10, v4
	ds_write_b32 v9, v2

; DI int rev4(int pp) { const unsigned br = __brev((unsigned)pp) >> 18; return (int)(((br & 0x2AAAu) >> 1) | ((br & 0x1555u) << 1)); }
; DI void pw_h(LAS hc* X, const f32x4* spec, int tid) {
;     ...
;     if (tid == 0) { const int pp = rev4(8192); const f32x4 sp = spec[8192]; const hc zh = X[XI(pp)]; const cf z = (cf){(float)zh.x, (float)zh.y};
;         const cf y = (cmul(z, (cf){sp[0], sp[1]}) + cmul((cf){z.x, -z.y}, (cf){sp[2], sp[3]})) * 256.0f; X[XI(pp)] = (hc){(_Float16)y.x, (_Float16)y.y}; }
.LBB0_746:
	s_and_saveexec_b64 s[22:23], vcc
	s_cbranch_execz .LBB0_748
	ds_read_b32 v5, v97 offset:8
	v_mov_b32_e32 v0, v132
	v_mov_b32_e32 v1, v133
	v_mov_b32_e32 v2, v134
	v_mov_b32_e32 v3, v135
	s_waitcnt lgkmcnt(0)
	v_cvt_f32_f16_e32 v4, v5
	v_cvt_f32_f16_sdwa v5, v5 dst_sel:DWORD dst_unused:UNUSED_PAD src0_sel:WORD_1
	s_waitcnt vmcnt(0)
	v_pk_mul_f32 v[6:7], v[4:5], v[0:1] op_sel:[0,0] op_sel_hi:[0,1]
	v_pk_fma_f32 v[0:1], v[4:5], v[0:1], v[6:7] op_sel:[1,1,0] op_sel_hi:[1,0,1] neg_lo:[0,1,0]
	v_xor_b32_e32 v5, 0x80000000, v5
	v_pk_mul_f32 v[6:7], v[4:5], v[2:3] op_sel:[0,0] op_sel_hi:[0,1]
	v_pk_fma_f32 v[2:3], v[4:5], v[2:3], v[6:7] op_sel:[1,1,0] op_sel_hi:[1,0,1] neg_lo:[0,1,0]
	v_pk_add_f32 v[0:1], v[0:1], v[2:3]
	s_nop 0
	v_pk_mul_f32 v[0:1], v[0:1], s[90:91] op_sel_hi:[1,0]
	s_nop 0
	v_cvt_pk_f16_f32 v0, v0, v1
	ds_write_b32 v97, v0 offset:8

; DI int rev4(int pp) { const unsigned br = __brev((unsigned)pp) >> 18; return (int)(((br & 0x2AAAu) >> 1) | ((br & 0x1555u) << 1)); }
; DI void pw_h(LAS hc* X, const f32x4* spec, int tid) {
;     ...
;     for (int r = 0; r < 16; ++r) {
;         const int k = tid + NTHR * r; const int pp = rev4(k);
;         const f32x4 sp = spec[k]; const cf P = (cf){sp[0], sp[1]} * 256.0f, Mq = (cf){sp[2], sp[3]} * 256.0f;
;         const hc zh = X[XI(pp)]; const cf z = (cf){(float)zh.x, (float)zh.y};
;         if (k == 0) { const cf y = cmul(z, P) + cmul((cf){z.x, -z.y}, Mq); X[XI(pp)] = (hc){(_Float16)y.x, (_Float16)y.y}; }
;         else { const int pm = rev4(16384 - k); const hc zmh = X[XI(pm)]; const cf zm = (cf){(float)zmh.x, (float)zmh.y};
;             const cf y = cmul(z, P) + cmul((cf){zm.x, -zm.y}, Mq);
;             const cf t = cmul((cf){zm.x, -zm.y}, P) + cmul(z, Mq);
;             X[XI(pp)] = (hc){(_Float16)y.x, (_Float16)y.y}; X[XI(pm)] = (hc){(_Float16)t.x, (_Float16)(-t.y)}; }
;     }
.LBB0_750:
	global_load_dwordx4 v[132:135], v224, s[20:21]
	global_load_dwordx4 v[4:7], v[0:1], off
	v_add_u32_e32 v8, s4, v12
	v_add_u32_e32 v2, 0x2000, v8
	v_bfrev_b32_e32 v2, v2
	v_lshrrev_b32_e32 v3, 19, v2
	v_lshrrev_b32_e32 v2, 17, v2
	v_and_b32_e32 v2, 0x2aaa, v2
	v_and_or_b32 v9, v3, s89, v2
	s_movk_i32 s5, 0xe000
	v_cmp_ne_u32_e64 s[40:41], s5, v8
	v_add_u32_e32 v100, 0x2200, v8
	v_ashrrev_i32_e32 v101, 31, v100
	v_lshl_add_u64 v[100:101], v[100:101], 4, s[20:21]
	global_load_dwordx4 v[104:107], v[100:101], off
	v_add_u32_e32 v100, 0x2400, v8
	v_ashrrev_i32_e32 v101, 31, v100
	v_lshl_add_u64 v[100:101], v[100:101], 4, s[20:21]
	global_load_dwordx4 v[108:111], v[100:101], off
	v_add_u32_e32 v100, 0x2600, v8
	v_ashrrev_i32_e32 v101, 31, v100
	v_lshl_add_u64 v[100:101], v[100:101], 4, s[20:21]
	global_load_dwordx4 v[112:115], v[100:101], off
	v_add_u32_e32 v100, 0x2800, v8
	v_ashrrev_i32_e32 v101, 31, v100
	v_lshl_add_u64 v[100:101], v[100:101], 4, s[20:21]
	global_load_dwordx4 v[116:119], v[100:101], off
	v_add_u32_e32 v100, 0x2a00, v8
	v_ashrrev_i32_e32 v101, 31, v100
	v_lshl_add_u64 v[100:101], v[100:101], 4, s[20:21]
	global_load_dwordx4 v[120:123], v[100:101], off
	v_add_u32_e32 v100, 0x2c00, v8
	v_ashrrev_i32_e32 v101, 31, v100
	v_lshl_add_u64 v[100:101], v[100:101], 4, s[20:21]
	global_load_dwordx4 v[124:127], v[100:101], off
	v_add_u32_e32 v100, 0x2e00, v8
	v_ashrrev_i32_e32 v101, 31, v100
	v_lshl_add_u64 v[100:101], v[100:101], 4, s[20:21]
	global_load_dwordx4 v[128:131], v[100:101], off
	v_add_u32_e32 v100, 0x3000, v8
	v_ashrrev_i32_e32 v101, 31, v100
	v_lshl_add_u64 v[100:101], v[100:101], 4, s[20:21]
	global_load_dword v136, v[100:101], off
	v_add_u32_e32 v100, 0x3200, v8
	v_ashrrev_i32_e32 v101, 31, v100
	v_lshl_add_u64 v[100:101], v[100:101], 4, s[20:21]
	global_load_dword v137, v[100:101], off
	v_add_u32_e32 v100, 0x3400, v8
	v_ashrrev_i32_e32 v101, 31, v100
	v_lshl_add_u64 v[100:101], v[100:101], 4, s[20:21]
	global_load_dword v138, v[100:101], off
	v_add_u32_e32 v100, 0x3600, v8
	v_ashrrev_i32_e32 v101, 31, v100
	v_lshl_add_u64 v[100:101], v[100:101], 4, s[20:21]
	global_load_dword v139, v[100:101], off
	v_add_u32_e32 v100, 0x3800, v8
	v_ashrrev_i32_e32 v101, 31, v100
	v_lshl_add_u64 v[100:101], v[100:101], 4, s[20:21]
	global_load_dword v140, v[100:101], off
	v_add_u32_e32 v100, 0x3a00, v8
	v_ashrrev_i32_e32 v101, 31, v100
	v_lshl_add_u64 v[100:101], v[100:101], 4, s[20:21]
	global_load_dword v141, v[100:101], off
	v_add_u32_e32 v100, 0x3c00, v8
	v_ashrrev_i32_e32 v101, 31, v100
	v_lshl_add_u64 v[100:101], v[100:101], 4, s[20:21]
	global_load_dword v142, v[100:101], off
	v_add_u32_e32 v100, 0x3e00, v8
	v_ashrrev_i32_e32 v101, 31, v100
	v_lshl_add_u64 v[100:101], v[100:101], 4, s[20:21]
	global_load_dword v143, v[100:101], off
	s_waitcnt vmcnt(15)
	v_pk_mul_f32 v[2:3], v[6:7], s[90:91] op_sel_hi:[1,0]
	v_lshl_add_u32 v6, v9, 2, s66
	v_lshrrev_b32_e32 v7, 2, v9
	v_lshrrev_b32_e32 v9, 6, v9
	v_and_b32_e32 v7, 0xffc, v7
	v_and_b32_e32 v9, 0xfc, v9
	v_add3_u32 v9, v6, v7, v9
	ds_read_b32 v7, v9
	v_pk_mul_f32 v[4:5], v[4:5], s[90:91] op_sel_hi:[1,0]
	s_waitcnt lgkmcnt(0)
	v_cvt_f32_f16_e32 v6, v7
	v_cvt_f32_f16_sdwa v7, v7 dst_sel:DWORD dst_unused:UNUSED_PAD src0_sel:WORD_1
	s_and_saveexec_b64 s[6:7], s[40:41]
	s_xor_b64 s[22:23], exec, s[6:7]
	s_cbranch_execz .LBB0_752
	v_add_u32_e32 v10, 0xe00, v20
	v_bfrev_b32_e32 v10, v10
	v_lshrrev_b32_e32 v11, 19, v10
	v_lshrrev_b32_e32 v10, 17, v10
	v_and_b32_e32 v10, 0x2aaa, v10
	v_and_or_b32 v10, v11, s89, v10
	v_lshl_add_u32 v11, v10, 2, s66
	v_lshrrev_b32_e32 v13, 2, v10
	v_lshrrev_b32_e32 v10, 6, v10
	v_and_b32_e32 v13, 0xffc, v13
	v_and_b32_e32 v10, 0xfc, v10
	v_add3_u32 v13, v11, v13, v10
	ds_read_b32 v11, v13
	v_pk_mul_f32 v[14:15], v[6:7], v[4:5] op_sel:[0,0] op_sel_hi:[0,1]
	s_waitcnt lgkmcnt(0)
	v_cvt_f32_f16_e32 v10, v11
	v_cvt_f32_f16_sdwa v11, -v11 dst_sel:DWORD dst_unused:UNUSED_PAD src0_sel:WORD_1
	v_pk_mul_f32 v[16:17], v[10:11], v[2:3] op_sel:[0,0] op_sel_hi:[0,1]
	v_pk_fma_f32 v[14:15], v[6:7], v[4:5], v[14:15] op_sel:[1,1,0] op_sel_hi:[1,0,1] neg_lo:[0,1,0]
	v_pk_fma_f32 v[16:17], v[10:11], v[2:3], v[16:17] op_sel:[1,1,0] op_sel_hi:[1,0,1] neg_lo:[0,1,0]
	v_pk_add_f32 v[14:15], v[14:15], v[16:17]
	v_pk_mul_f32 v[16:17], v[10:11], v[4:5] op_sel:[0,0] op_sel_hi:[0,1]
	v_pk_fma_f32 v[4:5], v[10:11], v[4:5], v[16:17] op_sel:[1,1,0] op_sel_hi:[1,0,1] neg_lo:[0,1,0]
	v_pk_mul_f32 v[10:11], v[6:7], v[2:3] op_sel:[0,0] op_sel_hi:[0,1]
	v_pk_fma_f32 v[2:3], v[6:7], v[2:3], v[10:11] op_sel:[1,1,0] op_sel_hi:[1,0,1] neg_lo:[0,1,0]
	s_nop 0
	v_pk_add_f32 v[2:3], v[4:5], v[2:3]
	v_cvt_pk_f16_f32 v4, v14, v15
	v_cvt_pk_f16_f32 v2, v2, -v3
	ds_write_b32 v9, v4
	ds_write_b32 v13, v2

; DI int rev4(int pp) { const unsigned br = __brev((unsigned)pp) >> 18; return (int)(((br & 0x2AAAu) >> 1) | ((br & 0x1555u) << 1)); }
; DI void pw_h(LAS hc* X, const f32x4* spec, int tid) {
;     ...
;     for (int r = 0; r < 16; ++r) {
;         const int k = tid + NTHR * r; const int pp = rev4(k);
;         const f32x4 sp = spec[k]; const cf P = (cf){sp[0], sp[1]} * 256.0f, Mq = (cf){sp[2], sp[3]} * 256.0f;
;         const hc zh = X[XI(pp)]; const cf z = (cf){(float)zh.x, (float)zh.y};
;         if (k == 0) { const cf y = cmul(z, P) + cmul((cf){z.x, -z.y}, Mq); X[XI(pp)] = (hc){(_Float16)y.x, (_Float16)y.y}; }
;         else { const int pm = rev4(16384 - k); const hc zmh = X[XI(pm)]; const cf zm = (cf){(float)zmh.x, (float)zmh.y};
;             const cf y = cmul(z, P) + cmul((cf){zm.x, -zm.y}, Mq);
;             const cf t = cmul((cf){zm.x, -zm.y}, P) + cmul(z, Mq);
;             X[XI(pp)] = (hc){(_Float16)y.x, (_Float16)y.y}; X[XI(pm)] = (hc){(_Float16)t.x, (_Float16)(-t.y)}; }
;     }
.LBB0_754:
	s_or_b64 exec, exec, s[22:23]
	v_add_u32_e32 v2, 0x2200, v8
	v_bfrev_b32_e32 v3, v2
	v_lshrrev_b32_e32 v4, 19, v3
	v_lshrrev_b32_e32 v3, 17, v3
	v_and_b32_e32 v3, 0x2aaa, v3
	v_and_or_b32 v9, v4, s89, v3
	s_movk_i32 s5, 0xde00
	v_cmp_ne_u32_e64 s[40:41], s5, v8
	s_waitcnt vmcnt(14)
	v_mov_b32_e32 v4, v104
	v_mov_b32_e32 v5, v105
	v_mov_b32_e32 v6, v106
	v_mov_b32_e32 v7, v107
	v_pk_mul_f32 v[2:3], v[6:7], s[90:91] op_sel_hi:[1,0]
	v_lshl_add_u32 v6, v9, 2, s66
	v_lshrrev_b32_e32 v7, 2, v9
	v_lshrrev_b32_e32 v9, 6, v9
	v_and_b32_e32 v7, 0xffc, v7
	v_and_b32_e32 v9, 0xfc, v9
	v_add3_u32 v9, v6, v7, v9
	ds_read_b32 v7, v9
	v_pk_mul_f32 v[4:5], v[4:5], s[90:91] op_sel_hi:[1,0]
	s_waitcnt lgkmcnt(0)
	v_cvt_f32_f16_e32 v6, v7
	v_cvt_f32_f16_sdwa v7, v7 dst_sel:DWORD dst_unused:UNUSED_PAD src0_sel:WORD_1
	s_and_saveexec_b64 s[6:7], s[40:41]
	s_xor_b64 s[22:23], exec, s[6:7]
	s_cbranch_execz .LBB0_756
	v_add_u32_e32 v10, 0xc00, v20
	v_bfrev_b32_e32 v10, v10
	v_lshrrev_b32_e32 v11, 19, v10
	v_lshrrev_b32_e32 v10, 17, v10
	v_and_b32_e32 v10, 0x2aaa, v10
	v_and_or_b32 v10, v11, s89, v10
	v_lshl_add_u32 v11, v10, 2, s66
	v_lshrrev_b32_e32 v13, 2, v10
	v_lshrrev_b32_e32 v10, 6, v10
	v_and_b32_e32 v13, 0xffc, v13
	v_and_b32_e32 v10, 0xfc, v10
	v_add3_u32 v13, v11, v13, v10
	ds_read_b32 v11, v13
	v_pk_mul_f32 v[14:15], v[6:7], v[4:5] op_sel:[0,0] op_sel_hi:[0,1]
	s_waitcnt lgkmcnt(0)
	v_cvt_f32_f16_e32 v10, v11
	v_cvt_f32_f16_sdwa v11, -v11 dst_sel:DWORD dst_unused:UNUSED_PAD src0_sel:WORD_1
	v_pk_mul_f32 v[16:17], v[10:11], v[2:3] op_sel:[0,0] op_sel_hi:[0,1]
	v_pk_fma_f32 v[14:15], v[6:7], v[4:5], v[14:15] op_sel:[1,1,0] op_sel_hi:[1,0,1] neg_lo:[0,1,0]
	v_pk_fma_f32 v[16:17], v[10:11], v[2:3], v[16:17] op_sel:[1,1,0] op_sel_hi:[1,0,1] neg_lo:[0,1,0]
	v_pk_add_f32 v[14:15], v[14:15], v[16:17]
	v_pk_mul_f32 v[16:17], v[10:11], v[4:5] op_sel:[0,0] op_sel_hi:[0,1]
	v_pk_fma_f32 v[4:5], v[10:11], v[4:5], v[16:17] op_sel:[1,1,0] op_sel_hi:[1,0,1] neg_lo:[0,1,0]
	v_pk_mul_f32 v[10:11], v[6:7], v[2:3] op_sel:[0,0] op_sel_hi:[0,1]
	v_pk_fma_f32 v[2:3], v[6:7], v[2:3], v[10:11] op_sel:[1,1,0] op_sel_hi:[1,0,1] neg_lo:[0,1,0]
	s_nop 0
	v_pk_add_f32 v[2:3], v[4:5], v[2:3]
	v_cvt_pk_f16_f32 v4, v14, v15
	v_cvt_pk_f16_f32 v2, v2, -v3
	ds_write_b32 v9, v4
	ds_write_b32 v13, v2

; DI int rev4(int pp) { const unsigned br = __brev((unsigned)pp) >> 18; return (int)(((br & 0x2AAAu) >> 1) | ((br & 0x1555u) << 1)); }
; DI void pw_h(LAS hc* X, const f32x4* spec, int tid) {
;     ...
;     for (int r = 0; r < 16; ++r) {
;         const int k = tid + NTHR * r; const int pp = rev4(k);
;         const f32x4 sp = spec[k]; const cf P = (cf){sp[0], sp[1]} * 256.0f, Mq = (cf){sp[2], sp[3]} * 256.0f;
;         const hc zh = X[XI(pp)]; const cf z = (cf){(float)zh.x, (float)zh.y};
;         if (k == 0) { const cf y = cmul(z, P) + cmul((cf){z.x, -z.y}, Mq); X[XI(pp)] = (hc){(_Float16)y.x, (_Float16)y.y}; }
;         else { const int pm = rev4(16384 - k); const hc zmh = X[XI(pm)]; const cf zm = (cf){(float)zmh.x, (float)zmh.y};
;             const cf y = cmul(z, P) + cmul((cf){zm.x, -zm.y}, Mq);
;             const cf t = cmul((cf){zm.x, -zm.y}, P) + cmul(z, Mq);
;             X[XI(pp)] = (hc){(_Float16)y.x, (_Float16)y.y}; X[XI(pm)] = (hc){(_Float16)t.x, (_Float16)(-t.y)}; }
;     }
.LBB0_758:
	s_or_b64 exec, exec, s[22:23]
	v_add_u32_e32 v2, 0x2400, v8
	v_bfrev_b32_e32 v3, v2
	v_lshrrev_b32_e32 v4, 19, v3
	v_lshrrev_b32_e32 v3, 17, v3
	v_and_b32_e32 v3, 0x2aaa, v3
	v_and_or_b32 v9, v4, s89, v3
	s_movk_i32 s5, 0xdc00
	v_cmp_ne_u32_e64 s[40:41], s5, v8
	s_waitcnt vmcnt(13)
	v_mov_b32_e32 v4, v108
	v_mov_b32_e32 v5, v109
	v_mov_b32_e32 v6, v110
	v_mov_b32_e32 v7, v111
	v_pk_mul_f32 v[2:3], v[6:7], s[90:91] op_sel_hi:[1,0]
	v_lshl_add_u32 v6, v9, 2, s66
	v_lshrrev_b32_e32 v7, 2, v9
	v_lshrrev_b32_e32 v9, 6, v9
	v_and_b32_e32 v7, 0xffc, v7
	v_and_b32_e32 v9, 0xfc, v9
	v_add3_u32 v9, v6, v7, v9
	ds_read_b32 v7, v9
	v_pk_mul_f32 v[4:5], v[4:5], s[90:91] op_sel_hi:[1,0]
	s_waitcnt lgkmcnt(0)
	v_cvt_f32_f16_e32 v6, v7
	v_cvt_f32_f16_sdwa v7, v7 dst_sel:DWORD dst_unused:UNUSED_PAD src0_sel:WORD_1
	s_and_saveexec_b64 s[6:7], s[40:41]
	s_xor_b64 s[22:23], exec, s[6:7]
	s_cbranch_execz .LBB0_760
	v_add_u32_e32 v10, 0xa00, v20
	v_bfrev_b32_e32 v10, v10
	v_lshrrev_b32_e32 v11, 19, v10
	v_lshrrev_b32_e32 v10, 17, v10
	v_and_b32_e32 v10, 0x2aaa, v10
	v_and_or_b32 v10, v11, s89, v10
	v_lshl_add_u32 v11, v10, 2, s66
	v_lshrrev_b32_e32 v13, 2, v10
	v_lshrrev_b32_e32 v10, 6, v10
	v_and_b32_e32 v13, 0xffc, v13
	v_and_b32_e32 v10, 0xfc, v10
	v_add3_u32 v13, v11, v13, v10
	ds_read_b32 v11, v13
	v_pk_mul_f32 v[14:15], v[6:7], v[4:5] op_sel:[0,0] op_sel_hi:[0,1]
	s_waitcnt lgkmcnt(0)
	v_cvt_f32_f16_e32 v10, v11
	v_cvt_f32_f16_sdwa v11, -v11 dst_sel:DWORD dst_unused:UNUSED_PAD src0_sel:WORD_1
	v_pk_mul_f32 v[16:17], v[10:11], v[2:3] op_sel:[0,0] op_sel_hi:[0,1]
	v_pk_fma_f32 v[14:15], v[6:7], v[4:5], v[14:15] op_sel:[1,1,0] op_sel_hi:[1,0,1] neg_lo:[0,1,0]
	v_pk_fma_f32 v[16:17], v[10:11], v[2:3], v[16:17] op_sel:[1,1,0] op_sel_hi:[1,0,1] neg_lo:[0,1,0]
	v_pk_add_f32 v[14:15], v[14:15], v[16:17]
	v_pk_mul_f32 v[16:17], v[10:11], v[4:5] op_sel:[0,0] op_sel_hi:[0,1]
	v_pk_fma_f32 v[4:5], v[10:11], v[4:5], v[16:17] op_sel:[1,1,0] op_sel_hi:[1,0,1] neg_lo:[0,1,0]
	v_pk_mul_f32 v[10:11], v[6:7], v[2:3] op_sel:[0,0] op_sel_hi:[0,1]
	v_pk_fma_f32 v[2:3], v[6:7], v[2:3], v[10:11] op_sel:[1,1,0] op_sel_hi:[1,0,1] neg_lo:[0,1,0]
	s_nop 0
	v_pk_add_f32 v[2:3], v[4:5], v[2:3]
	v_cvt_pk_f16_f32 v4, v14, v15
	v_cvt_pk_f16_f32 v2, v2, -v3
	ds_write_b32 v9, v4
	ds_write_b32 v13, v2

; DI int rev4(int pp) { const unsigned br = __brev((unsigned)pp) >> 18; return (int)(((br & 0x2AAAu) >> 1) | ((br & 0x1555u) << 1)); }
; DI void pw_h(LAS hc* X, const f32x4* spec, int tid) {
;     ...
;     for (int r = 0; r < 16; ++r) {
;         const int k = tid + NTHR * r; const int pp = rev4(k);
;         const f32x4 sp = spec[k]; const cf P = (cf){sp[0], sp[1]} * 256.0f, Mq = (cf){sp[2], sp[3]} * 256.0f;
;         const hc zh = X[XI(pp)]; const cf z = (cf){(float)zh.x, (float)zh.y};
;         if (k == 0) { const cf y = cmul(z, P) + cmul((cf){z.x, -z.y}, Mq); X[XI(pp)] = (hc){(_Float16)y.x, (_Float16)y.y}; }
;         else { const int pm = rev4(16384 - k); const hc zmh = X[XI(pm)]; const cf zm = (cf){(float)zmh.x, (float)zmh.y};
;             const cf y = cmul(z, P) + cmul((cf){zm.x, -zm.y}, Mq);
;             const cf t = cmul((cf){zm.x, -zm.y}, P) + cmul(z, Mq);
;             X[XI(pp)] = (hc){(_Float16)y.x, (_Float16)y.y}; X[XI(pm)] = (hc){(_Float16)t.x, (_Float16)(-t.y)}; }
;     }
.LBB0_762:
	s_or_b64 exec, exec, s[22:23]
	v_add_u32_e32 v2, 0x2600, v8
	v_bfrev_b32_e32 v3, v2
	v_lshrrev_b32_e32 v4, 19, v3
	v_lshrrev_b32_e32 v3, 17, v3
	v_and_b32_e32 v3, 0x2aaa, v3
	v_and_or_b32 v9, v4, s89, v3
	s_movk_i32 s5, 0xda00
	v_cmp_ne_u32_e64 s[40:41], s5, v8
	s_waitcnt vmcnt(12)
	v_mov_b32_e32 v4, v112
	v_mov_b32_e32 v5, v113
	v_mov_b32_e32 v6, v114
	v_mov_b32_e32 v7, v115
	v_pk_mul_f32 v[2:3], v[6:7], s[90:91] op_sel_hi:[1,0]
	v_lshl_add_u32 v6, v9, 2, s66
	v_lshrrev_b32_e32 v7, 2, v9
	v_lshrrev_b32_e32 v9, 6, v9
	v_and_b32_e32 v7, 0xffc, v7
	v_and_b32_e32 v9, 0xfc, v9
	v_add3_u32 v9, v6, v7, v9
	ds_read_b32 v7, v9
	v_pk_mul_f32 v[4:5], v[4:5], s[90:91] op_sel_hi:[1,0]
	s_waitcnt lgkmcnt(0)
	v_cvt_f32_f16_e32 v6, v7
	v_cvt_f32_f16_sdwa v7, v7 dst_sel:DWORD dst_unused:UNUSED_PAD src0_sel:WORD_1
	s_and_saveexec_b64 s[6:7], s[40:41]
	s_xor_b64 s[22:23], exec, s[6:7]
	s_cbranch_execz .LBB0_764
	v_add_u32_e32 v10, 0x800, v20
	v_bfrev_b32_e32 v10, v10
	v_lshrrev_b32_e32 v11, 19, v10
	v_lshrrev_b32_e32 v10, 17, v10
	v_and_b32_e32 v10, 0x2aaa, v10
	v_and_or_b32 v10, v11, s89, v10
	v_lshl_add_u32 v11, v10, 2, s66
	v_lshrrev_b32_e32 v13, 2, v10
	v_lshrrev_b32_e32 v10, 6, v10
	v_and_b32_e32 v13, 0xffc, v13
	v_and_b32_e32 v10, 0xfc, v10
	v_add3_u32 v13, v11, v13, v10
	ds_read_b32 v11, v13
	v_pk_mul_f32 v[14:15], v[6:7], v[4:5] op_sel:[0,0] op_sel_hi:[0,1]
	s_waitcnt lgkmcnt(0)
	v_cvt_f32_f16_e32 v10, v11
	v_cvt_f32_f16_sdwa v11, -v11 dst_sel:DWORD dst_unused:UNUSED_PAD src0_sel:WORD_1
	v_pk_mul_f32 v[16:17], v[10:11], v[2:3] op_sel:[0,0] op_sel_hi:[0,1]
	v_pk_fma_f32 v[14:15], v[6:7], v[4:5], v[14:15] op_sel:[1,1,0] op_sel_hi:[1,0,1] neg_lo:[0,1,0]
	v_pk_fma_f32 v[16:17], v[10:11], v[2:3], v[16:17] op_sel:[1,1,0] op_sel_hi:[1,0,1] neg_lo:[0,1,0]
	v_pk_add_f32 v[14:15], v[14:15], v[16:17]
	v_pk_mul_f32 v[16:17], v[10:11], v[4:5] op_sel:[0,0] op_sel_hi:[0,1]
	v_pk_fma_f32 v[4:5], v[10:11], v[4:5], v[16:17] op_sel:[1,1,0] op_sel_hi:[1,0,1] neg_lo:[0,1,0]
	v_pk_mul_f32 v[10:11], v[6:7], v[2:3] op_sel:[0,0] op_sel_hi:[0,1]
	v_pk_fma_f32 v[2:3], v[6:7], v[2:3], v[10:11] op_sel:[1,1,0] op_sel_hi:[1,0,1] neg_lo:[0,1,0]
	s_nop 0
	v_pk_add_f32 v[2:3], v[4:5], v[2:3]
	v_cvt_pk_f16_f32 v4, v14, v15
	v_cvt_pk_f16_f32 v2, v2, -v3
	ds_write_b32 v9, v4
	ds_write_b32 v13, v2

; DI int rev4(int pp) { const unsigned br = __brev((unsigned)pp) >> 18; return (int)(((br & 0x2AAAu) >> 1) | ((br & 0x1555u) << 1)); }
; DI void pw_h(LAS hc* X, const f32x4* spec, int tid) {
;     ...
;     for (int r = 0; r < 16; ++r) {
;         const int k = tid + NTHR * r; const int pp = rev4(k);
;         const f32x4 sp = spec[k]; const cf P = (cf){sp[0], sp[1]} * 256.0f, Mq = (cf){sp[2], sp[3]} * 256.0f;
;         const hc zh = X[XI(pp)]; const cf z = (cf){(float)zh.x, (float)zh.y};
;         if (k == 0) { const cf y = cmul(z, P) + cmul((cf){z.x, -z.y}, Mq); X[XI(pp)] = (hc){(_Float16)y.x, (_Float16)y.y}; }
;         else { const int pm = rev4(16384 - k); const hc zmh = X[XI(pm)]; const cf zm = (cf){(float)zmh.x, (float)zmh.y};
;             const cf y = cmul(z, P) + cmul((cf){zm.x, -zm.y}, Mq);
;             const cf t = cmul((cf){zm.x, -zm.y}, P) + cmul(z, Mq);
;             X[XI(pp)] = (hc){(_Float16)y.x, (_Float16)y.y}; X[XI(pm)] = (hc){(_Float16)t.x, (_Float16)(-t.y)}; }
;     }
.LBB0_766:
	s_or_b64 exec, exec, s[22:23]
	v_add_u32_e32 v2, 0x2800, v8
	v_bfrev_b32_e32 v3, v2
	v_lshrrev_b32_e32 v4, 19, v3
	v_lshrrev_b32_e32 v3, 17, v3
	v_and_b32_e32 v3, 0x2aaa, v3
	v_and_or_b32 v9, v4, s89, v3
	s_movk_i32 s5, 0xd800
	v_cmp_ne_u32_e64 s[40:41], s5, v8
	s_waitcnt vmcnt(11)
	v_mov_b32_e32 v4, v116
	v_mov_b32_e32 v5, v117
	v_mov_b32_e32 v6, v118
	v_mov_b32_e32 v7, v119
	v_pk_mul_f32 v[2:3], v[6:7], s[90:91] op_sel_hi:[1,0]
	v_lshl_add_u32 v6, v9, 2, s66
	v_lshrrev_b32_e32 v7, 2, v9
	v_lshrrev_b32_e32 v9, 6, v9
	v_and_b32_e32 v7, 0xffc, v7
	v_and_b32_e32 v9, 0xfc, v9
	v_add3_u32 v9, v6, v7, v9
	ds_read_b32 v7, v9
	v_pk_mul_f32 v[4:5], v[4:5], s[90:91] op_sel_hi:[1,0]
	s_waitcnt lgkmcnt(0)
	v_cvt_f32_f16_e32 v6, v7
	v_cvt_f32_f16_sdwa v7, v7 dst_sel:DWORD dst_unused:UNUSED_PAD src0_sel:WORD_1
	s_and_saveexec_b64 s[6:7], s[40:41]
	s_xor_b64 s[22:23], exec, s[6:7]
	s_cbranch_execz .LBB0_768
	v_add_u32_e32 v10, 0x600, v20
	v_bfrev_b32_e32 v10, v10
	v_lshrrev_b32_e32 v11, 19, v10
	v_lshrrev_b32_e32 v10, 17, v10
	v_and_b32_e32 v10, 0x2aaa, v10
	v_and_or_b32 v10, v11, s89, v10
	v_lshl_add_u32 v11, v10, 2, s66
	v_lshrrev_b32_e32 v13, 2, v10
	v_lshrrev_b32_e32 v10, 6, v10
	v_and_b32_e32 v13, 0xffc, v13
	v_and_b32_e32 v10, 0xfc, v10
	v_add3_u32 v13, v11, v13, v10
	ds_read_b32 v11, v13
	v_pk_mul_f32 v[14:15], v[6:7], v[4:5] op_sel:[0,0] op_sel_hi:[0,1]
	s_waitcnt lgkmcnt(0)
	v_cvt_f32_f16_e32 v10, v11
	v_cvt_f32_f16_sdwa v11, -v11 dst_sel:DWORD dst_unused:UNUSED_PAD src0_sel:WORD_1
	v_pk_mul_f32 v[16:17], v[10:11], v[2:3] op_sel:[0,0] op_sel_hi:[0,1]
	v_pk_fma_f32 v[14:15], v[6:7], v[4:5], v[14:15] op_sel:[1,1,0] op_sel_hi:[1,0,1] neg_lo:[0,1,0]
	v_pk_fma_f32 v[16:17], v[10:11], v[2:3], v[16:17] op_sel:[1,1,0] op_sel_hi:[1,0,1] neg_lo:[0,1,0]
	v_pk_add_f32 v[14:15], v[14:15], v[16:17]
	v_pk_mul_f32 v[16:17], v[10:11], v[4:5] op_sel:[0,0] op_sel_hi:[0,1]
	v_pk_fma_f32 v[4:5], v[10:11], v[4:5], v[16:17] op_sel:[1,1,0] op_sel_hi:[1,0,1] neg_lo:[0,1,0]
	v_pk_mul_f32 v[10:11], v[6:7], v[2:3] op_sel:[0,0] op_sel_hi:[0,1]
	v_pk_fma_f32 v[2:3], v[6:7], v[2:3], v[10:11] op_sel:[1,1,0] op_sel_hi:[1,0,1] neg_lo:[0,1,0]
	s_nop 0
	v_pk_add_f32 v[2:3], v[4:5], v[2:3]
	v_cvt_pk_f16_f32 v4, v14, v15
	v_cvt_pk_f16_f32 v2, v2, -v3
	ds_write_b32 v9, v4
	ds_write_b32 v13, v2

; DI int rev4(int pp) { const unsigned br = __brev((unsigned)pp) >> 18; return (int)(((br & 0x2AAAu) >> 1) | ((br & 0x1555u) << 1)); }
; DI void pw_h(LAS hc* X, const f32x4* spec, int tid) {
;     ...
;     for (int r = 0; r < 16; ++r) {
;         const int k = tid + NTHR * r; const int pp = rev4(k);
;         const f32x4 sp = spec[k]; const cf P = (cf){sp[0], sp[1]} * 256.0f, Mq = (cf){sp[2], sp[3]} * 256.0f;
;         const hc zh = X[XI(pp)]; const cf z = (cf){(float)zh.x, (float)zh.y};
;         if (k == 0) { const cf y = cmul(z, P) + cmul((cf){z.x, -z.y}, Mq); X[XI(pp)] = (hc){(_Float16)y.x, (_Float16)y.y}; }
;         else { const int pm = rev4(16384 - k); const hc zmh = X[XI(pm)]; const cf zm = (cf){(float)zmh.x, (float)zmh.y};
;             const cf y = cmul(z, P) + cmul((cf){zm.x, -zm.y}, Mq);
;             const cf t = cmul((cf){zm.x, -zm.y}, P) + cmul(z, Mq);
;             X[XI(pp)] = (hc){(_Float16)y.x, (_Float16)y.y}; X[XI(pm)] = (hc){(_Float16)t.x, (_Float16)(-t.y)}; }
;     }
.LBB0_770:
	s_or_b64 exec, exec, s[22:23]
	v_add_u32_e32 v2, 0x2a00, v8
	v_bfrev_b32_e32 v3, v2
	v_lshrrev_b32_e32 v4, 19, v3
	v_lshrrev_b32_e32 v3, 17, v3
	v_and_b32_e32 v3, 0x2aaa, v3
	v_and_or_b32 v9, v4, s89, v3
	s_movk_i32 s5, 0xd600
	v_cmp_ne_u32_e64 s[40:41], s5, v8
	s_waitcnt vmcnt(10)
	v_mov_b32_e32 v4, v120
	v_mov_b32_e32 v5, v121
	v_mov_b32_e32 v6, v122
	v_mov_b32_e32 v7, v123
	v_pk_mul_f32 v[2:3], v[6:7], s[90:91] op_sel_hi:[1,0]
	v_lshl_add_u32 v6, v9, 2, s66
	v_lshrrev_b32_e32 v7, 2, v9
	v_lshrrev_b32_e32 v9, 6, v9
	v_and_b32_e32 v7, 0xffc, v7
	v_and_b32_e32 v9, 0xfc, v9
	v_add3_u32 v9, v6, v7, v9
	ds_read_b32 v7, v9
	v_pk_mul_f32 v[4:5], v[4:5], s[90:91] op_sel_hi:[1,0]
	s_waitcnt lgkmcnt(0)
	v_cvt_f32_f16_e32 v6, v7
	v_cvt_f32_f16_sdwa v7, v7 dst_sel:DWORD dst_unused:UNUSED_PAD src0_sel:WORD_1
	s_and_saveexec_b64 s[6:7], s[40:41]
	s_xor_b64 s[22:23], exec, s[6:7]
	s_cbranch_execz .LBB0_772
	v_add_u32_e32 v10, 0x400, v20
	v_bfrev_b32_e32 v10, v10
	v_lshrrev_b32_e32 v11, 19, v10
	v_lshrrev_b32_e32 v10, 17, v10
	v_and_b32_e32 v10, 0x2aaa, v10
	v_and_or_b32 v10, v11, s89, v10
	v_lshl_add_u32 v11, v10, 2, s66
	v_lshrrev_b32_e32 v13, 2, v10
	v_lshrrev_b32_e32 v10, 6, v10
	v_and_b32_e32 v13, 0xffc, v13
	v_and_b32_e32 v10, 0xfc, v10
	v_add3_u32 v13, v11, v13, v10
	ds_read_b32 v11, v13
	v_pk_mul_f32 v[14:15], v[6:7], v[4:5] op_sel:[0,0] op_sel_hi:[0,1]
	s_waitcnt lgkmcnt(0)
	v_cvt_f32_f16_e32 v10, v11
	v_cvt_f32_f16_sdwa v11, -v11 dst_sel:DWORD dst_unused:UNUSED_PAD src0_sel:WORD_1
	v_pk_mul_f32 v[16:17], v[10:11], v[2:3] op_sel:[0,0] op_sel_hi:[0,1]
	v_pk_fma_f32 v[14:15], v[6:7], v[4:5], v[14:15] op_sel:[1,1,0] op_sel_hi:[1,0,1] neg_lo:[0,1,0]
	v_pk_fma_f32 v[16:17], v[10:11], v[2:3], v[16:17] op_sel:[1,1,0] op_sel_hi:[1,0,1] neg_lo:[0,1,0]
	v_pk_add_f32 v[14:15], v[14:15], v[16:17]
	v_pk_mul_f32 v[16:17], v[10:11], v[4:5] op_sel:[0,0] op_sel_hi:[0,1]
	v_pk_fma_f32 v[4:5], v[10:11], v[4:5], v[16:17] op_sel:[1,1,0] op_sel_hi:[1,0,1] neg_lo:[0,1,0]
	v_pk_mul_f32 v[10:11], v[6:7], v[2:3] op_sel:[0,0] op_sel_hi:[0,1]
	v_pk_fma_f32 v[2:3], v[6:7], v[2:3], v[10:11] op_sel:[1,1,0] op_sel_hi:[1,0,1] neg_lo:[0,1,0]
	s_nop 0
	v_pk_add_f32 v[2:3], v[4:5], v[2:3]
	v_cvt_pk_f16_f32 v4, v14, v15
	v_cvt_pk_f16_f32 v2, v2, -v3
	ds_write_b32 v9, v4
	ds_write_b32 v13, v2

; DI int rev4(int pp) { const unsigned br = __brev((unsigned)pp) >> 18; return (int)(((br & 0x2AAAu) >> 1) | ((br & 0x1555u) << 1)); }
; DI void pw_h(LAS hc* X, const f32x4* spec, int tid) {
;     ...
;     for (int r = 0; r < 16; ++r) {
;         const int k = tid + NTHR * r; const int pp = rev4(k);
;         const f32x4 sp = spec[k]; const cf P = (cf){sp[0], sp[1]} * 256.0f, Mq = (cf){sp[2], sp[3]} * 256.0f;
;         const hc zh = X[XI(pp)]; const cf z = (cf){(float)zh.x, (float)zh.y};
;         if (k == 0) { const cf y = cmul(z, P) + cmul((cf){z.x, -z.y}, Mq); X[XI(pp)] = (hc){(_Float16)y.x, (_Float16)y.y}; }
;         else { const int pm = rev4(16384 - k); const hc zmh = X[XI(pm)]; const cf zm = (cf){(float)zmh.x, (float)zmh.y};
;             const cf y = cmul(z, P) + cmul((cf){zm.x, -zm.y}, Mq);
;             const cf t = cmul((cf){zm.x, -zm.y}, P) + cmul(z, Mq);
;             X[XI(pp)] = (hc){(_Float16)y.x, (_Float16)y.y}; X[XI(pm)] = (hc){(_Float16)t.x, (_Float16)(-t.y)}; }
;     }
.LBB0_774:
	s_or_b64 exec, exec, s[22:23]
	v_add_u32_e32 v2, 0x2c00, v8
	v_bfrev_b32_e32 v3, v2
	v_lshrrev_b32_e32 v4, 19, v3
	v_lshrrev_b32_e32 v3, 17, v3
	v_and_b32_e32 v3, 0x2aaa, v3
	v_and_or_b32 v9, v4, s89, v3
	v_cmp_ne_u32_e64 s[40:41], s96, v8
	s_waitcnt vmcnt(9)
	v_mov_b32_e32 v4, v124
	v_mov_b32_e32 v5, v125
	v_mov_b32_e32 v6, v126
	v_mov_b32_e32 v7, v127
	v_pk_mul_f32 v[2:3], v[6:7], s[90:91] op_sel_hi:[1,0]
	v_lshl_add_u32 v6, v9, 2, s66
	v_lshrrev_b32_e32 v7, 2, v9
	v_lshrrev_b32_e32 v9, 6, v9
	v_and_b32_e32 v7, 0xffc, v7
	v_and_b32_e32 v9, 0xfc, v9
	v_add3_u32 v9, v6, v7, v9
	ds_read_b32 v7, v9
	v_pk_mul_f32 v[4:5], v[4:5], s[90:91] op_sel_hi:[1,0]
	s_waitcnt lgkmcnt(0)
	v_cvt_f32_f16_e32 v6, v7
	v_cvt_f32_f16_sdwa v7, v7 dst_sel:DWORD dst_unused:UNUSED_PAD src0_sel:WORD_1
	s_and_saveexec_b64 s[6:7], s[40:41]
	s_xor_b64 s[22:23], exec, s[6:7]
	s_cbranch_execz .LBB0_776
	v_add_u32_e32 v10, 0x200, v20
	v_bfrev_b32_e32 v10, v10
	v_lshrrev_b32_e32 v11, 19, v10
	v_lshrrev_b32_e32 v10, 17, v10
	v_and_b32_e32 v10, 0x2aaa, v10
	v_and_or_b32 v10, v11, s89, v10
	v_lshl_add_u32 v11, v10, 2, s66
	v_lshrrev_b32_e32 v13, 2, v10
	v_lshrrev_b32_e32 v10, 6, v10
	v_and_b32_e32 v13, 0xffc, v13
	v_and_b32_e32 v10, 0xfc, v10
	v_add3_u32 v13, v11, v13, v10
	ds_read_b32 v11, v13
	v_pk_mul_f32 v[14:15], v[6:7], v[4:5] op_sel:[0,0] op_sel_hi:[0,1]
	s_waitcnt lgkmcnt(0)
	v_cvt_f32_f16_e32 v10, v11
	v_cvt_f32_f16_sdwa v11, -v11 dst_sel:DWORD dst_unused:UNUSED_PAD src0_sel:WORD_1
	v_pk_mul_f32 v[16:17], v[10:11], v[2:3] op_sel:[0,0] op_sel_hi:[0,1]
	v_pk_fma_f32 v[14:15], v[6:7], v[4:5], v[14:15] op_sel:[1,1,0] op_sel_hi:[1,0,1] neg_lo:[0,1,0]
	v_pk_fma_f32 v[16:17], v[10:11], v[2:3], v[16:17] op_sel:[1,1,0] op_sel_hi:[1,0,1] neg_lo:[0,1,0]
	v_pk_add_f32 v[14:15], v[14:15], v[16:17]
	v_pk_mul_f32 v[16:17], v[10:11], v[4:5] op_sel:[0,0] op_sel_hi:[0,1]
	v_pk_fma_f32 v[4:5], v[10:11], v[4:5], v[16:17] op_sel:[1,1,0] op_sel_hi:[1,0,1] neg_lo:[0,1,0]
	v_pk_mul_f32 v[10:11], v[6:7], v[2:3] op_sel:[0,0] op_sel_hi:[0,1]
	v_pk_fma_f32 v[2:3], v[6:7], v[2:3], v[10:11] op_sel:[1,1,0] op_sel_hi:[1,0,1] neg_lo:[0,1,0]
	s_nop 0
	v_pk_add_f32 v[2:3], v[4:5], v[2:3]
	v_cvt_pk_f16_f32 v4, v14, v15
	v_cvt_pk_f16_f32 v2, v2, -v3
	ds_write_b32 v9, v4
	ds_write_b32 v13, v2

; DI int rev4(int pp) { const unsigned br = __brev((unsigned)pp) >> 18; return (int)(((br & 0x2AAAu) >> 1) | ((br & 0x1555u) << 1)); }
; DI void pw_h(LAS hc* X, const f32x4* spec, int tid) {
;     ...
;     for (int r = 0; r < 16; ++r) {
;         const int k = tid + NTHR * r; const int pp = rev4(k);
;         const f32x4 sp = spec[k]; const cf P = (cf){sp[0], sp[1]} * 256.0f, Mq = (cf){sp[2], sp[3]} * 256.0f;
;         const hc zh = X[XI(pp)]; const cf z = (cf){(float)zh.x, (float)zh.y};
;         if (k == 0) { const cf y = cmul(z, P) + cmul((cf){z.x, -z.y}, Mq); X[XI(pp)] = (hc){(_Float16)y.x, (_Float16)y.y}; }
;         else { const int pm = rev4(16384 - k); const hc zmh = X[XI(pm)]; const cf zm = (cf){(float)zmh.x, (float)zmh.y};
;             const cf y = cmul(z, P) + cmul((cf){zm.x, -zm.y}, Mq);
;             const cf t = cmul((cf){zm.x, -zm.y}, P) + cmul(z, Mq);
;             X[XI(pp)] = (hc){(_Float16)y.x, (_Float16)y.y}; X[XI(pm)] = (hc){(_Float16)t.x, (_Float16)(-t.y)}; }
;     }
.LBB0_778:
	s_or_b64 exec, exec, s[22:23]
	v_add_u32_e32 v2, 0x2e00, v8
	v_bfrev_b32_e32 v3, v2
	v_lshrrev_b32_e32 v4, 19, v3
	v_lshrrev_b32_e32 v3, 17, v3
	v_and_b32_e32 v3, 0x2aaa, v3
	v_and_or_b32 v9, v4, s89, v3
	v_cmp_ne_u32_e64 s[40:41], s84, v8
	s_waitcnt vmcnt(8)
	v_mov_b32_e32 v4, v128
	v_mov_b32_e32 v5, v129
	v_mov_b32_e32 v6, v130
	v_mov_b32_e32 v7, v131
	v_pk_mul_f32 v[2:3], v[6:7], s[90:91] op_sel_hi:[1,0]
	v_lshl_add_u32 v6, v9, 2, s66
	v_lshrrev_b32_e32 v7, 2, v9
	v_lshrrev_b32_e32 v9, 6, v9
	v_and_b32_e32 v7, 0xffc, v7
	v_and_b32_e32 v9, 0xfc, v9
	v_add3_u32 v9, v6, v7, v9
	ds_read_b32 v7, v9
	v_pk_mul_f32 v[4:5], v[4:5], s[90:91] op_sel_hi:[1,0]
	s_waitcnt lgkmcnt(0)
	v_cvt_f32_f16_e32 v6, v7
	v_cvt_f32_f16_sdwa v7, v7 dst_sel:DWORD dst_unused:UNUSED_PAD src0_sel:WORD_1
	s_and_saveexec_b64 s[6:7], s[40:41]
	s_xor_b64 s[22:23], exec, s[6:7]
	s_cbranch_execz .LBB0_780
	v_bfrev_b32_e32 v8, v20
	v_lshrrev_b32_e32 v10, 19, v8
	v_lshrrev_b32_e32 v8, 17, v8
	v_and_b32_e32 v8, 0x2aaa, v8
	v_and_or_b32 v8, v10, s89, v8
	v_lshl_add_u32 v10, v8, 2, s66
	v_lshrrev_b32_e32 v11, 2, v8
	v_lshrrev_b32_e32 v8, 6, v8
	v_and_b32_e32 v11, 0xffc, v11
	v_and_b32_e32 v8, 0xfc, v8
	v_add3_u32 v8, v10, v11, v8
	ds_read_b32 v11, v8
	v_pk_mul_f32 v[14:15], v[6:7], v[4:5] op_sel:[0,0] op_sel_hi:[0,1]
	s_waitcnt lgkmcnt(0)
	v_cvt_f32_f16_e32 v10, v11
	v_cvt_f32_f16_sdwa v11, -v11 dst_sel:DWORD dst_unused:UNUSED_PAD src0_sel:WORD_1
	v_pk_mul_f32 v[16:17], v[10:11], v[2:3] op_sel:[0,0] op_sel_hi:[0,1]
	v_pk_fma_f32 v[14:15], v[6:7], v[4:5], v[14:15] op_sel:[1,1,0] op_sel_hi:[1,0,1] neg_lo:[0,1,0]
	v_pk_fma_f32 v[16:17], v[10:11], v[2:3], v[16:17] op_sel:[1,1,0] op_sel_hi:[1,0,1] neg_lo:[0,1,0]
	v_pk_add_f32 v[14:15], v[14:15], v[16:17]
	v_pk_mul_f32 v[16:17], v[10:11], v[4:5] op_sel:[0,0] op_sel_hi:[0,1]
	v_pk_fma_f32 v[4:5], v[10:11], v[4:5], v[16:17] op_sel:[1,1,0] op_sel_hi:[1,0,1] neg_lo:[0,1,0]
	v_pk_mul_f32 v[10:11], v[6:7], v[2:3] op_sel:[0,0] op_sel_hi:[0,1]
	v_pk_fma_f32 v[2:3], v[6:7], v[2:3], v[10:11] op_sel:[1,1,0] op_sel_hi:[1,0,1] neg_lo:[0,1,0]
	s_nop 0
	v_pk_add_f32 v[2:3], v[4:5], v[2:3]
	v_cvt_pk_f16_f32 v4, v14, v15
	v_cvt_pk_f16_f32 v2, v2, -v3
	ds_write_b32 v9, v4
	ds_write_b32 v8, v2

; DI void hyena_item(const Params& p, int l, int dpr, LAS unsigned char* lds) {
;     ...
; #pragma unroll 4
;     for (int r = 0; r < 16; ++r) { const int t = tid + NTHR * r; const hc y0 = X0[XI(t)], y1 = X1[XI(t)];
;         const float yv[4] = {(float)y0.x, (float)y0.y, (float)y1.x, (float)y1.y};
; #pragma unroll
;         for (int c = 0; c < 4; ++c) z2t[(size_t)(a + c) * S + t] = yv[c] * (1.0f / 64.0f) * conv3(bint + (size_t)(2048 + a + c) * S, t, w[c][0], w[c][1], w[c][2]); }
.LBB0_797:
	v_add_u32_e32 v14, s7, v12
	v_mov_b32_e32 v149, 0
	v_mov_b32_e32 v151, 0
	v_mov_b32_e32 v153, 0
	v_mov_b32_e32 v148, v14
	v_max_i32_e32 v150, 1, v148
	v_min_i32_e32 v152, 0x1ffe, v148
	v_lshlrev_b32_e32 v148, 2, v148
	v_lshlrev_b32_e32 v150, 2, v150
	v_lshlrev_b32_e32 v152, 2, v152
	v_lshl_add_u64 v[154:155], s[24:25], 0, v[148:149]
	global_load_dword v100, v[154:155], off
	v_lshl_add_u64 v[154:155], s[24:25], 0, v[150:151]
	global_load_dword v101, v[154:155], off offset:-4
	v_lshl_add_u64 v[154:155], s[24:25], 0, v[152:153]
	global_load_dword v102, v[154:155], off offset:4
	v_lshl_add_u64 v[154:155], s[22:23], 0, v[148:149]
	global_load_dword v103, v[154:155], off
	v_lshl_add_u64 v[154:155], s[22:23], 0, v[150:151]
	global_load_dword v104, v[154:155], off offset:-4
	v_lshl_add_u64 v[154:155], s[22:23], 0, v[152:153]
	global_load_dword v105, v[154:155], off offset:4
	v_lshl_add_u64 v[154:155], s[18:19], 0, v[148:149]
	global_load_dword v106, v[154:155], off
	v_lshl_add_u64 v[154:155], s[18:19], 0, v[150:151]
	global_load_dword v107, v[154:155], off offset:-4
	v_lshl_add_u64 v[154:155], s[18:19], 0, v[152:153]
	global_load_dword v108, v[154:155], off offset:4
	v_lshl_add_u64 v[154:155], s[16:17], 0, v[148:149]
	global_load_dword v109, v[154:155], off
	v_lshl_add_u64 v[154:155], s[16:17], 0, v[150:151]
	global_load_dword v110, v[154:155], off offset:-4
	v_lshl_add_u64 v[154:155], s[16:17], 0, v[152:153]
	global_load_dword v111, v[154:155], off offset:4
	v_add_u32_e32 v148, 0x200, v14
	v_max_i32_e32 v150, 1, v148
	v_min_i32_e32 v152, 0x1ffe, v148
	v_lshlrev_b32_e32 v148, 2, v148
	v_lshlrev_b32_e32 v150, 2, v150
	v_lshlrev_b32_e32 v152, 2, v152
	v_lshl_add_u64 v[154:155], s[24:25], 0, v[148:149]
	global_load_dword v112, v[154:155], off
	v_lshl_add_u64 v[154:155], s[24:25], 0, v[150:151]
	global_load_dword v113, v[154:155], off offset:-4
	v_lshl_add_u64 v[154:155], s[24:25], 0, v[152:153]
	global_load_dword v114, v[154:155], off offset:4
	v_lshl_add_u64 v[154:155], s[22:23], 0, v[148:149]
	global_load_dword v115, v[154:155], off
	v_lshl_add_u64 v[154:155], s[22:23], 0, v[150:151]
	global_load_dword v116, v[154:155], off offset:-4
	v_lshl_add_u64 v[154:155], s[22:23], 0, v[152:153]
	global_load_dword v117, v[154:155], off offset:4
	v_lshl_add_u64 v[154:155], s[18:19], 0, v[148:149]
	global_load_dword v118, v[154:155], off
	v_lshl_add_u64 v[154:155], s[18:19], 0, v[150:151]
	global_load_dword v119, v[154:155], off offset:-4
	v_lshl_add_u64 v[154:155], s[18:19], 0, v[152:153]
	global_load_dword v120, v[154:155], off offset:4
	v_lshl_add_u64 v[154:155], s[16:17], 0, v[148:149]
	global_load_dword v121, v[154:155], off
	v_lshl_add_u64 v[154:155], s[16:17], 0, v[150:151]
	global_load_dword v122, v[154:155], off offset:-4
	v_lshl_add_u64 v[154:155], s[16:17], 0, v[152:153]
	global_load_dword v123, v[154:155], off offset:4
	v_add_u32_e32 v148, 0x400, v14
	v_max_i32_e32 v150, 1, v148
	v_min_i32_e32 v152, 0x1ffe, v148
	v_lshlrev_b32_e32 v148, 2, v148
	v_lshlrev_b32_e32 v150, 2, v150
	v_lshlrev_b32_e32 v152, 2, v152
	v_lshl_add_u64 v[154:155], s[24:25], 0, v[148:149]
	global_load_dword v124, v[154:155], off
	v_lshl_add_u64 v[154:155], s[24:25], 0, v[150:151]
	global_load_dword v125, v[154:155], off offset:-4
	v_lshl_add_u64 v[154:155], s[24:25], 0, v[152:153]
	global_load_dword v126, v[154:155], off offset:4
	v_lshl_add_u64 v[154:155], s[22:23], 0, v[148:149]
	global_load_dword v127, v[154:155], off
	v_lshl_add_u64 v[154:155], s[22:23], 0, v[150:151]
	global_load_dword v128, v[154:155], off offset:-4
	v_lshl_add_u64 v[154:155], s[22:23], 0, v[152:153]
	global_load_dword v129, v[154:155], off offset:4
	v_lshl_add_u64 v[154:155], s[18:19], 0, v[148:149]
	global_load_dword v130, v[154:155], off
	v_lshl_add_u64 v[154:155], s[18:19], 0, v[150:151]
	global_load_dword v131, v[154:155], off offset:-4
	v_lshl_add_u64 v[154:155], s[18:19], 0, v[152:153]
	global_load_dword v132, v[154:155], off offset:4
	v_lshl_add_u64 v[154:155], s[16:17], 0, v[148:149]
	global_load_dword v133, v[154:155], off
	v_lshl_add_u64 v[154:155], s[16:17], 0, v[150:151]
	global_load_dword v134, v[154:155], off offset:-4
	v_lshl_add_u64 v[154:155], s[16:17], 0, v[152:153]
	global_load_dword v135, v[154:155], off offset:4
	v_add_u32_e32 v148, 0x600, v14
	v_max_i32_e32 v150, 1, v148
	v_min_i32_e32 v152, 0x1ffe, v148
	v_lshlrev_b32_e32 v148, 2, v148
	v_lshlrev_b32_e32 v150, 2, v150
	v_lshlrev_b32_e32 v152, 2, v152
	v_lshl_add_u64 v[154:155], s[24:25], 0, v[148:149]
	global_load_dword v136, v[154:155], off
	v_lshl_add_u64 v[154:155], s[24:25], 0, v[150:151]
	global_load_dword v137, v[154:155], off offset:-4
	v_lshl_add_u64 v[154:155], s[24:25], 0, v[152:153]
	global_load_dword v138, v[154:155], off offset:4
	v_lshl_add_u64 v[154:155], s[22:23], 0, v[148:149]
	global_load_dword v139, v[154:155], off
	v_lshl_add_u64 v[154:155], s[22:23], 0, v[150:151]
	global_load_dword v140, v[154:155], off offset:-4
	v_lshl_add_u64 v[154:155], s[22:23], 0, v[152:153]
	global_load_dword v141, v[154:155], off offset:4
	v_lshl_add_u64 v[154:155], s[18:19], 0, v[148:149]
	global_load_dword v142, v[154:155], off
	v_lshl_add_u64 v[154:155], s[18:19], 0, v[150:151]
	global_load_dword v143, v[154:155], off offset:-4
	v_lshl_add_u64 v[154:155], s[18:19], 0, v[152:153]
	global_load_dword v144, v[154:155], off offset:4
	v_lshl_add_u64 v[154:155], s[16:17], 0, v[148:149]
	global_load_dword v145, v[154:155], off
	v_lshl_add_u64 v[154:155], s[16:17], 0, v[150:151]
	global_load_dword v146, v[154:155], off offset:-4
	v_lshl_add_u64 v[154:155], s[16:17], 0, v[152:153]
	global_load_dword v147, v[154:155], off offset:4
; DI void hyena_item(const Params& p, int l, int dpr, LAS unsigned char* lds) {
;     ...
; #pragma unroll 4
;     for (int r = 0; r < 16; ++r) { const int t = tid + NTHR * r; const hc y0 = X0[XI(t)], y1 = X1[XI(t)];
;         const float yv[4] = {(float)y0.x, (float)y0.y, (float)y1.x, (float)y1.y};
; #pragma unroll
;         for (int c = 0; c < 4; ++c) z2t[(size_t)(a + c) * S + t] = yv[c] * (1.0f / 64.0f) * conv3(bint + (size_t)(2048 + a + c) * S, t, w[c][0], w[c][1], w[c][2]); }
	v_add_u32_e32 v156, 0x800, v14
	v_mov_b32_e32 v157, 0
	v_lshlrev_b32_e32 v156, 2, v156
	v_lshl_add_u64 v[158:159], s[24:25], 0, v[156:157]
	global_load_dword v160, v[158:159], off
	v_lshl_add_u64 v[158:159], s[22:23], 0, v[156:157]
	global_load_dword v161, v[158:159], off
	v_lshl_add_u64 v[158:159], s[18:19], 0, v[156:157]
	global_load_dword v162, v[158:159], off
	v_lshl_add_u64 v[158:159], s[16:17], 0, v[156:157]
	global_load_dword v163, v[158:159], off
	v_add_u32_e32 v156, 0xa00, v14
	v_mov_b32_e32 v157, 0
	v_lshlrev_b32_e32 v156, 2, v156
	v_lshl_add_u64 v[158:159], s[24:25], 0, v[156:157]
	global_load_dword v164, v[158:159], off
	v_lshl_add_u64 v[158:159], s[22:23], 0, v[156:157]
	global_load_dword v165, v[158:159], off
	v_lshl_add_u64 v[158:159], s[18:19], 0, v[156:157]
	global_load_dword v166, v[158:159], off
	v_lshl_add_u64 v[158:159], s[16:17], 0, v[156:157]
	global_load_dword v167, v[158:159], off
	v_add_u32_e32 v156, 0xc00, v14
	v_mov_b32_e32 v157, 0
	v_lshlrev_b32_e32 v156, 2, v156
	v_lshl_add_u64 v[158:159], s[24:25], 0, v[156:157]
	global_load_dword v168, v[158:159], off
	v_lshl_add_u64 v[158:159], s[22:23], 0, v[156:157]
	global_load_dword v169, v[158:159], off
	v_lshl_add_u64 v[158:159], s[18:19], 0, v[156:157]
	global_load_dword v170, v[158:159], off
	v_lshl_add_u64 v[158:159], s[16:17], 0, v[156:157]
	global_load_dword v171, v[158:159], off
	v_add_u32_e32 v156, 0xe00, v14
	v_mov_b32_e32 v157, 0
	v_lshlrev_b32_e32 v156, 2, v156
	v_lshl_add_u64 v[158:159], s[24:25], 0, v[156:157]
	global_load_dword v172, v[158:159], off
	v_lshl_add_u64 v[158:159], s[22:23], 0, v[156:157]
	global_load_dword v173, v[158:159], off
	v_lshl_add_u64 v[158:159], s[18:19], 0, v[156:157]
	global_load_dword v174, v[158:159], off
	v_lshl_add_u64 v[158:159], s[16:17], 0, v[156:157]
	global_load_dword v175, v[158:159], off
	s_waitcnt vmcnt(16)
	v_ashrrev_i32_e32 v13, 4, v14
	v_ashrrev_i32_e32 v15, 8, v14
	v_add_u32_e32 v13, v13, v15
	v_add_lshl_u32 v13, v14, v13, 2
	v_add_u32_e32 v15, 0, v13
	ds_read_b32 v15, v15
	v_add_u32_e32 v13, s66, v13
	ds_read_b32 v13, v13
	v_max_i32_e32 v96, 1, v14
	v_min_i32_e32 v18, 0x1ffe, v14
	s_waitcnt lgkmcnt(1)
	v_cvt_f32_f16_e32 v20, v15
	v_cvt_f32_f16_sdwa v26, v15 dst_sel:DWORD dst_unused:UNUSED_PAD src0_sel:WORD_1
	v_ashrrev_i32_e32 v15, 31, v14
	v_lshlrev_b64 v[22:23], 2, v[14:15]
	v_mul_f32_e32 v15, 0x3c800000, v20
	v_lshl_add_u64 v[20:21], s[24:25], 0, v[22:23]
	v_mov_b32_e32 v28, v100
	v_lshlrev_b64 v[20:21], 2, v[96:97]
	v_ashrrev_i32_e32 v19, 31, v18
	v_lshl_add_u64 v[24:25], s[24:25], 0, v[20:21]
	v_mov_b32_e32 v29, v101
	v_lshlrev_b64 v[18:19], 2, v[18:19]
	v_lshl_add_u64 v[24:25], s[24:25], 0, v[18:19]
	v_mov_b32_e32 v24, v102
	v_cmp_lt_i32_e32 vcc, 0, v14
	v_cmp_gt_i32_e64 s[40:41], s29, v14
	v_lshl_add_u64 v[16:17], s[20:21], 0, v[22:23]
	s_waitcnt lgkmcnt(0)
	v_cvt_f32_f16_e32 v27, v13
	v_cvt_f32_f16_sdwa v13, v13 dst_sel:DWORD dst_unused:UNUSED_PAD src0_sel:WORD_1
	s_addk_i32 s7, 0x800
	s_cmpk_lg_i32 s7, 0x2000
	v_mul_f32_e32 v13, 0x3c800000, v13
	s_nop 0
	v_cndmask_b32_e32 v25, 0, v29, vcc
	v_mul_f32_e32 v25, v0, v25
	v_fmac_f32_e32 v25, v4, v28
	s_nop 0
	v_cndmask_b32_e64 v24, 0, v24, s[40:41]
	v_fmac_f32_e32 v25, v8, v24
	v_mul_f32_e32 v15, v15, v25
	v_lshl_add_u64 v[24:25], v[16:17], 0, s[50:51]
	global_store_dword v[24:25], v15, off
	v_lshl_add_u64 v[24:25], s[22:23], 0, v[22:23]
	v_mul_f32_e32 v15, 0x3c800000, v26
	v_mov_b32_e32 v26, v103
	v_lshl_add_u64 v[24:25], s[22:23], 0, v[20:21]
	v_mov_b32_e32 v28, v104
	v_lshl_add_u64 v[24:25], s[22:23], 0, v[18:19]
	v_mov_b32_e32 v24, v105
	s_nop 0
	v_cndmask_b32_e32 v25, 0, v28, vcc
	v_mul_f32_e32 v25, v1, v25
	s_nop 0
	v_cndmask_b32_e64 v24, 0, v24, s[40:41]
	v_fmac_f32_e32 v25, v5, v26
	v_fmac_f32_e32 v25, v9, v24
	v_mul_f32_e32 v15, v15, v25
	v_lshl_add_u64 v[24:25], v[16:17], 0, s[52:53]
	global_store_dword v[24:25], v15, off
	v_lshl_add_u64 v[24:25], s[18:19], 0, v[22:23]
	v_mov_b32_e32 v26, v106
	v_lshl_add_u64 v[24:25], s[18:19], 0, v[20:21]
	v_mul_f32_e32 v15, 0x3c800000, v27
	v_mov_b32_e32 v27, v107
	v_lshl_add_u64 v[24:25], s[18:19], 0, v[18:19]
	v_mov_b32_e32 v24, v108
	v_lshl_add_u64 v[22:23], s[16:17], 0, v[22:23]
	v_lshl_add_u64 v[20:21], s[16:17], 0, v[20:21]
	v_lshl_add_u64 v[18:19], s[16:17], 0, v[18:19]
	s_nop 0
	v_cndmask_b32_e32 v25, 0, v27, vcc
	v_mul_f32_e32 v25, v2, v25
	s_nop 0
	v_cndmask_b32_e64 v24, 0, v24, s[40:41]
	v_fmac_f32_e32 v25, v6, v26
	v_fmac_f32_e32 v25, v10, v24
	v_mul_f32_e32 v15, v15, v25
	v_lshl_add_u64 v[24:25], v[16:17], 0, s[54:55]
	global_store_dword v[24:25], v15, off
	v_mov_b32_e32 v15, v109
	v_lshl_add_u64 v[16:17], v[16:17], 0, s[56:57]
	v_mov_b32_e32 v20, v110
	s_nop 0
	v_mov_b32_e32 v18, v111
	s_nop 0
	v_cndmask_b32_e32 v19, 0, v20, vcc
	v_mul_f32_e32 v19, v3, v19
	s_nop 0
	v_cndmask_b32_e64 v18, 0, v18, s[40:41]
	v_fmac_f32_e32 v19, v7, v15
	v_fmac_f32_e32 v19, v11, v18
	v_mul_f32_e32 v13, v13, v19
	global_store_dword v[16:17], v13, off
	v_add_u32_e32 v16, 0x200, v14
	v_ashrrev_i32_e32 v13, 4, v16
	v_ashrrev_i32_e32 v15, 8, v16
	v_add_u32_e32 v13, v13, v15
	v_add_lshl_u32 v13, v14, v13, 2
	v_add_u32_e32 v15, 0, v13
	ds_read_b32 v15, v15 offset:2048
	v_add_u32_e32 v13, s66, v13
	ds_read_b32 v13, v13 offset:2048
	v_ashrrev_i32_e32 v17, 31, v16
	v_cmp_lt_i32_e32 vcc, 0, v16
	s_waitcnt lgkmcnt(1)
	v_cvt_f32_f16_e32 v18, v15
	v_max_i32_e32 v96, 1, v16
	v_cmp_gt_i32_e64 s[40:41], s29, v16
	v_min_i32_e32 v20, 0x1ffe, v16
	v_lshlrev_b64 v[16:17], 2, v[16:17]
	v_mul_f32_e32 v25, 0x3c800000, v18
	v_lshl_add_u64 v[18:19], s[24:25], 0, v[16:17]
	v_mov_b32_e32 v26, v112
	v_lshlrev_b64 v[18:19], 2, v[96:97]
	v_ashrrev_i32_e32 v21, 31, v20
	v_lshl_add_u64 v[22:23], s[24:25], 0, v[18:19]
	v_mov_b32_e32 v27, v113
	v_lshlrev_b64 v[20:21], 2, v[20:21]
	v_lshl_add_u64 v[22:23], s[24:25], 0, v[20:21]
	v_mov_b32_e32 v22, v114
	v_cvt_f32_f16_sdwa v15, v15 dst_sel:DWORD dst_unused:UNUSED_PAD src0_sel:WORD_1
	s_waitcnt lgkmcnt(0)
; DI void hyena_item(const Params& p, int l, int dpr, LAS unsigned char* lds) {
;     ...
; #pragma unroll 4
;     for (int r = 0; r < 16; ++r) { const int t = tid + NTHR * r; const hc y0 = X0[XI(t)], y1 = X1[XI(t)];
;         const float yv[4] = {(float)y0.x, (float)y0.y, (float)y1.x, (float)y1.y};
; #pragma unroll
;         for (int c = 0; c < 4; ++c) z2t[(size_t)(a + c) * S + t] = yv[c] * (1.0f / 64.0f) * conv3(bint + (size_t)(2048 + a + c) * S, t, w[c][0], w[c][1], w[c][2]); }
	v_cvt_f32_f16_e32 v24, v13
	v_cvt_f32_f16_sdwa v13, v13 dst_sel:DWORD dst_unused:UNUSED_PAD src0_sel:WORD_1
	v_mul_f32_e32 v15, 0x3c800000, v15
	v_mul_f32_e32 v13, 0x3c800000, v13
	s_nop 0
	v_cndmask_b32_e32 v23, 0, v27, vcc
	v_mul_f32_e32 v23, v0, v23
	v_fmac_f32_e32 v23, v4, v26
	s_nop 0
	v_cndmask_b32_e64 v22, 0, v22, s[40:41]
	v_fmac_f32_e32 v23, v8, v22
	v_mul_f32_e32 v25, v25, v23
	v_lshl_add_u64 v[22:23], s[26:27], 0, v[16:17]
	global_store_dword v[22:23], v25, off
	v_lshl_add_u64 v[22:23], s[22:23], 0, v[16:17]
	v_mov_b32_e32 v25, v115
	v_lshl_add_u64 v[22:23], s[22:23], 0, v[18:19]
	v_mov_b32_e32 v26, v116
	v_lshl_add_u64 v[22:23], s[22:23], 0, v[20:21]
	v_mov_b32_e32 v22, v117
	s_nop 0
	v_cndmask_b32_e32 v23, 0, v26, vcc
	v_mul_f32_e32 v23, v1, v23
	s_nop 0
	v_cndmask_b32_e64 v22, 0, v22, s[40:41]
	v_fmac_f32_e32 v23, v5, v25
	v_fmac_f32_e32 v23, v9, v22
	v_mul_f32_e32 v15, v15, v23
	v_lshl_add_u64 v[22:23], s[42:43], 0, v[16:17]
	global_store_dword v[22:23], v15, off
	v_lshl_add_u64 v[22:23], s[18:19], 0, v[16:17]
	v_mul_f32_e32 v15, 0x3c800000, v24
	v_mov_b32_e32 v24, v118
	v_lshl_add_u64 v[22:23], s[18:19], 0, v[18:19]
	v_mov_b32_e32 v25, v119
	v_lshl_add_u64 v[22:23], s[18:19], 0, v[20:21]
	v_mov_b32_e32 v22, v120
	v_lshl_add_u64 v[18:19], s[16:17], 0, v[18:19]
	s_nop 0
	v_cndmask_b32_e32 v23, 0, v25, vcc
	v_mul_f32_e32 v23, v2, v23
	s_nop 0
	v_cndmask_b32_e64 v22, 0, v22, s[40:41]
	v_fmac_f32_e32 v23, v6, v24
	v_fmac_f32_e32 v23, v10, v22
	v_mul_f32_e32 v15, v15, v23
	v_lshl_add_u64 v[22:23], s[58:59], 0, v[16:17]
	global_store_dword v[22:23], v15, off
	v_lshl_add_u64 v[22:23], s[16:17], 0, v[16:17]
	v_mov_b32_e32 v15, v121
	v_lshl_add_u64 v[16:17], s[60:61], 0, v[16:17]
	v_mov_b32_e32 v22, v122
	v_lshl_add_u64 v[18:19], s[16:17], 0, v[20:21]
	v_mov_b32_e32 v18, v123
	s_nop 0
	v_cndmask_b32_e32 v19, 0, v22, vcc
	v_mul_f32_e32 v19, v3, v19
	s_nop 0
	v_cndmask_b32_e64 v18, 0, v18, s[40:41]
	v_fmac_f32_e32 v19, v7, v15
	v_fmac_f32_e32 v19, v11, v18
	v_mul_f32_e32 v13, v13, v19
	global_store_dword v[16:17], v13, off
	v_add_u32_e32 v16, 0x400, v14
	v_ashrrev_i32_e32 v13, 4, v16
	v_ashrrev_i32_e32 v15, 8, v16
	v_add_u32_e32 v13, v13, v15
	v_add_lshl_u32 v13, v14, v13, 2
	v_add_u32_e32 v15, 0, v13
	ds_read_b32 v15, v15 offset:4096
	v_add_u32_e32 v13, s66, v13
	ds_read_b32 v13, v13 offset:4096
	v_ashrrev_i32_e32 v17, 31, v16
	v_lshlrev_b64 v[22:23], 2, v[16:17]
	s_waitcnt lgkmcnt(1)
	v_cvt_f32_f16_e32 v18, v15
	v_max_i32_e32 v96, 1, v16
	v_min_i32_e32 v20, 0x1ffe, v16
	v_ashrrev_i32_e32 v21, 31, v20
	v_mul_f32_e32 v27, 0x3c800000, v18
	v_lshl_add_u64 v[18:19], s[24:25], 0, v[22:23]
	v_mov_b32_e32 v28, v124
	v_lshlrev_b64 v[18:19], 2, v[96:97]
	v_lshl_add_u64 v[24:25], s[24:25], 0, v[18:19]
	v_mov_b32_e32 v29, v125
	v_lshlrev_b64 v[20:21], 2, v[20:21]
	v_lshl_add_u64 v[24:25], s[24:25], 0, v[20:21]
	v_mov_b32_e32 v24, v126
	v_cmp_lt_i32_e32 vcc, 0, v16
	v_cmp_gt_i32_e64 s[40:41], s29, v16
	v_lshl_add_u64 v[16:17], s[20:21], 0, v[22:23]
	v_cvt_f32_f16_sdwa v15, v15 dst_sel:DWORD dst_unused:UNUSED_PAD src0_sel:WORD_1
	s_waitcnt lgkmcnt(0)
	v_cvt_f32_f16_e32 v26, v13
	v_cvt_f32_f16_sdwa v13, v13 dst_sel:DWORD dst_unused:UNUSED_PAD src0_sel:WORD_1
	v_mul_f32_e32 v15, 0x3c800000, v15
	v_mul_f32_e32 v13, 0x3c800000, v13
	s_nop 0
	v_cndmask_b32_e32 v25, 0, v29, vcc
	v_mul_f32_e32 v25, v0, v25
	v_fmac_f32_e32 v25, v4, v28
	s_nop 0
	v_cndmask_b32_e64 v24, 0, v24, s[40:41]
	v_fmac_f32_e32 v25, v8, v24
	v_mul_f32_e32 v27, v27, v25
	v_lshl_add_u64 v[24:25], v[16:17], 0, s[50:51]
	global_store_dword v[24:25], v27, off
	v_lshl_add_u64 v[24:25], s[22:23], 0, v[22:23]
	v_mov_b32_e32 v27, v127
	v_lshl_add_u64 v[24:25], s[22:23], 0, v[18:19]
	v_mov_b32_e32 v28, v128
	v_lshl_add_u64 v[24:25], s[22:23], 0, v[20:21]
	v_mov_b32_e32 v24, v129
	s_nop 0
	v_cndmask_b32_e32 v25, 0, v28, vcc
	v_mul_f32_e32 v25, v1, v25
	s_nop 0
	v_cndmask_b32_e64 v24, 0, v24, s[40:41]
	v_fmac_f32_e32 v25, v5, v27
	v_fmac_f32_e32 v25, v9, v24
	v_mul_f32_e32 v15, v15, v25
	v_lshl_add_u64 v[24:25], v[16:17], 0, s[52:53]
	global_store_dword v[24:25], v15, off
	v_lshl_add_u64 v[24:25], s[18:19], 0, v[22:23]
	v_mul_f32_e32 v15, 0x3c800000, v26
	v_mov_b32_e32 v26, v130
	v_lshl_add_u64 v[24:25], s[18:19], 0, v[18:19]
	v_mov_b32_e32 v27, v131
	v_lshl_add_u64 v[24:25], s[18:19], 0, v[20:21]
	v_mov_b32_e32 v24, v132
	v_lshl_add_u64 v[22:23], s[16:17], 0, v[22:23]
	v_lshl_add_u64 v[18:19], s[16:17], 0, v[18:19]
	s_nop 0
	v_cndmask_b32_e32 v25, 0, v27, vcc
	v_mul_f32_e32 v25, v2, v25
	s_nop 0
	v_cndmask_b32_e64 v24, 0, v24, s[40:41]
	v_fmac_f32_e32 v25, v6, v26
	v_fmac_f32_e32 v25, v10, v24
	v_mul_f32_e32 v15, v15, v25
	v_lshl_add_u64 v[24:25], v[16:17], 0, s[54:55]
	global_store_dword v[24:25], v15, off
	v_mov_b32_e32 v15, v133
	v_lshl_add_u64 v[16:17], v[16:17], 0, s[56:57]
	v_mov_b32_e32 v22, v134
	v_lshl_add_u64 v[18:19], s[16:17], 0, v[20:21]
	v_mov_b32_e32 v18, v135
	s_nop 0
	v_cndmask_b32_e32 v19, 0, v22, vcc
	v_mul_f32_e32 v19, v3, v19
	s_nop 0
	v_cndmask_b32_e64 v18, 0, v18, s[40:41]
	v_fmac_f32_e32 v19, v7, v15
	v_fmac_f32_e32 v19, v11, v18
	v_mul_f32_e32 v13, v13, v19
	global_store_dword v[16:17], v13, off
	v_add_u32_e32 v16, 0x600, v14
	v_ashrrev_i32_e32 v13, 4, v16
	v_ashrrev_i32_e32 v15, 8, v16
	v_add_u32_e32 v13, v13, v15
	v_add_lshl_u32 v13, v14, v13, 2
	v_add_u32_e32 v14, 0, v13
	ds_read_b32 v14, v14 offset:6144
	v_add_u32_e32 v13, s66, v13
	ds_read_b32 v13, v13 offset:6144
	v_ashrrev_i32_e32 v17, 31, v16
	v_max_i32_e32 v96, 1, v16
	s_waitcnt lgkmcnt(1)
; DI void hyena_item(const Params& p, int l, int dpr, LAS unsigned char* lds) {
;     ...
; #pragma unroll 4
;     for (int r = 0; r < 16; ++r) { const int t = tid + NTHR * r; const hc y0 = X0[XI(t)], y1 = X1[XI(t)];
;         const float yv[4] = {(float)y0.x, (float)y0.y, (float)y1.x, (float)y1.y};
; #pragma unroll
;         for (int c = 0; c < 4; ++c) z2t[(size_t)(a + c) * S + t] = yv[c] * (1.0f / 64.0f) * conv3(bint + (size_t)(2048 + a + c) * S, t, w[c][0], w[c][1], w[c][2]); }
;     __syncthreads();
	v_cvt_f32_f16_e32 v20, v14
	v_lshlrev_b64 v[18:19], 2, v[16:17]
	v_cmp_lt_i32_e32 vcc, 0, v16
	v_cmp_gt_i32_e64 s[40:41], s29, v16
	v_min_i32_e32 v22, 0x1ffe, v16
	v_mul_f32_e32 v26, 0x3c800000, v20
	v_lshl_add_u64 v[16:17], s[24:25], 0, v[18:19]
	v_lshlrev_b64 v[20:21], 2, v[96:97]
	v_ashrrev_i32_e32 v23, 31, v22
	v_mov_b32_e32 v27, v136
	v_lshl_add_u64 v[16:17], s[24:25], 0, v[20:21]
	v_mov_b32_e32 v28, v137
	v_lshlrev_b64 v[16:17], 2, v[22:23]
	v_lshl_add_u64 v[22:23], s[24:25], 0, v[16:17]
	v_mov_b32_e32 v22, v138
	v_cvt_f32_f16_sdwa v24, v14 dst_sel:DWORD dst_unused:UNUSED_PAD src0_sel:WORD_1
	v_lshl_add_u64 v[14:15], s[20:21], 0, v[18:19]
	s_waitcnt lgkmcnt(0)
	v_cvt_f32_f16_e32 v25, v13
	v_cvt_f32_f16_sdwa v13, v13 dst_sel:DWORD dst_unused:UNUSED_PAD src0_sel:WORD_1
	v_mul_f32_e32 v24, 0x3c800000, v24
	v_mul_f32_e32 v13, 0x3c800000, v13
	s_nop 0
	v_cndmask_b32_e32 v23, 0, v28, vcc
	v_mul_f32_e32 v23, v0, v23
	v_fmac_f32_e32 v23, v4, v27
	s_nop 0
	v_cndmask_b32_e64 v22, 0, v22, s[40:41]
	v_fmac_f32_e32 v23, v8, v22
	v_mul_f32_e32 v26, v26, v23
	v_lshl_add_u64 v[22:23], v[14:15], 0, s[50:51]
	global_store_dword v[22:23], v26, off
	v_lshl_add_u64 v[22:23], s[22:23], 0, v[18:19]
	v_mov_b32_e32 v26, v139
	v_lshl_add_u64 v[22:23], s[22:23], 0, v[20:21]
	v_mov_b32_e32 v27, v140
	v_lshl_add_u64 v[22:23], s[22:23], 0, v[16:17]
	v_mov_b32_e32 v22, v141
	s_nop 0
	v_cndmask_b32_e32 v23, 0, v27, vcc
	v_mul_f32_e32 v23, v1, v23
	s_nop 0
	v_cndmask_b32_e64 v22, 0, v22, s[40:41]
	v_fmac_f32_e32 v23, v5, v26
	v_fmac_f32_e32 v23, v9, v22
	v_mul_f32_e32 v24, v24, v23
	v_lshl_add_u64 v[22:23], v[14:15], 0, s[52:53]
	global_store_dword v[22:23], v24, off
	v_lshl_add_u64 v[22:23], s[18:19], 0, v[18:19]
	v_mul_f32_e32 v24, 0x3c800000, v25
	v_mov_b32_e32 v25, v142
	v_lshl_add_u64 v[22:23], s[18:19], 0, v[20:21]
	v_mov_b32_e32 v26, v143
	v_lshl_add_u64 v[22:23], s[18:19], 0, v[16:17]
	v_mov_b32_e32 v22, v144
	v_lshl_add_u64 v[18:19], s[16:17], 0, v[18:19]
	v_lshl_add_u64 v[16:17], s[16:17], 0, v[16:17]
	s_nop 0
	v_cndmask_b32_e32 v23, 0, v26, vcc
	v_mul_f32_e32 v23, v2, v23
	s_nop 0
	v_cndmask_b32_e64 v22, 0, v22, s[40:41]
	v_fmac_f32_e32 v23, v6, v25
	v_fmac_f32_e32 v23, v10, v22
	v_mul_f32_e32 v24, v24, v23
	v_lshl_add_u64 v[22:23], v[14:15], 0, s[54:55]
	global_store_dword v[22:23], v24, off
	v_mov_b32_e32 v22, v145
	v_lshl_add_u64 v[18:19], s[16:17], 0, v[20:21]
	v_mov_b32_e32 v18, v146
	v_lshl_add_u64 v[14:15], v[14:15], 0, s[56:57]
	v_mov_b32_e32 v16, v147
	s_nop 0
	v_cndmask_b32_e32 v17, 0, v18, vcc
	v_mul_f32_e32 v17, v3, v17
	s_nop 0
	v_cndmask_b32_e64 v16, 0, v16, s[40:41]
	v_fmac_f32_e32 v17, v7, v22
	v_fmac_f32_e32 v17, v11, v16
	v_mul_f32_e32 v13, v13, v17
	global_store_dword v[14:15], v13, off
	s_cbranch_scc1 .LBB0_797
	v_readlane_b32 s62, v255, 31
	v_readlane_b32 s54, v255, 58
	v_readlane_b32 s63, v255, 32
	v_readlane_b32 s52, v255, 48
	v_readlane_b32 s55, v255, 59
	v_readlane_b32 s61, v255, 33
	s_movk_i32 s63, 0x2000
	s_mov_b32 s26, 0x800000
	s_mov_b32 s60, 0x78a5c000
	s_mov_b32 s27, 0x9000000
	s_mov_b32 s51, 0x409b43d5
	v_readlane_b32 s53, v255, 49
	v_readlane_b32 s50, v255, 52
	v_readlane_b32 s56, v255, 56
	v_readlane_b32 s58, v255, 54
	s_mov_b32 s55, s2
	s_barrier
	v_readlane_b32 s57, v255, 57
	v_readlane_b32 s59, v255, 55
